# v17 + K-loops: s_setprio 1 moved in front of the barrier and the redundant lgkmcnt(0) behind the barrier removed (first MFMA directly behind the barrier)
# speedup vs baseline: 1.0146x; 1.0146x over previous
; #define PG8_STAGE(bufoff, gbase, voff) do { _Pragma("unroll") for (int _i = 0; _i < 2; ++_i) \
;         __builtin_amdgcn_global_load_lds((const unsigned*)((const char*)(gbase) + (voff)[_i]), (PG8_LAS unsigned*)(lds + (bufoff) + ldsw + _i * 8192), 16, 0, 0); } while (0)
; #define PG8_WAIT_V(n) asm volatile("s_waitcnt vmcnt(" #n ")" ::: "memory")
; #define PG8_WAIT_L(n) asm volatile("s_waitcnt lgkmcnt(" #n ")" ::: "memory")
; #define PG8_BAR __builtin_amdgcn_s_barrier()
; #define PG8_SCHED __builtin_amdgcn_sched_barrier(0)
; template <class Epi, class Sched, bool ALIGN_EPI = true, bool SP2 = true>
; __device__ __forceinline__ void gemm_phase(PG8_LAS unsigned char* lds, const int K  , const Sched& S, const Epi& E) {
;     ...
;             PG8_LDB(B0, 0, 0); PG8_LDB(B1, 0, 1); PG8_SCHED; PG8_LDA(At, 0, 0); PG8_STAGE(PG8_SA(1, 1), a1 + hstep, voffA);
;             PG8_WAIT_V(8); PG8_WAIT_L(0); PG8_BAR; PG8_MMA(0, 0, At, B0); PG8_MMA(0, 1, At, B1); PG8_BAR; PG8_SCHED;
;             PG8_LDA(At, 0, 1); PG8_STAGE(PG8_SB(0, 0), b2, voffB); PG8_STAGE(PG8_SB(0, 1), b2 + hstep, voffB); PG8_STAGE(PG8_SA(0, 0), a2, voffA);
;             PG8_WAIT_V(8); PG8_WAIT_L(0); PG8_BAR; PG8_MMA(1, 0, At, B0); PG8_MMA(1, 1, At, B1); PG8_BAR; PG8_SCHED;
.LBB0_219:
	ds_read_b128 v[148:151], v154
	ds_read_b128 v[160:163], v154 offset:1024
	ds_read_b128 v[164:167], v154 offset:2048
	ds_read_b128 v[168:171], v154 offset:3072
	ds_read_b128 v[172:175], v155
	ds_read_b128 v[176:179], v155 offset:1024
	ds_read_b128 v[180:183], v155 offset:2048
	ds_read_b128 v[184:187], v155 offset:3072
	s_add_u32 s22, s20, 0xfff80080
	s_addc_u32 s23, s21, -1
	s_cmp_eq_u32 s48, 28
	s_cselect_b32 s25, s13, s23
	s_cselect_b32 s24, s44, s22
	s_cselect_b32 s23, s11, s47
	s_cselect_b32 s22, s45, s46
	v_lshl_add_u64 v[220:221], s[20:21], 0, v[140:141]
	s_add_i32 m0, s19, 0xc000
	ds_read_b128 v[188:191], v156
	ds_read_b128 v[192:195], v156 offset:1024
	ds_read_b128 v[196:199], v156 offset:2048
	ds_read_b128 v[200:203], v156 offset:3072
	ds_read_b128 v[204:207], v156 offset:4096
	ds_read_b128 v[208:211], v156 offset:5120
	ds_read_b128 v[212:215], v156 offset:6144
	ds_read_b128 v[216:219], v156 offset:7168
	global_load_lds_dwordx4 v[220:221], off
	v_lshl_add_u64 v[220:221], s[20:21], 0, v[142:143]
	s_add_i32 m0, s19, 0xe000
	s_nop 0
	global_load_lds_dwordx4 v[220:221], off
	s_waitcnt vmcnt(8)
	s_waitcnt lgkmcnt(0)
	s_setprio 1
	s_barrier
	v_mfma_f32_16x16x32_bf16 v[126:129], v[148:151], v[188:191], v[126:129]
	v_mfma_f32_16x16x32_bf16 v[118:121], v[164:167], v[188:191], v[118:121]
	v_mfma_f32_16x16x32_bf16 v[110:113], v[148:151], v[196:199], v[110:113]
	v_mfma_f32_16x16x32_bf16 v[102:105], v[164:167], v[196:199], v[102:105]
	v_mfma_f32_16x16x32_bf16 v[94:97], v[148:151], v[204:207], v[94:97]
	v_mfma_f32_16x16x32_bf16 v[86:89], v[164:167], v[204:207], v[86:89]
	v_mfma_f32_16x16x32_bf16 v[78:81], v[148:151], v[212:215], v[78:81]
	v_mfma_f32_16x16x32_bf16 v[70:73], v[164:167], v[212:215], v[70:73]
	v_mfma_f32_16x16x32_bf16 v[126:129], v[160:163], v[192:195], v[126:129]
	v_mfma_f32_16x16x32_bf16 v[118:121], v[168:171], v[192:195], v[118:121]
	v_mfma_f32_16x16x32_bf16 v[110:113], v[160:163], v[200:203], v[110:113]
	v_mfma_f32_16x16x32_bf16 v[102:105], v[168:171], v[200:203], v[102:105]
	v_mfma_f32_16x16x32_bf16 v[94:97], v[160:163], v[208:211], v[94:97]
	v_mfma_f32_16x16x32_bf16 v[86:89], v[168:171], v[208:211], v[86:89]
	v_mfma_f32_16x16x32_bf16 v[78:81], v[160:163], v[216:219], v[78:81]
	v_mfma_f32_16x16x32_bf16 v[70:73], v[168:171], v[216:219], v[70:73]
	s_setprio 0
	s_setprio 1
	v_mfma_f32_16x16x32_bf16 v[122:125], v[172:175], v[188:191], v[122:125]
	v_mfma_f32_16x16x32_bf16 v[114:117], v[180:183], v[188:191], v[114:117]
	v_mfma_f32_16x16x32_bf16 v[106:109], v[172:175], v[196:199], v[106:109]
	v_mfma_f32_16x16x32_bf16 v[98:101], v[180:183], v[196:199], v[98:101]
	v_mfma_f32_16x16x32_bf16 v[90:93], v[172:175], v[204:207], v[90:93]
	v_mfma_f32_16x16x32_bf16 v[82:85], v[180:183], v[204:207], v[82:85]
	v_mfma_f32_16x16x32_bf16 v[74:77], v[172:175], v[212:215], v[74:77]
	v_mfma_f32_16x16x32_bf16 v[66:69], v[180:183], v[212:215], v[66:69]
	v_mfma_f32_16x16x32_bf16 v[122:125], v[176:179], v[192:195], v[122:125]
	v_mfma_f32_16x16x32_bf16 v[114:117], v[184:187], v[192:195], v[114:117]
	v_mfma_f32_16x16x32_bf16 v[106:109], v[176:179], v[200:203], v[106:109]
	v_mfma_f32_16x16x32_bf16 v[98:101], v[184:187], v[200:203], v[98:101]
	v_mfma_f32_16x16x32_bf16 v[90:93], v[176:179], v[208:211], v[90:93]
	v_mfma_f32_16x16x32_bf16 v[82:85], v[184:187], v[208:211], v[82:85]
	v_mfma_f32_16x16x32_bf16 v[74:77], v[176:179], v[216:219], v[74:77]
	v_mfma_f32_16x16x32_bf16 v[66:69], v[184:187], v[216:219], v[66:69]
	s_setprio 0
	s_barrier
	s_add_i32 s49, s39, s29
	v_lshl_add_u64 v[220:221], s[22:23], 0, v[136:137]
	s_mov_b32 m0, s49
	ds_read_b128 v[188:191], v156 offset:16384
	ds_read_b128 v[192:195], v156 offset:17408
	ds_read_b128 v[196:199], v156 offset:18432
	ds_read_b128 v[200:203], v156 offset:19456
	ds_read_b128 v[204:207], v156 offset:20480
	ds_read_b128 v[208:211], v156 offset:21504
	ds_read_b128 v[212:215], v156 offset:22528
	ds_read_b128 v[216:219], v156 offset:23552
	global_load_lds_dwordx4 v[220:221], off
	s_add_i32 m0, s49, 0x2000
	s_add_u32 s50, s22, 0x80000
	v_lshl_add_u64 v[222:223], s[22:23], 0, v[132:133]
	s_addc_u32 s51, s23, 0
	s_add_i32 s49, s40, s29
	global_load_lds_dwordx4 v[222:223], off
	v_lshl_add_u64 v[224:225], s[50:51], 0, v[136:137]
	s_mov_b32 m0, s49
	v_lshl_add_u64 v[226:227], s[24:25], 0, v[134:135]
	global_load_lds_dwordx4 v[224:225], off
	v_lshl_add_u64 v[224:225], s[50:51], 0, v[132:133]
	s_add_i32 m0, s49, 0x2000
	s_nop 0
	global_load_lds_dwordx4 v[224:225], off
	v_lshl_add_u64 v[224:225], s[24:25], 0, v[138:139]
	s_mov_b32 m0, s19
	s_nop 0
	global_load_lds_dwordx4 v[224:225], off
	s_mov_b32 m0, s31
	s_nop 0
	global_load_lds_dwordx4 v[226:227], off
	s_waitcnt vmcnt(8)
	s_waitcnt lgkmcnt(0)
	s_setprio 1
	s_barrier
; #define PG8_STAGE(bufoff, gbase, voff) do { _Pragma("unroll") for (int _i = 0; _i < 2; ++_i) \
;         __builtin_amdgcn_global_load_lds((const unsigned*)((const char*)(gbase) + (voff)[_i]), (PG8_LAS unsigned*)(lds + (bufoff) + ldsw + _i * 8192), 16, 0, 0); } while (0)
; #define PG8_WAIT_V(n) asm volatile("s_waitcnt vmcnt(" #n ")" ::: "memory")
; #define PG8_WAIT_L(n) asm volatile("s_waitcnt lgkmcnt(" #n ")" ::: "memory")
; #define PG8_BAR __builtin_amdgcn_s_barrier()
; #define PG8_SCHED __builtin_amdgcn_sched_barrier(0)
; template <class Epi, class Sched, bool ALIGN_EPI = true, bool SP2 = true>
; __device__ __forceinline__ void gemm_phase(PG8_LAS unsigned char* lds, const int K  , const Sched& S, const Epi& E) {
;     ...
;             PG8_WAIT_V(8); PG8_WAIT_L(0); PG8_BAR; PG8_MMA(1, 0, At, B0); PG8_MMA(1, 1, At, B1); PG8_BAR; PG8_SCHED;
;             PG8_LDB(B0, 1, 0); PG8_LDB(B1, 1, 1); PG8_SCHED; PG8_LDA(At, 1, 0); PG8_STAGE(PG8_SA(0, 1), a2 + hstep, voffA);
;             PG8_WAIT_V(8); PG8_WAIT_L(0); PG8_BAR; PG8_MMA(0, 0, At, B0); PG8_MMA(0, 1, At, B1); PG8_BAR; PG8_SCHED;
	v_mfma_f32_16x16x32_bf16 v[62:65], v[148:151], v[188:191], v[62:65]
	v_mfma_f32_16x16x32_bf16 v[54:57], v[164:167], v[188:191], v[54:57]
	v_mfma_f32_16x16x32_bf16 v[46:49], v[148:151], v[196:199], v[46:49]
	v_mfma_f32_16x16x32_bf16 v[38:41], v[164:167], v[196:199], v[38:41]
	v_mfma_f32_16x16x32_bf16 v[30:33], v[148:151], v[204:207], v[30:33]
	v_mfma_f32_16x16x32_bf16 v[22:25], v[164:167], v[204:207], v[22:25]
	v_mfma_f32_16x16x32_bf16 v[14:17], v[148:151], v[212:215], v[14:17]
	v_mfma_f32_16x16x32_bf16 v[6:9], v[164:167], v[212:215], v[6:9]
	v_mfma_f32_16x16x32_bf16 v[62:65], v[160:163], v[192:195], v[62:65]
	v_mfma_f32_16x16x32_bf16 v[54:57], v[168:171], v[192:195], v[54:57]
	v_mfma_f32_16x16x32_bf16 v[46:49], v[160:163], v[200:203], v[46:49]
	v_mfma_f32_16x16x32_bf16 v[38:41], v[168:171], v[200:203], v[38:41]
	v_mfma_f32_16x16x32_bf16 v[30:33], v[160:163], v[208:211], v[30:33]
	v_mfma_f32_16x16x32_bf16 v[22:25], v[168:171], v[208:211], v[22:25]
	v_mfma_f32_16x16x32_bf16 v[14:17], v[160:163], v[216:219], v[14:17]
	v_mfma_f32_16x16x32_bf16 v[6:9], v[168:171], v[216:219], v[6:9]
	s_setprio 0
	s_setprio 1
	v_mfma_f32_16x16x32_bf16 v[58:61], v[172:175], v[188:191], v[58:61]
	v_mfma_f32_16x16x32_bf16 v[50:53], v[180:183], v[188:191], v[50:53]
	v_mfma_f32_16x16x32_bf16 v[42:45], v[172:175], v[196:199], v[42:45]
	v_mfma_f32_16x16x32_bf16 v[34:37], v[180:183], v[196:199], v[34:37]
	v_mfma_f32_16x16x32_bf16 v[26:29], v[172:175], v[204:207], v[26:29]
	v_mfma_f32_16x16x32_bf16 v[18:21], v[180:183], v[204:207], v[18:21]
	v_mfma_f32_16x16x32_bf16 v[10:13], v[172:175], v[212:215], v[10:13]
	v_mfma_f32_16x16x32_bf16 v[2:5], v[180:183], v[212:215], v[2:5]
	v_mfma_f32_16x16x32_bf16 v[58:61], v[176:179], v[192:195], v[58:61]
	v_mfma_f32_16x16x32_bf16 v[50:53], v[184:187], v[192:195], v[50:53]
	v_mfma_f32_16x16x32_bf16 v[42:45], v[176:179], v[200:203], v[42:45]
	v_mfma_f32_16x16x32_bf16 v[34:37], v[184:187], v[200:203], v[34:37]
	v_mfma_f32_16x16x32_bf16 v[26:29], v[176:179], v[208:211], v[26:29]
	v_mfma_f32_16x16x32_bf16 v[18:21], v[184:187], v[208:211], v[18:21]
	v_mfma_f32_16x16x32_bf16 v[10:13], v[176:179], v[216:219], v[10:13]
	v_mfma_f32_16x16x32_bf16 v[2:5], v[184:187], v[216:219], v[2:5]
	s_setprio 0
	s_barrier
	s_add_i32 s49, 0, 0x18000
	v_add_u32_e32 v159, s49, v152
	s_add_i32 s50, 0, 0x1c000
	ds_read_b128 v[148:151], v159
	ds_read_b128 v[160:163], v159 offset:1024
	ds_read_b128 v[164:167], v159 offset:2048
	ds_read_b128 v[168:171], v159 offset:3072
	v_add_u32_e32 v159, s50, v152
	ds_read_b128 v[172:175], v159
	ds_read_b128 v[176:179], v159 offset:1024
	ds_read_b128 v[180:183], v159 offset:2048
	ds_read_b128 v[184:187], v159 offset:3072
	s_add_u32 s24, s24, 0x80000
	s_addc_u32 s25, s25, 0
	s_mov_b32 m0, s33
	v_lshl_add_u64 v[230:231], s[24:25], 0, v[138:139]
	ds_read_b128 v[188:191], v156 offset:32768
	ds_read_b128 v[192:195], v156 offset:33792
	ds_read_b128 v[196:199], v156 offset:34816
	ds_read_b128 v[200:203], v156 offset:35840
	ds_read_b128 v[204:207], v156 offset:36864
	ds_read_b128 v[208:211], v156 offset:37888
	ds_read_b128 v[212:215], v156 offset:38912
	ds_read_b128 v[216:219], v156 offset:39936
	global_load_lds_dwordx4 v[230:231], off
	v_lshl_add_u64 v[230:231], s[24:25], 0, v[134:135]
	s_mov_b32 m0, s34
	s_nop 0
	global_load_lds_dwordx4 v[230:231], off
	s_waitcnt vmcnt(8)
	s_waitcnt lgkmcnt(0)
	s_setprio 1
	s_barrier
	v_mfma_f32_16x16x32_bf16 v[126:129], v[148:151], v[188:191], v[126:129]
	v_mfma_f32_16x16x32_bf16 v[118:121], v[164:167], v[188:191], v[118:121]
	v_mfma_f32_16x16x32_bf16 v[110:113], v[148:151], v[196:199], v[110:113]
	v_mfma_f32_16x16x32_bf16 v[102:105], v[164:167], v[196:199], v[102:105]
	v_mfma_f32_16x16x32_bf16 v[94:97], v[148:151], v[204:207], v[94:97]
	v_mfma_f32_16x16x32_bf16 v[86:89], v[164:167], v[204:207], v[86:89]
	v_mfma_f32_16x16x32_bf16 v[78:81], v[148:151], v[212:215], v[78:81]
	v_mfma_f32_16x16x32_bf16 v[70:73], v[164:167], v[212:215], v[70:73]
	v_mfma_f32_16x16x32_bf16 v[126:129], v[160:163], v[192:195], v[126:129]
	v_mfma_f32_16x16x32_bf16 v[118:121], v[168:171], v[192:195], v[118:121]
	v_mfma_f32_16x16x32_bf16 v[110:113], v[160:163], v[200:203], v[110:113]
	v_mfma_f32_16x16x32_bf16 v[102:105], v[168:171], v[200:203], v[102:105]
	v_mfma_f32_16x16x32_bf16 v[94:97], v[160:163], v[208:211], v[94:97]
	v_mfma_f32_16x16x32_bf16 v[86:89], v[168:171], v[208:211], v[86:89]
	v_mfma_f32_16x16x32_bf16 v[78:81], v[160:163], v[216:219], v[78:81]
	v_mfma_f32_16x16x32_bf16 v[70:73], v[168:171], v[216:219], v[70:73]
	s_setprio 0
	s_setprio 1
	v_mfma_f32_16x16x32_bf16 v[122:125], v[172:175], v[188:191], v[122:125]
	v_mfma_f32_16x16x32_bf16 v[114:117], v[180:183], v[188:191], v[114:117]
	v_mfma_f32_16x16x32_bf16 v[106:109], v[172:175], v[196:199], v[106:109]
	v_mfma_f32_16x16x32_bf16 v[98:101], v[180:183], v[196:199], v[98:101]
	v_mfma_f32_16x16x32_bf16 v[90:93], v[172:175], v[204:207], v[90:93]
	v_mfma_f32_16x16x32_bf16 v[82:85], v[180:183], v[204:207], v[82:85]
	v_mfma_f32_16x16x32_bf16 v[74:77], v[172:175], v[212:215], v[74:77]
	v_mfma_f32_16x16x32_bf16 v[66:69], v[180:183], v[212:215], v[66:69]
	v_mfma_f32_16x16x32_bf16 v[122:125], v[176:179], v[192:195], v[122:125]
	v_mfma_f32_16x16x32_bf16 v[114:117], v[184:187], v[192:195], v[114:117]
	v_mfma_f32_16x16x32_bf16 v[106:109], v[176:179], v[200:203], v[106:109]
	v_mfma_f32_16x16x32_bf16 v[98:101], v[184:187], v[200:203], v[98:101]
	v_mfma_f32_16x16x32_bf16 v[90:93], v[176:179], v[208:211], v[90:93]
	v_mfma_f32_16x16x32_bf16 v[82:85], v[184:187], v[208:211], v[82:85]
	v_mfma_f32_16x16x32_bf16 v[74:77], v[176:179], v[216:219], v[74:77]
	v_mfma_f32_16x16x32_bf16 v[66:69], v[184:187], v[216:219], v[66:69]
	s_setprio 0
	s_barrier
; #define PG8_STAGE(bufoff, gbase, voff) do { _Pragma("unroll") for (int _i = 0; _i < 2; ++_i) \
;         __builtin_amdgcn_global_load_lds((const unsigned*)((const char*)(gbase) + (voff)[_i]), (PG8_LAS unsigned*)(lds + (bufoff) + ldsw + _i * 8192), 16, 0, 0); } while (0)
; #define PG8_WAIT_V(n) asm volatile("s_waitcnt vmcnt(" #n ")" ::: "memory")
; #define PG8_WAIT_L(n) asm volatile("s_waitcnt lgkmcnt(" #n ")" ::: "memory")
; #define PG8_BAR __builtin_amdgcn_s_barrier()
; #define PG8_SCHED __builtin_amdgcn_sched_barrier(0)
; template <class Epi, class Sched, bool ALIGN_EPI = true, bool SP2 = true>
; __device__ __forceinline__ void gemm_phase(PG8_LAS unsigned char* lds, const int K  , const Sched& S, const Epi& E) {
;     ...
;             PG8_LDA(At, 1, 1); PG8_STAGE(PG8_SB(1, 0), b3, voffB); PG8_STAGE(PG8_SB(1, 1), b3 + hstep, voffB); PG8_STAGE(PG8_SA(1, 0), a3, voffA);
;             PG8_WAIT_V(8); PG8_WAIT_L(0); PG8_BAR; PG8_MMA(1, 0, At, B0); PG8_MMA(1, 1, At, B1); PG8_BAR; PG8_SCHED;
;     ...
;         if constexpr (ALIGN_EPI) { if (wr == 0) PG8_BAR; }
	s_add_i32 s24, s49, s29
	v_lshl_add_u64 v[220:221], v[220:221], 0, s[6:7]
	s_mov_b32 m0, s24
	ds_read_b128 v[188:191], v156 offset:49152
	ds_read_b128 v[192:195], v156 offset:50176
	ds_read_b128 v[196:199], v156 offset:51200
	ds_read_b128 v[200:203], v156 offset:52224
	ds_read_b128 v[204:207], v156 offset:53248
	ds_read_b128 v[208:211], v156 offset:54272
	ds_read_b128 v[212:215], v156 offset:55296
	ds_read_b128 v[216:219], v156 offset:56320
	global_load_lds_dwordx4 v[220:221], off
	s_add_i32 m0, s24, 0x2000
	s_add_u32 s22, s22, 0x80080
	v_lshl_add_u64 v[220:221], v[222:223], 0, s[6:7]
	s_addc_u32 s23, s23, 0
	s_add_i32 s24, s50, s29
	global_load_lds_dwordx4 v[220:221], off
	v_lshl_add_u64 v[220:221], s[22:23], 0, v[136:137]
	s_mov_b32 m0, s24
	s_nop 0
	global_load_lds_dwordx4 v[220:221], off
	v_lshl_add_u64 v[220:221], s[22:23], 0, v[132:133]
	s_add_i32 m0, s24, 0x2000
	s_nop 0
	global_load_lds_dwordx4 v[220:221], off
	v_lshl_add_u64 v[220:221], v[224:225], 0, s[6:7]
	s_mov_b32 m0, s36
	s_nop 0
	global_load_lds_dwordx4 v[220:221], off
	v_lshl_add_u64 v[220:221], v[226:227], 0, s[6:7]
	s_mov_b32 m0, s37
	s_nop 0
	global_load_lds_dwordx4 v[220:221], off
	s_waitcnt vmcnt(8)
	s_waitcnt lgkmcnt(0)
	s_setprio 1
	s_barrier
	v_mfma_f32_16x16x32_bf16 v[62:65], v[148:151], v[188:191], v[62:65]
	v_mfma_f32_16x16x32_bf16 v[54:57], v[164:167], v[188:191], v[54:57]
	v_mfma_f32_16x16x32_bf16 v[46:49], v[148:151], v[196:199], v[46:49]
	v_mfma_f32_16x16x32_bf16 v[38:41], v[164:167], v[196:199], v[38:41]
	v_mfma_f32_16x16x32_bf16 v[30:33], v[148:151], v[204:207], v[30:33]
	v_mfma_f32_16x16x32_bf16 v[22:25], v[164:167], v[204:207], v[22:25]
	v_mfma_f32_16x16x32_bf16 v[14:17], v[148:151], v[212:215], v[14:17]
	v_mfma_f32_16x16x32_bf16 v[6:9], v[164:167], v[212:215], v[6:9]
	v_mfma_f32_16x16x32_bf16 v[62:65], v[160:163], v[192:195], v[62:65]
	v_mfma_f32_16x16x32_bf16 v[54:57], v[168:171], v[192:195], v[54:57]
	v_mfma_f32_16x16x32_bf16 v[46:49], v[160:163], v[200:203], v[46:49]
	v_mfma_f32_16x16x32_bf16 v[38:41], v[168:171], v[200:203], v[38:41]
	v_mfma_f32_16x16x32_bf16 v[30:33], v[160:163], v[208:211], v[30:33]
	v_mfma_f32_16x16x32_bf16 v[22:25], v[168:171], v[208:211], v[22:25]
	v_mfma_f32_16x16x32_bf16 v[14:17], v[160:163], v[216:219], v[14:17]
	v_mfma_f32_16x16x32_bf16 v[6:9], v[168:171], v[216:219], v[6:9]
	s_setprio 0
	s_setprio 1
	v_mfma_f32_16x16x32_bf16 v[58:61], v[172:175], v[188:191], v[58:61]
	v_mfma_f32_16x16x32_bf16 v[50:53], v[180:183], v[188:191], v[50:53]
	v_mfma_f32_16x16x32_bf16 v[42:45], v[172:175], v[196:199], v[42:45]
	v_mfma_f32_16x16x32_bf16 v[34:37], v[180:183], v[196:199], v[34:37]
	v_mfma_f32_16x16x32_bf16 v[26:29], v[172:175], v[204:207], v[26:29]
	v_mfma_f32_16x16x32_bf16 v[18:21], v[180:183], v[204:207], v[18:21]
	v_mfma_f32_16x16x32_bf16 v[10:13], v[172:175], v[212:215], v[10:13]
	v_mfma_f32_16x16x32_bf16 v[2:5], v[180:183], v[212:215], v[2:5]
	v_mfma_f32_16x16x32_bf16 v[58:61], v[176:179], v[192:195], v[58:61]
	v_mfma_f32_16x16x32_bf16 v[50:53], v[184:187], v[192:195], v[50:53]
	v_mfma_f32_16x16x32_bf16 v[42:45], v[176:179], v[200:203], v[42:45]
	v_mfma_f32_16x16x32_bf16 v[34:37], v[184:187], v[200:203], v[34:37]
	v_mfma_f32_16x16x32_bf16 v[26:29], v[176:179], v[208:211], v[26:29]
	v_mfma_f32_16x16x32_bf16 v[18:21], v[184:187], v[208:211], v[18:21]
	v_mfma_f32_16x16x32_bf16 v[10:13], v[176:179], v[216:219], v[10:13]
	v_mfma_f32_16x16x32_bf16 v[2:5], v[184:187], v[216:219], v[2:5]
	s_setprio 0
	s_barrier
	s_add_i32 s48, s48, 2
	s_add_u32 s20, s20, 0x100
	s_addc_u32 s21, s21, 0
	s_add_u32 s46, s46, 0x100
	s_addc_u32 s47, s47, 0
	s_cmp_gt_u32 s48, 29
	s_cbranch_scc0 .LBB0_219
	s_and_b64 vcc, exec, s[8:9]
	s_cbranch_vccz .LBB0_222
	s_barrier

; #define PG8_STAGE(bufoff, gbase, voff) do { _Pragma("unroll") for (int _i = 0; _i < 2; ++_i) \
;         __builtin_amdgcn_global_load_lds((const unsigned*)((const char*)(gbase) + (voff)[_i]), (PG8_LAS unsigned*)(lds + (bufoff) + ldsw + _i * 8192), 16, 0, 0); } while (0)
; #define PG8_WAIT_V(n) asm volatile("s_waitcnt vmcnt(" #n ")" ::: "memory")
; #define PG8_WAIT_L(n) asm volatile("s_waitcnt lgkmcnt(" #n ")" ::: "memory")
; #define PG8_BAR __builtin_amdgcn_s_barrier()
; #define PG8_SCHED __builtin_amdgcn_sched_barrier(0)
; template <class Epi, class Sched, bool ALIGN_EPI = true, bool SP2 = true>
; __device__ __forceinline__ void gemm_phase(PG8_LAS unsigned char* lds, const int K  , const Sched& S, const Epi& E) {
;     ...
;             PG8_LDB(B0, 0, 0); PG8_LDB(B1, 0, 1); PG8_SCHED; PG8_LDA(At, 0, 0); PG8_STAGE(PG8_SA(1, 1), a1 + hstep, voffA);
;             PG8_WAIT_V(8); PG8_WAIT_L(0); PG8_BAR; PG8_MMA(0, 0, At, B0); PG8_MMA(0, 1, At, B1); PG8_BAR; PG8_SCHED;
;             PG8_LDA(At, 0, 1); PG8_STAGE(PG8_SB(0, 0), b2, voffB); PG8_STAGE(PG8_SB(0, 1), b2 + hstep, voffB); PG8_STAGE(PG8_SA(0, 0), a2, voffA);
;             PG8_WAIT_V(8); PG8_WAIT_L(0); PG8_BAR; PG8_MMA(1, 0, At, B0); PG8_MMA(1, 1, At, B1); PG8_BAR; PG8_SCHED;
.LBB0_393:
	ds_read_b128 v[18:21], v190
	ds_read_b128 v[22:25], v190 offset:1024
	ds_read_b128 v[26:29], v190 offset:2048
	ds_read_b128 v[30:33], v190 offset:3072
	ds_read_b128 v[2:5], v191
	ds_read_b128 v[6:9], v191 offset:1024
	ds_read_b128 v[10:13], v191 offset:2048
	ds_read_b128 v[14:17], v191 offset:3072
	s_add_i32 s50, s22, 2
	s_add_u32 s20, s18, 0xfff50080
	s_addc_u32 s21, s19, -1
	s_cmp_eq_u32 s47, s22
	s_cselect_b32 s22, s14, s20
	s_cselect_b32 s23, s15, s21
	s_cselect_b32 s21, s17, s49
	s_cselect_b32 s20, s16, s48
	v_lshl_add_u64 v[218:219], s[18:19], 0, v[170:171]
	s_add_i32 m0, s26, 0xc000
	ds_read_b128 v[178:181], v192
	ds_read_b128 v[182:185], v192 offset:1024
	ds_read_b128 v[194:197], v192 offset:2048
	ds_read_b128 v[198:201], v192 offset:3072
	ds_read_b128 v[202:205], v192 offset:4096
	ds_read_b128 v[206:209], v192 offset:5120
	ds_read_b128 v[210:213], v192 offset:6144
	ds_read_b128 v[214:217], v192 offset:7168
	global_load_lds_dwordx4 v[218:219], off
	v_lshl_add_u64 v[218:219], s[18:19], 0, v[172:173]
	s_add_i32 m0, s26, 0xe000
	s_nop 0
	global_load_lds_dwordx4 v[218:219], off
	s_waitcnt vmcnt(8)
	s_waitcnt lgkmcnt(0)
	s_setprio 1
	s_barrier
	v_mfma_scale_f32_16x16x128_f8f6f4 v[158:161], v[18:25], v[178:185], v[158:161], v186, v186 op_sel_hi:[0,0,0]
	v_mfma_scale_f32_16x16x128_f8f6f4 v[154:157], v[26:33], v[178:185], v[154:157], v186, v186 op_sel_hi:[0,0,0]
	v_mfma_scale_f32_16x16x128_f8f6f4 v[150:153], v[18:25], v[194:201], v[150:153], v186, v186 op_sel_hi:[0,0,0]
	v_mfma_scale_f32_16x16x128_f8f6f4 v[142:145], v[26:33], v[194:201], v[142:145], v186, v186 op_sel_hi:[0,0,0]
	v_mfma_scale_f32_16x16x128_f8f6f4 v[134:137], v[18:25], v[202:209], v[134:137], v186, v186 op_sel_hi:[0,0,0]
	v_mfma_scale_f32_16x16x128_f8f6f4 v[126:129], v[26:33], v[202:209], v[126:129], v186, v186 op_sel_hi:[0,0,0]
	v_mfma_scale_f32_16x16x128_f8f6f4 v[118:121], v[18:25], v[210:217], v[118:121], v186, v186 op_sel_hi:[0,0,0]
	v_mfma_scale_f32_16x16x128_f8f6f4 v[110:113], v[26:33], v[210:217], v[110:113], v186, v186 op_sel_hi:[0,0,0]
	s_setprio 0
	s_setprio 1
	v_mfma_scale_f32_16x16x128_f8f6f4 v[146:149], v[2:9], v[178:185], v[146:149], v186, v186 op_sel_hi:[0,0,0]
	v_mfma_scale_f32_16x16x128_f8f6f4 v[138:141], v[10:17], v[178:185], v[138:141], v186, v186 op_sel_hi:[0,0,0]
	v_mfma_scale_f32_16x16x128_f8f6f4 v[130:133], v[2:9], v[194:201], v[130:133], v186, v186 op_sel_hi:[0,0,0]
	v_mfma_scale_f32_16x16x128_f8f6f4 v[122:125], v[10:17], v[194:201], v[122:125], v186, v186 op_sel_hi:[0,0,0]
	v_mfma_scale_f32_16x16x128_f8f6f4 v[114:117], v[2:9], v[202:209], v[114:117], v186, v186 op_sel_hi:[0,0,0]
	v_mfma_scale_f32_16x16x128_f8f6f4 v[106:109], v[10:17], v[202:209], v[106:109], v186, v186 op_sel_hi:[0,0,0]
	v_mfma_scale_f32_16x16x128_f8f6f4 v[102:105], v[2:9], v[210:217], v[102:105], v186, v186 op_sel_hi:[0,0,0]
	v_mfma_scale_f32_16x16x128_f8f6f4 v[98:101], v[10:17], v[210:217], v[98:101], v186, v186 op_sel_hi:[0,0,0]
	s_setprio 0
	s_barrier
	s_add_i32 s51, s37, s25
	v_lshl_add_u64 v[178:179], s[20:21], 0, v[164:165]
	s_mov_b32 m0, s51
	ds_read_b128 v[194:197], v192 offset:16384
	ds_read_b128 v[198:201], v192 offset:17408
	ds_read_b128 v[202:205], v192 offset:18432
	ds_read_b128 v[206:209], v192 offset:19456
	ds_read_b128 v[210:213], v192 offset:20480
	ds_read_b128 v[214:217], v192 offset:21504
	ds_read_b128 v[218:221], v192 offset:22528
	ds_read_b128 v[222:225], v192 offset:23552
	global_load_lds_dwordx4 v[178:179], off
	s_add_i32 m0, s51, 0x2000
	s_add_u32 s68, s20, 0xb0000
	v_lshl_add_u64 v[180:181], s[20:21], 0, v[168:169]
	s_addc_u32 s69, s21, 0
	s_add_i32 s51, s38, s25
	global_load_lds_dwordx4 v[180:181], off
	v_lshl_add_u64 v[182:183], s[68:69], 0, v[164:165]
	s_mov_b32 m0, s51
	v_lshl_add_u64 v[184:185], s[22:23], 0, v[166:167]
	global_load_lds_dwordx4 v[182:183], off
	v_lshl_add_u64 v[182:183], s[68:69], 0, v[168:169]
	s_add_i32 m0, s51, 0x2000
	s_nop 0
	global_load_lds_dwordx4 v[182:183], off
	v_lshl_add_u64 v[182:183], s[22:23], 0, v[162:163]
	s_mov_b32 m0, s26
	s_nop 0
	global_load_lds_dwordx4 v[182:183], off
	s_mov_b32 m0, s27
	s_nop 0
	global_load_lds_dwordx4 v[184:185], off
	s_waitcnt vmcnt(8)
	s_waitcnt lgkmcnt(0)
	s_setprio 1
	s_barrier
	v_mfma_scale_f32_16x16x128_f8f6f4 v[94:97], v[18:25], v[194:201], v[94:97], v186, v186 op_sel_hi:[0,0,0]
	v_mfma_scale_f32_16x16x128_f8f6f4 v[90:93], v[26:33], v[194:201], v[90:93], v186, v186 op_sel_hi:[0,0,0]
	v_mfma_scale_f32_16x16x128_f8f6f4 v[86:89], v[18:25], v[202:209], v[86:89], v186, v186 op_sel_hi:[0,0,0]
	v_mfma_scale_f32_16x16x128_f8f6f4 v[78:81], v[26:33], v[202:209], v[78:81], v186, v186 op_sel_hi:[0,0,0]
	v_mfma_scale_f32_16x16x128_f8f6f4 v[70:73], v[18:25], v[210:217], v[70:73], v186, v186 op_sel_hi:[0,0,0]
	v_mfma_scale_f32_16x16x128_f8f6f4 v[62:65], v[26:33], v[210:217], v[62:65], v186, v186 op_sel_hi:[0,0,0]
	v_mfma_scale_f32_16x16x128_f8f6f4 v[54:57], v[18:25], v[218:225], v[54:57], v186, v186 op_sel_hi:[0,0,0]
	v_mfma_scale_f32_16x16x128_f8f6f4 v[46:49], v[26:33], v[218:225], v[46:49], v186, v186 op_sel_hi:[0,0,0]
	s_setprio 0
	s_setprio 1
	v_mfma_scale_f32_16x16x128_f8f6f4 v[82:85], v[2:9], v[194:201], v[82:85], v186, v186 op_sel_hi:[0,0,0]
	v_mfma_scale_f32_16x16x128_f8f6f4 v[74:77], v[10:17], v[194:201], v[74:77], v186, v186 op_sel_hi:[0,0,0]
	v_mfma_scale_f32_16x16x128_f8f6f4 v[66:69], v[2:9], v[202:209], v[66:69], v186, v186 op_sel_hi:[0,0,0]
	v_mfma_scale_f32_16x16x128_f8f6f4 v[58:61], v[10:17], v[202:209], v[58:61], v186, v186 op_sel_hi:[0,0,0]
	v_mfma_scale_f32_16x16x128_f8f6f4 v[50:53], v[2:9], v[210:217], v[50:53], v186, v186 op_sel_hi:[0,0,0]
	v_mfma_scale_f32_16x16x128_f8f6f4 v[42:45], v[10:17], v[210:217], v[42:45], v186, v186 op_sel_hi:[0,0,0]
	v_mfma_scale_f32_16x16x128_f8f6f4 v[38:41], v[2:9], v[218:225], v[38:41], v186, v186 op_sel_hi:[0,0,0]
	v_mfma_scale_f32_16x16x128_f8f6f4 v[34:37], v[10:17], v[218:225], v[34:37], v186, v186 op_sel_hi:[0,0,0]
	s_setprio 0
	s_barrier
; #define PG8_STAGE(bufoff, gbase, voff) do { _Pragma("unroll") for (int _i = 0; _i < 2; ++_i) \
;         __builtin_amdgcn_global_load_lds((const unsigned*)((const char*)(gbase) + (voff)[_i]), (PG8_LAS unsigned*)(lds + (bufoff) + ldsw + _i * 8192), 16, 0, 0); } while (0)
; #define PG8_WAIT_V(n) asm volatile("s_waitcnt vmcnt(" #n ")" ::: "memory")
; #define PG8_WAIT_L(n) asm volatile("s_waitcnt lgkmcnt(" #n ")" ::: "memory")
; #define PG8_BAR __builtin_amdgcn_s_barrier()
; #define PG8_SCHED __builtin_amdgcn_sched_barrier(0)
; template <class Epi, class Sched, bool ALIGN_EPI = true, bool SP2 = true>
; __device__ __forceinline__ void gemm_phase(PG8_LAS unsigned char* lds, const int K  , const Sched& S, const Epi& E) {
;     ...
;             PG8_LDB(B0, 1, 0); PG8_LDB(B1, 1, 1); PG8_SCHED; PG8_LDA(At, 1, 0); PG8_STAGE(PG8_SA(0, 1), a2 + hstep, voffA);
;             PG8_WAIT_V(8); PG8_WAIT_L(0); PG8_BAR; PG8_MMA(0, 0, At, B0); PG8_MMA(0, 1, At, B1); PG8_BAR; PG8_SCHED;
;             PG8_LDA(At, 1, 1); PG8_STAGE(PG8_SB(1, 0), b3, voffB); PG8_STAGE(PG8_SB(1, 1), b3 + hstep, voffB); PG8_STAGE(PG8_SA(1, 0), a3, voffA);
;             PG8_WAIT_V(8); PG8_WAIT_L(0); PG8_BAR; PG8_MMA(1, 0, At, B0); PG8_MMA(1, 1, At, B1); PG8_BAR; PG8_SCHED;
;     ...
;         if constexpr (Epi::FP8) asm volatile("s_nop 15\n\ts_nop 15\n\ts_nop 15\n\ts_nop 15\n\ts_nop 15" ::: "memory");
;         if constexpr (ALIGN_EPI) { if (wr == 0) PG8_BAR; }
	s_add_i32 s51, 0, 0x18000
	s_add_i32 s68, 0, 0x1c000
	v_add_u32_e32 v14, s51, v188
	v_add_u32_e32 v30, s68, v188
	ds_read_b128 v[2:5], v14
	ds_read_b128 v[6:9], v14 offset:1024
	ds_read_b128 v[10:13], v14 offset:2048
	ds_read_b128 v[14:17], v14 offset:3072
	ds_read_b128 v[18:21], v30
	ds_read_b128 v[22:25], v30 offset:1024
	ds_read_b128 v[26:29], v30 offset:2048
	ds_read_b128 v[30:33], v30 offset:3072
	s_add_u32 s22, s22, 0xb0000
	s_addc_u32 s23, s23, 0
	s_mov_b32 m0, s28
	v_lshl_add_u64 v[226:227], s[22:23], 0, v[162:163]
	ds_read_b128 v[194:197], v192 offset:32768
	ds_read_b128 v[198:201], v192 offset:33792
	ds_read_b128 v[202:205], v192 offset:34816
	ds_read_b128 v[206:209], v192 offset:35840
	ds_read_b128 v[210:213], v192 offset:36864
	ds_read_b128 v[214:217], v192 offset:37888
	ds_read_b128 v[218:221], v192 offset:38912
	ds_read_b128 v[222:225], v192 offset:39936
	global_load_lds_dwordx4 v[226:227], off
	v_lshl_add_u64 v[226:227], s[22:23], 0, v[166:167]
	s_mov_b32 m0, s29
	s_nop 0
	global_load_lds_dwordx4 v[226:227], off
	s_waitcnt vmcnt(8)
	s_waitcnt lgkmcnt(0)
	s_setprio 1
	s_barrier
	v_mfma_scale_f32_16x16x128_f8f6f4 v[158:161], v[2:9], v[194:201], v[158:161], v186, v186 op_sel_hi:[0,0,0]
	v_mfma_scale_f32_16x16x128_f8f6f4 v[154:157], v[10:17], v[194:201], v[154:157], v186, v186 op_sel_hi:[0,0,0]
	v_mfma_scale_f32_16x16x128_f8f6f4 v[150:153], v[2:9], v[202:209], v[150:153], v186, v186 op_sel_hi:[0,0,0]
	v_mfma_scale_f32_16x16x128_f8f6f4 v[142:145], v[10:17], v[202:209], v[142:145], v186, v186 op_sel_hi:[0,0,0]
	v_mfma_scale_f32_16x16x128_f8f6f4 v[134:137], v[2:9], v[210:217], v[134:137], v186, v186 op_sel_hi:[0,0,0]
	v_mfma_scale_f32_16x16x128_f8f6f4 v[126:129], v[10:17], v[210:217], v[126:129], v186, v186 op_sel_hi:[0,0,0]
	v_mfma_scale_f32_16x16x128_f8f6f4 v[118:121], v[2:9], v[218:225], v[118:121], v186, v186 op_sel_hi:[0,0,0]
	v_mfma_scale_f32_16x16x128_f8f6f4 v[110:113], v[10:17], v[218:225], v[110:113], v186, v186 op_sel_hi:[0,0,0]
	s_setprio 0
	s_setprio 1
	v_mfma_scale_f32_16x16x128_f8f6f4 v[146:149], v[18:25], v[194:201], v[146:149], v186, v186 op_sel_hi:[0,0,0]
	v_mfma_scale_f32_16x16x128_f8f6f4 v[138:141], v[26:33], v[194:201], v[138:141], v186, v186 op_sel_hi:[0,0,0]
	v_mfma_scale_f32_16x16x128_f8f6f4 v[130:133], v[18:25], v[202:209], v[130:133], v186, v186 op_sel_hi:[0,0,0]
	v_mfma_scale_f32_16x16x128_f8f6f4 v[122:125], v[26:33], v[202:209], v[122:125], v186, v186 op_sel_hi:[0,0,0]
	v_mfma_scale_f32_16x16x128_f8f6f4 v[114:117], v[18:25], v[210:217], v[114:117], v186, v186 op_sel_hi:[0,0,0]
	v_mfma_scale_f32_16x16x128_f8f6f4 v[106:109], v[26:33], v[210:217], v[106:109], v186, v186 op_sel_hi:[0,0,0]
	v_mfma_scale_f32_16x16x128_f8f6f4 v[102:105], v[18:25], v[218:225], v[102:105], v186, v186 op_sel_hi:[0,0,0]
	v_mfma_scale_f32_16x16x128_f8f6f4 v[98:101], v[26:33], v[218:225], v[98:101], v186, v186 op_sel_hi:[0,0,0]
	s_setprio 0
	s_barrier
	s_add_i32 s22, s51, s25
	v_lshl_add_u64 v[178:179], v[178:179], 0, s[8:9]
	s_mov_b32 m0, s22
	ds_read_b128 v[194:197], v192 offset:49152
	ds_read_b128 v[198:201], v192 offset:50176
	ds_read_b128 v[202:205], v192 offset:51200
	ds_read_b128 v[206:209], v192 offset:52224
	ds_read_b128 v[210:213], v192 offset:53248
	ds_read_b128 v[214:217], v192 offset:54272
	ds_read_b128 v[218:221], v192 offset:55296
	ds_read_b128 v[222:225], v192 offset:56320
	global_load_lds_dwordx4 v[178:179], off
	s_add_i32 m0, s22, 0x2000
	s_add_u32 s20, s20, 0xb0080
	v_lshl_add_u64 v[178:179], v[180:181], 0, s[8:9]
	s_addc_u32 s21, s21, 0
	s_add_i32 s22, s68, s25
	global_load_lds_dwordx4 v[178:179], off
	v_lshl_add_u64 v[178:179], s[20:21], 0, v[164:165]
	s_mov_b32 m0, s22
	s_nop 0
	global_load_lds_dwordx4 v[178:179], off
	v_lshl_add_u64 v[178:179], s[20:21], 0, v[168:169]
	s_add_i32 m0, s22, 0x2000
	s_nop 0
	global_load_lds_dwordx4 v[178:179], off
	v_lshl_add_u64 v[178:179], v[182:183], 0, s[8:9]
	s_mov_b32 m0, s33
	s_nop 0
	global_load_lds_dwordx4 v[178:179], off
	v_lshl_add_u64 v[178:179], v[184:185], 0, s[8:9]
	s_mov_b32 m0, s34
	s_nop 0
	global_load_lds_dwordx4 v[178:179], off
	s_waitcnt vmcnt(8)
	s_waitcnt lgkmcnt(0)
	s_setprio 1
	s_barrier
	v_mfma_scale_f32_16x16x128_f8f6f4 v[94:97], v[2:9], v[194:201], v[94:97], v186, v186 op_sel_hi:[0,0,0]
	v_mfma_scale_f32_16x16x128_f8f6f4 v[90:93], v[10:17], v[194:201], v[90:93], v186, v186 op_sel_hi:[0,0,0]
	v_mfma_scale_f32_16x16x128_f8f6f4 v[86:89], v[2:9], v[202:209], v[86:89], v186, v186 op_sel_hi:[0,0,0]
	v_mfma_scale_f32_16x16x128_f8f6f4 v[78:81], v[10:17], v[202:209], v[78:81], v186, v186 op_sel_hi:[0,0,0]
	v_mfma_scale_f32_16x16x128_f8f6f4 v[70:73], v[2:9], v[210:217], v[70:73], v186, v186 op_sel_hi:[0,0,0]
	v_mfma_scale_f32_16x16x128_f8f6f4 v[62:65], v[10:17], v[210:217], v[62:65], v186, v186 op_sel_hi:[0,0,0]
	v_mfma_scale_f32_16x16x128_f8f6f4 v[54:57], v[2:9], v[218:225], v[54:57], v186, v186 op_sel_hi:[0,0,0]
	v_mfma_scale_f32_16x16x128_f8f6f4 v[46:49], v[10:17], v[218:225], v[46:49], v186, v186 op_sel_hi:[0,0,0]
	s_setprio 0
	s_setprio 1
	v_mfma_scale_f32_16x16x128_f8f6f4 v[82:85], v[18:25], v[194:201], v[82:85], v186, v186 op_sel_hi:[0,0,0]
	v_mfma_scale_f32_16x16x128_f8f6f4 v[74:77], v[26:33], v[194:201], v[74:77], v186, v186 op_sel_hi:[0,0,0]
	v_mfma_scale_f32_16x16x128_f8f6f4 v[66:69], v[18:25], v[202:209], v[66:69], v186, v186 op_sel_hi:[0,0,0]
	v_mfma_scale_f32_16x16x128_f8f6f4 v[58:61], v[26:33], v[202:209], v[58:61], v186, v186 op_sel_hi:[0,0,0]
	v_mfma_scale_f32_16x16x128_f8f6f4 v[50:53], v[18:25], v[210:217], v[50:53], v186, v186 op_sel_hi:[0,0,0]
	v_mfma_scale_f32_16x16x128_f8f6f4 v[42:45], v[26:33], v[210:217], v[42:45], v186, v186 op_sel_hi:[0,0,0]
	v_mfma_scale_f32_16x16x128_f8f6f4 v[38:41], v[18:25], v[218:225], v[38:41], v186, v186 op_sel_hi:[0,0,0]
	v_mfma_scale_f32_16x16x128_f8f6f4 v[34:37], v[26:33], v[218:225], v[34:37], v186, v186 op_sel_hi:[0,0,0]
	s_setprio 0
	s_barrier
	s_add_u32 s18, s18, 0x100
	s_addc_u32 s19, s19, 0
	s_add_u32 s48, s48, 0x100
	s_addc_u32 s49, s49, 0
	s_cmp_ge_u32 s50, s4
	s_mov_b32 s22, s50
	s_cbranch_scc0 .LBB0_393
	s_nop 15
	s_nop 15
	s_nop 15
	s_nop 15
	s_nop 15
	s_and_b64 vcc, exec, s[10:11]
	s_cbranch_vccz .LBB0_396
	s_barrier

; #define PG8_STAGE(bufoff, gbase, voff) do { _Pragma("unroll") for (int _i = 0; _i < 2; ++_i) \
;         __builtin_amdgcn_global_load_lds((const unsigned*)((const char*)(gbase) + (voff)[_i]), (PG8_LAS unsigned*)(lds + (bufoff) + ldsw + _i * 8192), 16, 0, 0); } while (0)
; #define PG8_WAIT_V(n) asm volatile("s_waitcnt vmcnt(" #n ")" ::: "memory")
; #define PG8_WAIT_L(n) asm volatile("s_waitcnt lgkmcnt(" #n ")" ::: "memory")
; #define PG8_BAR __builtin_amdgcn_s_barrier()
; #define PG8_SCHED __builtin_amdgcn_sched_barrier(0)
; template <class Epi, class Sched, bool ALIGN_EPI = true, bool SP2 = true>
; __device__ __forceinline__ void gemm_phase(PG8_LAS unsigned char* lds, const int K  , const Sched& S, const Epi& E) {
;     ...
;             PG8_LDB(B0, 0, 0); PG8_LDB(B1, 0, 1); PG8_SCHED; PG8_LDA(At, 0, 0); PG8_STAGE(PG8_SA(1, 1), a1 + hstep, voffA);
;             PG8_WAIT_V(8); PG8_WAIT_L(0); PG8_BAR; PG8_MMA(0, 0, At, B0); PG8_MMA(0, 1, At, B1); PG8_BAR; PG8_SCHED;
;             PG8_LDA(At, 0, 1); PG8_STAGE(PG8_SB(0, 0), b2, voffB); PG8_STAGE(PG8_SB(0, 1), b2 + hstep, voffB); PG8_STAGE(PG8_SA(0, 0), a2, voffA);
.LBB0_537:
	ds_read_b128 v[150:153], v156
	ds_read_b128 v[160:163], v156 offset:1024
	ds_read_b128 v[164:167], v156 offset:2048
	ds_read_b128 v[168:171], v156 offset:3072
	ds_read_b128 v[172:175], v157
	ds_read_b128 v[176:179], v157 offset:1024
	ds_read_b128 v[180:183], v157 offset:2048
	ds_read_b128 v[184:187], v157 offset:3072
	s_add_u32 s22, s20, 0xfff80080
	s_addc_u32 s23, s21, -1
	s_cmp_eq_u32 s47, 28
	s_cselect_b32 s25, s13, s23
	s_cselect_b32 s24, s19, s22
	s_cselect_b32 s23, s11, s46
	s_cselect_b32 s22, s44, s45
	v_lshl_add_u64 v[220:221], s[20:21], 0, v[142:143]
	s_add_i32 m0, s31, 0xc000
	ds_read_b128 v[188:191], v158
	ds_read_b128 v[192:195], v158 offset:1024
	ds_read_b128 v[196:199], v158 offset:2048
	ds_read_b128 v[200:203], v158 offset:3072
	ds_read_b128 v[204:207], v158 offset:4096
	ds_read_b128 v[208:211], v158 offset:5120
	ds_read_b128 v[212:215], v158 offset:6144
	ds_read_b128 v[216:219], v158 offset:7168
	global_load_lds_dwordx4 v[220:221], off
	v_lshl_add_u64 v[220:221], s[20:21], 0, v[144:145]
	s_add_i32 m0, s31, 0xe000
	s_nop 0
	global_load_lds_dwordx4 v[220:221], off
	s_waitcnt vmcnt(8)
	s_waitcnt lgkmcnt(0)
	s_setprio 1
	s_barrier
	v_mfma_f32_16x16x32_bf16 v[126:129], v[150:153], v[188:191], v[126:129]
	v_mfma_f32_16x16x32_bf16 v[122:125], v[164:167], v[188:191], v[122:125]
	v_mfma_f32_16x16x32_bf16 v[118:121], v[150:153], v[196:199], v[118:121]
	v_mfma_f32_16x16x32_bf16 v[110:113], v[164:167], v[196:199], v[110:113]
	v_mfma_f32_16x16x32_bf16 v[102:105], v[150:153], v[204:207], v[102:105]
	v_mfma_f32_16x16x32_bf16 v[94:97], v[164:167], v[204:207], v[94:97]
	v_mfma_f32_16x16x32_bf16 v[86:89], v[150:153], v[212:215], v[86:89]
	v_mfma_f32_16x16x32_bf16 v[78:81], v[164:167], v[212:215], v[78:81]
	v_mfma_f32_16x16x32_bf16 v[126:129], v[160:163], v[192:195], v[126:129]
	v_mfma_f32_16x16x32_bf16 v[122:125], v[168:171], v[192:195], v[122:125]
	v_mfma_f32_16x16x32_bf16 v[118:121], v[160:163], v[200:203], v[118:121]
	v_mfma_f32_16x16x32_bf16 v[110:113], v[168:171], v[200:203], v[110:113]
	v_mfma_f32_16x16x32_bf16 v[102:105], v[160:163], v[208:211], v[102:105]
	v_mfma_f32_16x16x32_bf16 v[94:97], v[168:171], v[208:211], v[94:97]
	v_mfma_f32_16x16x32_bf16 v[86:89], v[160:163], v[216:219], v[86:89]
	v_mfma_f32_16x16x32_bf16 v[78:81], v[168:171], v[216:219], v[78:81]
	s_setprio 0
	s_setprio 1
	v_mfma_f32_16x16x32_bf16 v[114:117], v[172:175], v[188:191], v[114:117]
	v_mfma_f32_16x16x32_bf16 v[106:109], v[180:183], v[188:191], v[106:109]
	v_mfma_f32_16x16x32_bf16 v[98:101], v[172:175], v[196:199], v[98:101]
	v_mfma_f32_16x16x32_bf16 v[90:93], v[180:183], v[196:199], v[90:93]
	v_mfma_f32_16x16x32_bf16 v[82:85], v[172:175], v[204:207], v[82:85]
	v_mfma_f32_16x16x32_bf16 v[74:77], v[180:183], v[204:207], v[74:77]
	v_mfma_f32_16x16x32_bf16 v[70:73], v[172:175], v[212:215], v[70:73]
	v_mfma_f32_16x16x32_bf16 v[66:69], v[180:183], v[212:215], v[66:69]
	v_mfma_f32_16x16x32_bf16 v[114:117], v[176:179], v[192:195], v[114:117]
	v_mfma_f32_16x16x32_bf16 v[106:109], v[184:187], v[192:195], v[106:109]
	v_mfma_f32_16x16x32_bf16 v[98:101], v[176:179], v[200:203], v[98:101]
	v_mfma_f32_16x16x32_bf16 v[90:93], v[184:187], v[200:203], v[90:93]
	v_mfma_f32_16x16x32_bf16 v[82:85], v[176:179], v[208:211], v[82:85]
	v_mfma_f32_16x16x32_bf16 v[74:77], v[184:187], v[208:211], v[74:77]
	v_mfma_f32_16x16x32_bf16 v[70:73], v[176:179], v[216:219], v[70:73]
	v_mfma_f32_16x16x32_bf16 v[66:69], v[184:187], v[216:219], v[66:69]
	s_setprio 0
	s_barrier
	s_add_i32 s48, s40, s29
	v_lshl_add_u64 v[220:221], s[22:23], 0, v[136:137]
	s_mov_b32 m0, s48
	ds_read_b128 v[188:191], v158 offset:16384
	ds_read_b128 v[192:195], v158 offset:17408
	ds_read_b128 v[196:199], v158 offset:18432
	ds_read_b128 v[200:203], v158 offset:19456
	ds_read_b128 v[204:207], v158 offset:20480
	ds_read_b128 v[208:211], v158 offset:21504
	ds_read_b128 v[212:215], v158 offset:22528
	ds_read_b128 v[216:219], v158 offset:23552
	global_load_lds_dwordx4 v[220:221], off
	s_add_i32 m0, s48, 0x2000
	s_add_u32 s48, s22, 0x80000
	v_lshl_add_u64 v[222:223], s[22:23], 0, v[132:133]
	s_addc_u32 s49, s23, 0
	s_add_i32 s50, s41, s29
	global_load_lds_dwordx4 v[222:223], off
	v_lshl_add_u64 v[224:225], s[48:49], 0, v[136:137]
	s_mov_b32 m0, s50
	v_lshl_add_u64 v[226:227], s[24:25], 0, v[134:135]
	global_load_lds_dwordx4 v[224:225], off
	v_lshl_add_u64 v[224:225], s[48:49], 0, v[132:133]
	s_add_i32 m0, s50, 0x2000
	s_nop 0
	global_load_lds_dwordx4 v[224:225], off
	v_lshl_add_u64 v[224:225], s[24:25], 0, v[138:139]
	s_mov_b32 m0, s31
	s_nop 0
	global_load_lds_dwordx4 v[224:225], off
	s_mov_b32 m0, s33
	s_nop 0
	global_load_lds_dwordx4 v[226:227], off
	s_waitcnt vmcnt(8)
	s_waitcnt lgkmcnt(0)
	s_setprio 1
	s_barrier
; #define PG8_STAGE(bufoff, gbase, voff) do { _Pragma("unroll") for (int _i = 0; _i < 2; ++_i) \
;         __builtin_amdgcn_global_load_lds((const unsigned*)((const char*)(gbase) + (voff)[_i]), (PG8_LAS unsigned*)(lds + (bufoff) + ldsw + _i * 8192), 16, 0, 0); } while (0)
; #define PG8_WAIT_V(n) asm volatile("s_waitcnt vmcnt(" #n ")" ::: "memory")
; #define PG8_WAIT_L(n) asm volatile("s_waitcnt lgkmcnt(" #n ")" ::: "memory")
; #define PG8_BAR __builtin_amdgcn_s_barrier()
; #define PG8_SCHED __builtin_amdgcn_sched_barrier(0)
; template <class Epi, class Sched, bool ALIGN_EPI = true, bool SP2 = true>
; __device__ __forceinline__ void gemm_phase(PG8_LAS unsigned char* lds, const int K  , const Sched& S, const Epi& E) {
;     ...
;             PG8_WAIT_V(8); PG8_WAIT_L(0); PG8_BAR; PG8_MMA(1, 0, At, B0); PG8_MMA(1, 1, At, B1); PG8_BAR; PG8_SCHED;
;             PG8_LDB(B0, 1, 0); PG8_LDB(B1, 1, 1); PG8_SCHED; PG8_LDA(At, 1, 0); PG8_STAGE(PG8_SA(0, 1), a2 + hstep, voffA);
;             PG8_WAIT_V(8); PG8_WAIT_L(0); PG8_BAR; PG8_MMA(0, 0, At, B0); PG8_MMA(0, 1, At, B1); PG8_BAR; PG8_SCHED;
	v_mfma_f32_16x16x32_bf16 v[62:65], v[150:153], v[188:191], v[62:65]
	v_mfma_f32_16x16x32_bf16 v[58:61], v[164:167], v[188:191], v[58:61]
	v_mfma_f32_16x16x32_bf16 v[54:57], v[150:153], v[196:199], v[54:57]
	v_mfma_f32_16x16x32_bf16 v[46:49], v[164:167], v[196:199], v[46:49]
	v_mfma_f32_16x16x32_bf16 v[38:41], v[150:153], v[204:207], v[38:41]
	v_mfma_f32_16x16x32_bf16 v[30:33], v[164:167], v[204:207], v[30:33]
	v_mfma_f32_16x16x32_bf16 v[22:25], v[150:153], v[212:215], v[22:25]
	v_mfma_f32_16x16x32_bf16 v[14:17], v[164:167], v[212:215], v[14:17]
	v_mfma_f32_16x16x32_bf16 v[62:65], v[160:163], v[192:195], v[62:65]
	v_mfma_f32_16x16x32_bf16 v[58:61], v[168:171], v[192:195], v[58:61]
	v_mfma_f32_16x16x32_bf16 v[54:57], v[160:163], v[200:203], v[54:57]
	v_mfma_f32_16x16x32_bf16 v[46:49], v[168:171], v[200:203], v[46:49]
	v_mfma_f32_16x16x32_bf16 v[38:41], v[160:163], v[208:211], v[38:41]
	v_mfma_f32_16x16x32_bf16 v[30:33], v[168:171], v[208:211], v[30:33]
	v_mfma_f32_16x16x32_bf16 v[22:25], v[160:163], v[216:219], v[22:25]
	v_mfma_f32_16x16x32_bf16 v[14:17], v[168:171], v[216:219], v[14:17]
	s_setprio 0
	s_setprio 1
	v_mfma_f32_16x16x32_bf16 v[50:53], v[172:175], v[188:191], v[50:53]
	v_mfma_f32_16x16x32_bf16 v[42:45], v[180:183], v[188:191], v[42:45]
	v_mfma_f32_16x16x32_bf16 v[34:37], v[172:175], v[196:199], v[34:37]
	v_mfma_f32_16x16x32_bf16 v[26:29], v[180:183], v[196:199], v[26:29]
	v_mfma_f32_16x16x32_bf16 v[18:21], v[172:175], v[204:207], v[18:21]
	v_mfma_f32_16x16x32_bf16 v[10:13], v[180:183], v[204:207], v[10:13]
	v_mfma_f32_16x16x32_bf16 v[6:9], v[172:175], v[212:215], v[6:9]
	v_mfma_f32_16x16x32_bf16 v[2:5], v[180:183], v[212:215], v[2:5]
	v_mfma_f32_16x16x32_bf16 v[50:53], v[176:179], v[192:195], v[50:53]
	v_mfma_f32_16x16x32_bf16 v[42:45], v[184:187], v[192:195], v[42:45]
	v_mfma_f32_16x16x32_bf16 v[34:37], v[176:179], v[200:203], v[34:37]
	v_mfma_f32_16x16x32_bf16 v[26:29], v[184:187], v[200:203], v[26:29]
	v_mfma_f32_16x16x32_bf16 v[18:21], v[176:179], v[208:211], v[18:21]
	v_mfma_f32_16x16x32_bf16 v[10:13], v[184:187], v[208:211], v[10:13]
	v_mfma_f32_16x16x32_bf16 v[6:9], v[176:179], v[216:219], v[6:9]
	v_mfma_f32_16x16x32_bf16 v[2:5], v[184:187], v[216:219], v[2:5]
	s_setprio 0
	s_barrier
	s_add_i32 s48, 0, 0x18000
	v_add_u32_e32 v140, s48, v154
	s_add_i32 s49, 0, 0x1c000
	ds_read_b128 v[150:153], v140
	ds_read_b128 v[160:163], v140 offset:1024
	ds_read_b128 v[164:167], v140 offset:2048
	ds_read_b128 v[168:171], v140 offset:3072
	v_add_u32_e32 v140, s49, v154
	ds_read_b128 v[172:175], v140
	ds_read_b128 v[176:179], v140 offset:1024
	ds_read_b128 v[180:183], v140 offset:2048
	ds_read_b128 v[184:187], v140 offset:3072
	s_add_u32 s24, s24, 0x80000
	s_addc_u32 s25, s25, 0
	s_mov_b32 m0, s34
	v_lshl_add_u64 v[230:231], s[24:25], 0, v[138:139]
	ds_read_b128 v[188:191], v158 offset:32768
	ds_read_b128 v[192:195], v158 offset:33792
	ds_read_b128 v[196:199], v158 offset:34816
	ds_read_b128 v[200:203], v158 offset:35840
	ds_read_b128 v[204:207], v158 offset:36864
	ds_read_b128 v[208:211], v158 offset:37888
	ds_read_b128 v[212:215], v158 offset:38912
	ds_read_b128 v[216:219], v158 offset:39936
	global_load_lds_dwordx4 v[230:231], off
	v_lshl_add_u64 v[230:231], s[24:25], 0, v[134:135]
	s_mov_b32 m0, s35
	s_nop 0
	global_load_lds_dwordx4 v[230:231], off
	s_waitcnt vmcnt(8)
	s_waitcnt lgkmcnt(0)
	s_setprio 1
	s_barrier
	v_mfma_f32_16x16x32_bf16 v[126:129], v[150:153], v[188:191], v[126:129]
	v_mfma_f32_16x16x32_bf16 v[122:125], v[164:167], v[188:191], v[122:125]
	v_mfma_f32_16x16x32_bf16 v[118:121], v[150:153], v[196:199], v[118:121]
	v_mfma_f32_16x16x32_bf16 v[110:113], v[164:167], v[196:199], v[110:113]
	v_mfma_f32_16x16x32_bf16 v[102:105], v[150:153], v[204:207], v[102:105]
	v_mfma_f32_16x16x32_bf16 v[94:97], v[164:167], v[204:207], v[94:97]
	v_mfma_f32_16x16x32_bf16 v[86:89], v[150:153], v[212:215], v[86:89]
	v_mfma_f32_16x16x32_bf16 v[78:81], v[164:167], v[212:215], v[78:81]
	v_mfma_f32_16x16x32_bf16 v[126:129], v[160:163], v[192:195], v[126:129]
	v_mfma_f32_16x16x32_bf16 v[122:125], v[168:171], v[192:195], v[122:125]
	v_mfma_f32_16x16x32_bf16 v[118:121], v[160:163], v[200:203], v[118:121]
	v_mfma_f32_16x16x32_bf16 v[110:113], v[168:171], v[200:203], v[110:113]
	v_mfma_f32_16x16x32_bf16 v[102:105], v[160:163], v[208:211], v[102:105]
	v_mfma_f32_16x16x32_bf16 v[94:97], v[168:171], v[208:211], v[94:97]
	v_mfma_f32_16x16x32_bf16 v[86:89], v[160:163], v[216:219], v[86:89]
	v_mfma_f32_16x16x32_bf16 v[78:81], v[168:171], v[216:219], v[78:81]
	s_setprio 0
	s_setprio 1
	v_mfma_f32_16x16x32_bf16 v[114:117], v[172:175], v[188:191], v[114:117]
	v_mfma_f32_16x16x32_bf16 v[106:109], v[180:183], v[188:191], v[106:109]
	v_mfma_f32_16x16x32_bf16 v[98:101], v[172:175], v[196:199], v[98:101]
	v_mfma_f32_16x16x32_bf16 v[90:93], v[180:183], v[196:199], v[90:93]
	v_mfma_f32_16x16x32_bf16 v[82:85], v[172:175], v[204:207], v[82:85]
	v_mfma_f32_16x16x32_bf16 v[74:77], v[180:183], v[204:207], v[74:77]
	v_mfma_f32_16x16x32_bf16 v[70:73], v[172:175], v[212:215], v[70:73]
	v_mfma_f32_16x16x32_bf16 v[66:69], v[180:183], v[212:215], v[66:69]
	v_mfma_f32_16x16x32_bf16 v[114:117], v[176:179], v[192:195], v[114:117]
	v_mfma_f32_16x16x32_bf16 v[106:109], v[184:187], v[192:195], v[106:109]
	v_mfma_f32_16x16x32_bf16 v[98:101], v[176:179], v[200:203], v[98:101]
	v_mfma_f32_16x16x32_bf16 v[90:93], v[184:187], v[200:203], v[90:93]
	v_mfma_f32_16x16x32_bf16 v[82:85], v[176:179], v[208:211], v[82:85]
	v_mfma_f32_16x16x32_bf16 v[74:77], v[184:187], v[208:211], v[74:77]
	v_mfma_f32_16x16x32_bf16 v[70:73], v[176:179], v[216:219], v[70:73]
	v_mfma_f32_16x16x32_bf16 v[66:69], v[184:187], v[216:219], v[66:69]
	s_setprio 0
	s_barrier
; #define PG8_STAGE(bufoff, gbase, voff) do { _Pragma("unroll") for (int _i = 0; _i < 2; ++_i) \
;         __builtin_amdgcn_global_load_lds((const unsigned*)((const char*)(gbase) + (voff)[_i]), (PG8_LAS unsigned*)(lds + (bufoff) + ldsw + _i * 8192), 16, 0, 0); } while (0)
; #define PG8_WAIT_V(n) asm volatile("s_waitcnt vmcnt(" #n ")" ::: "memory")
; #define PG8_WAIT_L(n) asm volatile("s_waitcnt lgkmcnt(" #n ")" ::: "memory")
; #define PG8_BAR __builtin_amdgcn_s_barrier()
; #define PG8_SCHED __builtin_amdgcn_sched_barrier(0)
; template <class Epi, class Sched, bool ALIGN_EPI = true, bool SP2 = true>
; __device__ __forceinline__ void gemm_phase(PG8_LAS unsigned char* lds, const int K  , const Sched& S, const Epi& E) {
;     ...
;             PG8_LDA(At, 1, 1); PG8_STAGE(PG8_SB(1, 0), b3, voffB); PG8_STAGE(PG8_SB(1, 1), b3 + hstep, voffB); PG8_STAGE(PG8_SA(1, 0), a3, voffA);
;             PG8_WAIT_V(8); PG8_WAIT_L(0); PG8_BAR; PG8_MMA(1, 0, At, B0); PG8_MMA(1, 1, At, B1); PG8_BAR; PG8_SCHED;
;     ...
;         if constexpr (ALIGN_EPI) { if (wr == 0) PG8_BAR; }
	s_add_i32 s24, s48, s29
	v_lshl_add_u64 v[220:221], v[220:221], 0, s[6:7]
	s_mov_b32 m0, s24
	ds_read_b128 v[188:191], v158 offset:49152
	ds_read_b128 v[192:195], v158 offset:50176
	ds_read_b128 v[196:199], v158 offset:51200
	ds_read_b128 v[200:203], v158 offset:52224
	ds_read_b128 v[204:207], v158 offset:53248
	ds_read_b128 v[208:211], v158 offset:54272
	ds_read_b128 v[212:215], v158 offset:55296
	ds_read_b128 v[216:219], v158 offset:56320
	global_load_lds_dwordx4 v[220:221], off
	s_add_i32 m0, s24, 0x2000
	s_add_u32 s22, s22, 0x80080
	v_lshl_add_u64 v[220:221], v[222:223], 0, s[6:7]
	s_addc_u32 s23, s23, 0
	s_add_i32 s24, s49, s29
	global_load_lds_dwordx4 v[220:221], off
	v_lshl_add_u64 v[220:221], s[22:23], 0, v[136:137]
	s_mov_b32 m0, s24
	s_nop 0
	global_load_lds_dwordx4 v[220:221], off
	v_lshl_add_u64 v[220:221], s[22:23], 0, v[132:133]
	s_add_i32 m0, s24, 0x2000
	s_nop 0
	global_load_lds_dwordx4 v[220:221], off
	v_lshl_add_u64 v[220:221], v[224:225], 0, s[6:7]
	s_mov_b32 m0, s37
	s_nop 0
	global_load_lds_dwordx4 v[220:221], off
	v_lshl_add_u64 v[220:221], v[226:227], 0, s[6:7]
	s_mov_b32 m0, s38
	s_nop 0
	global_load_lds_dwordx4 v[220:221], off
	s_waitcnt vmcnt(8)
	s_waitcnt lgkmcnt(0)
	s_setprio 1
	s_barrier
	v_mfma_f32_16x16x32_bf16 v[62:65], v[150:153], v[188:191], v[62:65]
	v_mfma_f32_16x16x32_bf16 v[58:61], v[164:167], v[188:191], v[58:61]
	v_mfma_f32_16x16x32_bf16 v[54:57], v[150:153], v[196:199], v[54:57]
	v_mfma_f32_16x16x32_bf16 v[46:49], v[164:167], v[196:199], v[46:49]
	v_mfma_f32_16x16x32_bf16 v[38:41], v[150:153], v[204:207], v[38:41]
	v_mfma_f32_16x16x32_bf16 v[30:33], v[164:167], v[204:207], v[30:33]
	v_mfma_f32_16x16x32_bf16 v[22:25], v[150:153], v[212:215], v[22:25]
	v_mfma_f32_16x16x32_bf16 v[14:17], v[164:167], v[212:215], v[14:17]
	v_mfma_f32_16x16x32_bf16 v[62:65], v[160:163], v[192:195], v[62:65]
	v_mfma_f32_16x16x32_bf16 v[58:61], v[168:171], v[192:195], v[58:61]
	v_mfma_f32_16x16x32_bf16 v[54:57], v[160:163], v[200:203], v[54:57]
	v_mfma_f32_16x16x32_bf16 v[46:49], v[168:171], v[200:203], v[46:49]
	v_mfma_f32_16x16x32_bf16 v[38:41], v[160:163], v[208:211], v[38:41]
	v_mfma_f32_16x16x32_bf16 v[30:33], v[168:171], v[208:211], v[30:33]
	v_mfma_f32_16x16x32_bf16 v[22:25], v[160:163], v[216:219], v[22:25]
	v_mfma_f32_16x16x32_bf16 v[14:17], v[168:171], v[216:219], v[14:17]
	s_setprio 0
	s_setprio 1
	v_mfma_f32_16x16x32_bf16 v[50:53], v[172:175], v[188:191], v[50:53]
	v_mfma_f32_16x16x32_bf16 v[42:45], v[180:183], v[188:191], v[42:45]
	v_mfma_f32_16x16x32_bf16 v[34:37], v[172:175], v[196:199], v[34:37]
	v_mfma_f32_16x16x32_bf16 v[26:29], v[180:183], v[196:199], v[26:29]
	v_mfma_f32_16x16x32_bf16 v[18:21], v[172:175], v[204:207], v[18:21]
	v_mfma_f32_16x16x32_bf16 v[10:13], v[180:183], v[204:207], v[10:13]
	v_mfma_f32_16x16x32_bf16 v[6:9], v[172:175], v[212:215], v[6:9]
	v_mfma_f32_16x16x32_bf16 v[2:5], v[180:183], v[212:215], v[2:5]
	v_mfma_f32_16x16x32_bf16 v[50:53], v[176:179], v[192:195], v[50:53]
	v_mfma_f32_16x16x32_bf16 v[42:45], v[184:187], v[192:195], v[42:45]
	v_mfma_f32_16x16x32_bf16 v[34:37], v[176:179], v[200:203], v[34:37]
	v_mfma_f32_16x16x32_bf16 v[26:29], v[184:187], v[200:203], v[26:29]
	v_mfma_f32_16x16x32_bf16 v[18:21], v[176:179], v[208:211], v[18:21]
	v_mfma_f32_16x16x32_bf16 v[10:13], v[184:187], v[208:211], v[10:13]
	v_mfma_f32_16x16x32_bf16 v[6:9], v[176:179], v[216:219], v[6:9]
	v_mfma_f32_16x16x32_bf16 v[2:5], v[184:187], v[216:219], v[2:5]
	s_setprio 0
	s_barrier
	s_add_i32 s47, s47, 2
	s_add_u32 s20, s20, 0x100
	s_addc_u32 s21, s21, 0
	s_add_u32 s45, s45, 0x100
	s_addc_u32 s46, s46, 0
	s_cmp_gt_u32 s47, 29
	s_cbranch_scc0 .LBB0_537
	s_and_b64 vcc, exec, s[8:9]
	s_cbranch_vccz .LBB0_540
	s_barrier

; #define PG8_STAGE(bufoff, gbase, voff) do { _Pragma("unroll") for (int _i = 0; _i < 2; ++_i) \
;         __builtin_amdgcn_global_load_lds((const unsigned*)((const char*)(gbase) + (voff)[_i]), (PG8_LAS unsigned*)(lds + (bufoff) + ldsw + _i * 8192), 16, 0, 0); } while (0)
; #define PG8_WAIT_V(n) asm volatile("s_waitcnt vmcnt(" #n ")" ::: "memory")
; #define PG8_WAIT_L(n) asm volatile("s_waitcnt lgkmcnt(" #n ")" ::: "memory")
; #define PG8_BAR __builtin_amdgcn_s_barrier()
; #define PG8_SCHED __builtin_amdgcn_sched_barrier(0)
; template <class Epi, class Sched, bool ALIGN_EPI = true, bool SP2 = true>
; __device__ __forceinline__ void gemm_phase(PG8_LAS unsigned char* lds, const int K  , const Sched& S, const Epi& E) {
;     ...
;             PG8_LDB(B0, 0, 0); PG8_LDB(B1, 0, 1); PG8_SCHED; PG8_LDA(At, 0, 0); PG8_STAGE(PG8_SA(1, 1), a1 + hstep, voffA);
;             PG8_WAIT_V(8); PG8_WAIT_L(0); PG8_BAR; PG8_MMA(0, 0, At, B0); PG8_MMA(0, 1, At, B1); PG8_BAR; PG8_SCHED;
;             PG8_LDA(At, 0, 1); PG8_STAGE(PG8_SB(0, 0), b2, voffB); PG8_STAGE(PG8_SB(0, 1), b2 + hstep, voffB); PG8_STAGE(PG8_SA(0, 0), a2, voffA);
.LBB0_955:
	s_waitcnt vmcnt(0)
	ds_read_b128 v[130:133], v232
	ds_read_b128 v[134:137], v232 offset:1024
	ds_read_b128 v[138:141], v232 offset:2048
	ds_read_b128 v[142:145], v232 offset:3072
	ds_read_b128 v[146:149], v233
	ds_read_b128 v[150:153], v233 offset:1024
	ds_read_b128 v[154:157], v233 offset:2048
	ds_read_b128 v[158:161], v233 offset:3072
	s_add_i32 s73, s28, 2
	s_add_u32 s26, s24, 0xfff80080
	s_addc_u32 s27, s25, -1
	s_cmp_eq_u32 s13, s28
	s_cselect_b32 s28, s16, s26
	s_cselect_b32 s29, s17, s27
	s_cselect_b32 s27, s19, s21
	s_cselect_b32 s26, s18, s15
	v_lshl_add_u64 v[194:195], s[24:25], 0, v[214:215]
	s_add_i32 m0, s23, 0xc000
	ds_read_b128 v[162:165], v234
	ds_read_b128 v[166:169], v234 offset:1024
	ds_read_b128 v[170:173], v234 offset:2048
	ds_read_b128 v[174:177], v234 offset:3072
	ds_read_b128 v[178:181], v234 offset:4096
	ds_read_b128 v[182:185], v234 offset:5120
	ds_read_b128 v[186:189], v234 offset:6144
	ds_read_b128 v[190:193], v234 offset:7168
	global_load_lds_dwordx4 v[194:195], off
	v_lshl_add_u64 v[194:195], s[24:25], 0, v[216:217]
	s_add_i32 m0, s23, 0xe000
	s_nop 0
	global_load_lds_dwordx4 v[194:195], off
	s_waitcnt vmcnt(8)
	s_waitcnt lgkmcnt(0)
	s_setprio 1
	s_barrier
	v_mfma_f32_16x16x32_bf16 v[126:129], v[130:133], v[162:165], v[126:129]
	v_mfma_f32_16x16x32_bf16 v[122:125], v[138:141], v[162:165], v[122:125]
	v_mfma_f32_16x16x32_bf16 v[118:121], v[130:133], v[170:173], v[118:121]
	v_mfma_f32_16x16x32_bf16 v[110:113], v[138:141], v[170:173], v[110:113]
	v_mfma_f32_16x16x32_bf16 v[102:105], v[130:133], v[178:181], v[102:105]
	v_mfma_f32_16x16x32_bf16 v[94:97], v[138:141], v[178:181], v[94:97]
	v_mfma_f32_16x16x32_bf16 v[86:89], v[130:133], v[186:189], v[86:89]
	v_mfma_f32_16x16x32_bf16 v[78:81], v[138:141], v[186:189], v[78:81]
	v_mfma_f32_16x16x32_bf16 v[126:129], v[134:137], v[166:169], v[126:129]
	v_mfma_f32_16x16x32_bf16 v[122:125], v[142:145], v[166:169], v[122:125]
	v_mfma_f32_16x16x32_bf16 v[118:121], v[134:137], v[174:177], v[118:121]
	v_mfma_f32_16x16x32_bf16 v[110:113], v[142:145], v[174:177], v[110:113]
	v_mfma_f32_16x16x32_bf16 v[102:105], v[134:137], v[182:185], v[102:105]
	v_mfma_f32_16x16x32_bf16 v[94:97], v[142:145], v[182:185], v[94:97]
	v_mfma_f32_16x16x32_bf16 v[86:89], v[134:137], v[190:193], v[86:89]
	v_mfma_f32_16x16x32_bf16 v[78:81], v[142:145], v[190:193], v[78:81]
	s_setprio 0
	s_setprio 1
	v_mfma_f32_16x16x32_bf16 v[114:117], v[146:149], v[162:165], v[114:117]
	v_mfma_f32_16x16x32_bf16 v[106:109], v[154:157], v[162:165], v[106:109]
	v_mfma_f32_16x16x32_bf16 v[98:101], v[146:149], v[170:173], v[98:101]
	v_mfma_f32_16x16x32_bf16 v[90:93], v[154:157], v[170:173], v[90:93]
	v_mfma_f32_16x16x32_bf16 v[82:85], v[146:149], v[178:181], v[82:85]
	v_mfma_f32_16x16x32_bf16 v[74:77], v[154:157], v[178:181], v[74:77]
	v_mfma_f32_16x16x32_bf16 v[70:73], v[146:149], v[186:189], v[70:73]
	v_mfma_f32_16x16x32_bf16 v[66:69], v[154:157], v[186:189], v[66:69]
	v_mfma_f32_16x16x32_bf16 v[114:117], v[150:153], v[166:169], v[114:117]
	v_mfma_f32_16x16x32_bf16 v[106:109], v[158:161], v[166:169], v[106:109]
	v_mfma_f32_16x16x32_bf16 v[98:101], v[150:153], v[174:177], v[98:101]
	v_mfma_f32_16x16x32_bf16 v[90:93], v[158:161], v[174:177], v[90:93]
	v_mfma_f32_16x16x32_bf16 v[82:85], v[150:153], v[182:185], v[82:85]
	v_mfma_f32_16x16x32_bf16 v[74:77], v[158:161], v[182:185], v[74:77]
	v_mfma_f32_16x16x32_bf16 v[70:73], v[150:153], v[190:193], v[70:73]
	v_mfma_f32_16x16x32_bf16 v[66:69], v[158:161], v[190:193], v[66:69]
	s_setprio 0
	s_barrier
	s_add_i32 s74, s47, s33
	v_lshl_add_u64 v[194:195], s[26:27], 0, v[208:209]
	s_mov_b32 m0, s74
	ds_read_b128 v[162:165], v234 offset:16384
	ds_read_b128 v[166:169], v234 offset:17408
	ds_read_b128 v[170:173], v234 offset:18432
	ds_read_b128 v[174:177], v234 offset:19456
	ds_read_b128 v[178:181], v234 offset:20480
	ds_read_b128 v[182:185], v234 offset:21504
	ds_read_b128 v[186:189], v234 offset:22528
	ds_read_b128 v[190:193], v234 offset:23552
	global_load_lds_dwordx4 v[194:195], off
	s_add_i32 m0, s74, 0x2000
	s_add_u32 s74, s26, 0x80000
	v_lshl_add_u64 v[196:197], s[26:27], 0, v[212:213]
	s_addc_u32 s75, s27, 0
	s_add_i32 s76, s48, s33
	global_load_lds_dwordx4 v[196:197], off
	v_lshl_add_u64 v[198:199], s[74:75], 0, v[208:209]
	s_mov_b32 m0, s76
	v_lshl_add_u64 v[200:201], s[28:29], 0, v[210:211]
	global_load_lds_dwordx4 v[198:199], off
	v_lshl_add_u64 v[198:199], s[74:75], 0, v[212:213]
	s_add_i32 m0, s76, 0x2000
	s_nop 0
	global_load_lds_dwordx4 v[198:199], off
	v_lshl_add_u64 v[198:199], s[28:29], 0, v[206:207]
	s_mov_b32 m0, s23
	s_nop 0
	global_load_lds_dwordx4 v[198:199], off
	s_mov_b32 m0, s34
	s_nop 0
	global_load_lds_dwordx4 v[200:201], off
	s_waitcnt vmcnt(8)
	s_waitcnt lgkmcnt(0)
	s_setprio 1
	s_barrier
; #define PG8_STAGE(bufoff, gbase, voff) do { _Pragma("unroll") for (int _i = 0; _i < 2; ++_i) \
;         __builtin_amdgcn_global_load_lds((const unsigned*)((const char*)(gbase) + (voff)[_i]), (PG8_LAS unsigned*)(lds + (bufoff) + ldsw + _i * 8192), 16, 0, 0); } while (0)
; #define PG8_WAIT_V(n) asm volatile("s_waitcnt vmcnt(" #n ")" ::: "memory")
; #define PG8_WAIT_L(n) asm volatile("s_waitcnt lgkmcnt(" #n ")" ::: "memory")
; #define PG8_BAR __builtin_amdgcn_s_barrier()
; #define PG8_SCHED __builtin_amdgcn_sched_barrier(0)
; template <class Epi, class Sched, bool ALIGN_EPI = true, bool SP2 = true>
; __device__ __forceinline__ void gemm_phase(PG8_LAS unsigned char* lds, const int K  , const Sched& S, const Epi& E) {
;     ...
;             PG8_WAIT_V(8); PG8_WAIT_L(0); PG8_BAR; PG8_MMA(1, 0, At, B0); PG8_MMA(1, 1, At, B1); PG8_BAR; PG8_SCHED;
;             PG8_LDB(B0, 1, 0); PG8_LDB(B1, 1, 1); PG8_SCHED; PG8_LDA(At, 1, 0); PG8_STAGE(PG8_SA(0, 1), a2 + hstep, voffA);
;             PG8_WAIT_V(8); PG8_WAIT_L(0); PG8_BAR; PG8_MMA(0, 0, At, B0); PG8_MMA(0, 1, At, B1); PG8_BAR; PG8_SCHED;
	v_mfma_f32_16x16x32_bf16 v[62:65], v[130:133], v[162:165], v[62:65]
	v_mfma_f32_16x16x32_bf16 v[58:61], v[138:141], v[162:165], v[58:61]
	v_mfma_f32_16x16x32_bf16 v[54:57], v[130:133], v[170:173], v[54:57]
	v_mfma_f32_16x16x32_bf16 v[46:49], v[138:141], v[170:173], v[46:49]
	v_mfma_f32_16x16x32_bf16 v[38:41], v[130:133], v[178:181], v[38:41]
	v_mfma_f32_16x16x32_bf16 v[30:33], v[138:141], v[178:181], v[30:33]
	v_mfma_f32_16x16x32_bf16 v[22:25], v[130:133], v[186:189], v[22:25]
	v_mfma_f32_16x16x32_bf16 v[14:17], v[138:141], v[186:189], v[14:17]
	v_mfma_f32_16x16x32_bf16 v[62:65], v[134:137], v[166:169], v[62:65]
	v_mfma_f32_16x16x32_bf16 v[58:61], v[142:145], v[166:169], v[58:61]
	v_mfma_f32_16x16x32_bf16 v[54:57], v[134:137], v[174:177], v[54:57]
	v_mfma_f32_16x16x32_bf16 v[46:49], v[142:145], v[174:177], v[46:49]
	v_mfma_f32_16x16x32_bf16 v[38:41], v[134:137], v[182:185], v[38:41]
	v_mfma_f32_16x16x32_bf16 v[30:33], v[142:145], v[182:185], v[30:33]
	v_mfma_f32_16x16x32_bf16 v[22:25], v[134:137], v[190:193], v[22:25]
	v_mfma_f32_16x16x32_bf16 v[14:17], v[142:145], v[190:193], v[14:17]
	s_setprio 0
	s_setprio 1
	v_mfma_f32_16x16x32_bf16 v[50:53], v[146:149], v[162:165], v[50:53]
	v_mfma_f32_16x16x32_bf16 v[42:45], v[154:157], v[162:165], v[42:45]
	v_mfma_f32_16x16x32_bf16 v[34:37], v[146:149], v[170:173], v[34:37]
	v_mfma_f32_16x16x32_bf16 v[26:29], v[154:157], v[170:173], v[26:29]
	v_mfma_f32_16x16x32_bf16 v[18:21], v[146:149], v[178:181], v[18:21]
	v_mfma_f32_16x16x32_bf16 v[10:13], v[154:157], v[178:181], v[10:13]
	v_mfma_f32_16x16x32_bf16 v[6:9], v[146:149], v[186:189], v[6:9]
	v_mfma_f32_16x16x32_bf16 v[2:5], v[154:157], v[186:189], v[2:5]
	v_mfma_f32_16x16x32_bf16 v[50:53], v[150:153], v[166:169], v[50:53]
	v_mfma_f32_16x16x32_bf16 v[42:45], v[158:161], v[166:169], v[42:45]
	v_mfma_f32_16x16x32_bf16 v[34:37], v[150:153], v[174:177], v[34:37]
	v_mfma_f32_16x16x32_bf16 v[26:29], v[158:161], v[174:177], v[26:29]
	v_mfma_f32_16x16x32_bf16 v[18:21], v[150:153], v[182:185], v[18:21]
	v_mfma_f32_16x16x32_bf16 v[10:13], v[158:161], v[182:185], v[10:13]
	v_mfma_f32_16x16x32_bf16 v[6:9], v[150:153], v[190:193], v[6:9]
	v_mfma_f32_16x16x32_bf16 v[2:5], v[158:161], v[190:193], v[2:5]
	s_setprio 0
	s_barrier
	s_add_i32 s74, 0, 0x18000
	s_add_i32 s75, 0, 0x1c000
	v_add_u32_e32 v142, s74, v230
	v_add_u32_e32 v158, s75, v230
	ds_read_b128 v[130:133], v142
	ds_read_b128 v[134:137], v142 offset:1024
	ds_read_b128 v[138:141], v142 offset:2048
	ds_read_b128 v[142:145], v142 offset:3072
	ds_read_b128 v[146:149], v158
	ds_read_b128 v[150:153], v158 offset:1024
	ds_read_b128 v[154:157], v158 offset:2048
	ds_read_b128 v[158:161], v158 offset:3072
	s_add_u32 s28, s28, 0x80000
	s_addc_u32 s29, s29, 0
	s_mov_b32 m0, s35
	v_lshl_add_u64 v[202:203], s[28:29], 0, v[206:207]
	ds_read_b128 v[162:165], v234 offset:32768
	ds_read_b128 v[166:169], v234 offset:33792
	ds_read_b128 v[170:173], v234 offset:34816
	ds_read_b128 v[174:177], v234 offset:35840
	ds_read_b128 v[178:181], v234 offset:36864
	ds_read_b128 v[182:185], v234 offset:37888
	ds_read_b128 v[186:189], v234 offset:38912
	ds_read_b128 v[190:193], v234 offset:39936
	global_load_lds_dwordx4 v[202:203], off
	v_lshl_add_u64 v[202:203], s[28:29], 0, v[210:211]
	s_mov_b32 m0, s36
	s_nop 0
	global_load_lds_dwordx4 v[202:203], off
	s_waitcnt vmcnt(8)
	s_waitcnt lgkmcnt(0)
	s_setprio 1
	s_barrier
	v_mfma_f32_16x16x32_bf16 v[126:129], v[130:133], v[162:165], v[126:129]
	v_mfma_f32_16x16x32_bf16 v[122:125], v[138:141], v[162:165], v[122:125]
	v_mfma_f32_16x16x32_bf16 v[118:121], v[130:133], v[170:173], v[118:121]
	v_mfma_f32_16x16x32_bf16 v[110:113], v[138:141], v[170:173], v[110:113]
	v_mfma_f32_16x16x32_bf16 v[102:105], v[130:133], v[178:181], v[102:105]
	v_mfma_f32_16x16x32_bf16 v[94:97], v[138:141], v[178:181], v[94:97]
	v_mfma_f32_16x16x32_bf16 v[86:89], v[130:133], v[186:189], v[86:89]
	v_mfma_f32_16x16x32_bf16 v[78:81], v[138:141], v[186:189], v[78:81]
	v_mfma_f32_16x16x32_bf16 v[126:129], v[134:137], v[166:169], v[126:129]
	v_mfma_f32_16x16x32_bf16 v[122:125], v[142:145], v[166:169], v[122:125]
	v_mfma_f32_16x16x32_bf16 v[118:121], v[134:137], v[174:177], v[118:121]
	v_mfma_f32_16x16x32_bf16 v[110:113], v[142:145], v[174:177], v[110:113]
	v_mfma_f32_16x16x32_bf16 v[102:105], v[134:137], v[182:185], v[102:105]
	v_mfma_f32_16x16x32_bf16 v[94:97], v[142:145], v[182:185], v[94:97]
	v_mfma_f32_16x16x32_bf16 v[86:89], v[134:137], v[190:193], v[86:89]
	v_mfma_f32_16x16x32_bf16 v[78:81], v[142:145], v[190:193], v[78:81]
	s_setprio 0
	s_setprio 1
	v_mfma_f32_16x16x32_bf16 v[114:117], v[146:149], v[162:165], v[114:117]
	v_mfma_f32_16x16x32_bf16 v[106:109], v[154:157], v[162:165], v[106:109]
	v_mfma_f32_16x16x32_bf16 v[98:101], v[146:149], v[170:173], v[98:101]
	v_mfma_f32_16x16x32_bf16 v[90:93], v[154:157], v[170:173], v[90:93]
	v_mfma_f32_16x16x32_bf16 v[82:85], v[146:149], v[178:181], v[82:85]
	v_mfma_f32_16x16x32_bf16 v[74:77], v[154:157], v[178:181], v[74:77]
	v_mfma_f32_16x16x32_bf16 v[70:73], v[146:149], v[186:189], v[70:73]
	v_mfma_f32_16x16x32_bf16 v[66:69], v[154:157], v[186:189], v[66:69]
	v_mfma_f32_16x16x32_bf16 v[114:117], v[150:153], v[166:169], v[114:117]
	v_mfma_f32_16x16x32_bf16 v[106:109], v[158:161], v[166:169], v[106:109]
	v_mfma_f32_16x16x32_bf16 v[98:101], v[150:153], v[174:177], v[98:101]
	v_mfma_f32_16x16x32_bf16 v[90:93], v[158:161], v[174:177], v[90:93]
	v_mfma_f32_16x16x32_bf16 v[82:85], v[150:153], v[182:185], v[82:85]
	v_mfma_f32_16x16x32_bf16 v[74:77], v[158:161], v[182:185], v[74:77]
	v_mfma_f32_16x16x32_bf16 v[70:73], v[150:153], v[190:193], v[70:73]
	v_mfma_f32_16x16x32_bf16 v[66:69], v[158:161], v[190:193], v[66:69]
	s_setprio 0
	s_barrier
; #define PG8_STAGE(bufoff, gbase, voff) do { _Pragma("unroll") for (int _i = 0; _i < 2; ++_i) \
;         __builtin_amdgcn_global_load_lds((const unsigned*)((const char*)(gbase) + (voff)[_i]), (PG8_LAS unsigned*)(lds + (bufoff) + ldsw + _i * 8192), 16, 0, 0); } while (0)
; #define PG8_WAIT_V(n) asm volatile("s_waitcnt vmcnt(" #n ")" ::: "memory")
; #define PG8_WAIT_L(n) asm volatile("s_waitcnt lgkmcnt(" #n ")" ::: "memory")
; #define PG8_BAR __builtin_amdgcn_s_barrier()
; #define PG8_SCHED __builtin_amdgcn_sched_barrier(0)
; template <class Epi, class Sched, bool ALIGN_EPI = true, bool SP2 = true>
; __device__ __forceinline__ void gemm_phase(PG8_LAS unsigned char* lds, const int K  , const Sched& S, const Epi& E) {
;     ...
;             PG8_LDA(At, 1, 1); PG8_STAGE(PG8_SB(1, 0), b3, voffB); PG8_STAGE(PG8_SB(1, 1), b3 + hstep, voffB); PG8_STAGE(PG8_SA(1, 0), a3, voffA);
;             PG8_WAIT_V(8); PG8_WAIT_L(0); PG8_BAR; PG8_MMA(1, 0, At, B0); PG8_MMA(1, 1, At, B1); PG8_BAR; PG8_SCHED;
;     ...
;         if constexpr (ALIGN_EPI) { if (wr == 0) PG8_BAR; }
	s_add_i32 s28, s74, s33
	v_lshl_add_u64 v[194:195], v[194:195], 0, s[8:9]
	s_mov_b32 m0, s28
	ds_read_b128 v[162:165], v234 offset:49152
	ds_read_b128 v[166:169], v234 offset:50176
	ds_read_b128 v[170:173], v234 offset:51200
	ds_read_b128 v[174:177], v234 offset:52224
	ds_read_b128 v[178:181], v234 offset:53248
	ds_read_b128 v[182:185], v234 offset:54272
	ds_read_b128 v[186:189], v234 offset:55296
	ds_read_b128 v[190:193], v234 offset:56320
	global_load_lds_dwordx4 v[194:195], off
	s_add_i32 m0, s28, 0x2000
	s_add_u32 s26, s26, 0x80080
	v_lshl_add_u64 v[194:195], v[196:197], 0, s[8:9]
	s_addc_u32 s27, s27, 0
	s_add_i32 s28, s75, s33
	global_load_lds_dwordx4 v[194:195], off
	v_lshl_add_u64 v[194:195], s[26:27], 0, v[208:209]
	s_mov_b32 m0, s28
	s_nop 0
	global_load_lds_dwordx4 v[194:195], off
	v_lshl_add_u64 v[194:195], s[26:27], 0, v[212:213]
	s_add_i32 m0, s28, 0x2000
	s_nop 0
	global_load_lds_dwordx4 v[194:195], off
	v_lshl_add_u64 v[194:195], v[198:199], 0, s[8:9]
	s_mov_b32 m0, s42
	s_nop 0
	global_load_lds_dwordx4 v[194:195], off
	v_lshl_add_u64 v[194:195], v[200:201], 0, s[8:9]
	s_mov_b32 m0, s43
	s_nop 0
	global_load_lds_dwordx4 v[194:195], off
	s_waitcnt vmcnt(8)
	s_waitcnt lgkmcnt(0)
	s_setprio 1
	s_barrier
	v_mfma_f32_16x16x32_bf16 v[62:65], v[130:133], v[162:165], v[62:65]
	v_mfma_f32_16x16x32_bf16 v[58:61], v[138:141], v[162:165], v[58:61]
	v_mfma_f32_16x16x32_bf16 v[54:57], v[130:133], v[170:173], v[54:57]
	v_mfma_f32_16x16x32_bf16 v[46:49], v[138:141], v[170:173], v[46:49]
	v_mfma_f32_16x16x32_bf16 v[38:41], v[130:133], v[178:181], v[38:41]
	v_mfma_f32_16x16x32_bf16 v[30:33], v[138:141], v[178:181], v[30:33]
	v_mfma_f32_16x16x32_bf16 v[22:25], v[130:133], v[186:189], v[22:25]
	v_mfma_f32_16x16x32_bf16 v[14:17], v[138:141], v[186:189], v[14:17]
	v_mfma_f32_16x16x32_bf16 v[62:65], v[134:137], v[166:169], v[62:65]
	v_mfma_f32_16x16x32_bf16 v[58:61], v[142:145], v[166:169], v[58:61]
	v_mfma_f32_16x16x32_bf16 v[54:57], v[134:137], v[174:177], v[54:57]
	v_mfma_f32_16x16x32_bf16 v[46:49], v[142:145], v[174:177], v[46:49]
	v_mfma_f32_16x16x32_bf16 v[38:41], v[134:137], v[182:185], v[38:41]
	v_mfma_f32_16x16x32_bf16 v[30:33], v[142:145], v[182:185], v[30:33]
	v_mfma_f32_16x16x32_bf16 v[22:25], v[134:137], v[190:193], v[22:25]
	v_mfma_f32_16x16x32_bf16 v[14:17], v[142:145], v[190:193], v[14:17]
	s_setprio 0
	s_setprio 1
	v_mfma_f32_16x16x32_bf16 v[50:53], v[146:149], v[162:165], v[50:53]
	v_mfma_f32_16x16x32_bf16 v[42:45], v[154:157], v[162:165], v[42:45]
	v_mfma_f32_16x16x32_bf16 v[34:37], v[146:149], v[170:173], v[34:37]
	v_mfma_f32_16x16x32_bf16 v[26:29], v[154:157], v[170:173], v[26:29]
	v_mfma_f32_16x16x32_bf16 v[18:21], v[146:149], v[178:181], v[18:21]
	v_mfma_f32_16x16x32_bf16 v[10:13], v[154:157], v[178:181], v[10:13]
	v_mfma_f32_16x16x32_bf16 v[6:9], v[146:149], v[186:189], v[6:9]
	v_mfma_f32_16x16x32_bf16 v[2:5], v[154:157], v[186:189], v[2:5]
	v_mfma_f32_16x16x32_bf16 v[50:53], v[150:153], v[166:169], v[50:53]
	v_mfma_f32_16x16x32_bf16 v[42:45], v[158:161], v[166:169], v[42:45]
	v_mfma_f32_16x16x32_bf16 v[34:37], v[150:153], v[174:177], v[34:37]
	v_mfma_f32_16x16x32_bf16 v[26:29], v[158:161], v[174:177], v[26:29]
	v_mfma_f32_16x16x32_bf16 v[18:21], v[150:153], v[182:185], v[18:21]
	v_mfma_f32_16x16x32_bf16 v[10:13], v[158:161], v[182:185], v[10:13]
	v_mfma_f32_16x16x32_bf16 v[6:9], v[150:153], v[190:193], v[6:9]
	v_mfma_f32_16x16x32_bf16 v[2:5], v[158:161], v[190:193], v[2:5]
	s_setprio 0
	s_barrier
	s_add_u32 s24, s24, 0x100
	s_addc_u32 s25, s25, 0
	s_add_u32 s15, s15, 0x100
	s_addc_u32 s21, s21, 0
	s_cmp_ge_u32 s73, s4
	s_mov_b32 s28, s73
	s_cbranch_scc0 .LBB0_955
	s_and_b64 vcc, exec, s[10:11]
	s_cbranch_vccz .LBB0_958
	s_barrier

; #define PG8_STAGE(bufoff, gbase, voff) do { _Pragma("unroll") for (int _i = 0; _i < 2; ++_i) \
;         __builtin_amdgcn_global_load_lds((const unsigned*)((const char*)(gbase) + (voff)[_i]), (PG8_LAS unsigned*)(lds + (bufoff) + ldsw + _i * 8192), 16, 0, 0); } while (0)
; #define PG8_WAIT_V(n) asm volatile("s_waitcnt vmcnt(" #n ")" ::: "memory")
; #define PG8_WAIT_L(n) asm volatile("s_waitcnt lgkmcnt(" #n ")" ::: "memory")
; #define PG8_BAR __builtin_amdgcn_s_barrier()
; #define PG8_SCHED __builtin_amdgcn_sched_barrier(0)
; template <class Epi, class Sched, bool ALIGN_EPI = true, bool SP2 = true>
; __device__ __forceinline__ void gemm_phase(PG8_LAS unsigned char* lds, const int K  , const Sched& S, const Epi& E) {
;     ...
;             PG8_LDB(B0, 0, 0); PG8_LDB(B1, 0, 1); PG8_SCHED; PG8_LDA(At, 0, 0); PG8_STAGE(PG8_SA(1, 1), a1 + hstep, voffA);
;             PG8_WAIT_V(8); PG8_WAIT_L(0); PG8_BAR; PG8_MMA(0, 0, At, B0); PG8_MMA(0, 1, At, B1); PG8_BAR; PG8_SCHED;
;             PG8_LDA(At, 0, 1); PG8_STAGE(PG8_SB(0, 0), b2, voffB); PG8_STAGE(PG8_SB(0, 1), b2 + hstep, voffB); PG8_STAGE(PG8_SA(0, 0), a2, voffA);
.LBB0_1099:
	ds_read_b128 v[148:151], v154
	ds_read_b128 v[160:163], v154 offset:1024
	ds_read_b128 v[164:167], v154 offset:2048
	ds_read_b128 v[168:171], v154 offset:3072
	ds_read_b128 v[172:175], v155
	ds_read_b128 v[176:179], v155 offset:1024
	ds_read_b128 v[180:183], v155 offset:2048
	ds_read_b128 v[184:187], v155 offset:3072
	s_add_u32 s24, s22, 0xfff80080
	s_addc_u32 s25, s23, -1
	s_cmp_eq_u32 s48, 28
	s_cselect_b32 s27, s15, s25
	s_cselect_b32 s26, s44, s24
	s_cselect_b32 s25, s11, s47
	s_cselect_b32 s24, s45, s46
	v_lshl_add_u64 v[220:221], s[22:23], 0, v[140:141]
	s_add_i32 m0, s21, 0xc000
	ds_read_b128 v[188:191], v156
	ds_read_b128 v[192:195], v156 offset:1024
	ds_read_b128 v[196:199], v156 offset:2048
	ds_read_b128 v[200:203], v156 offset:3072
	ds_read_b128 v[204:207], v156 offset:4096
	ds_read_b128 v[208:211], v156 offset:5120
	ds_read_b128 v[212:215], v156 offset:6144
	ds_read_b128 v[216:219], v156 offset:7168
	global_load_lds_dwordx4 v[220:221], off
	v_lshl_add_u64 v[220:221], s[22:23], 0, v[142:143]
	s_add_i32 m0, s21, 0xe000
	s_nop 0
	global_load_lds_dwordx4 v[220:221], off
	s_waitcnt vmcnt(8)
	s_waitcnt lgkmcnt(0)
	s_setprio 1
	s_barrier
	v_mfma_f32_16x16x32_bf16 v[126:129], v[148:151], v[188:191], v[126:129]
	v_mfma_f32_16x16x32_bf16 v[118:121], v[164:167], v[188:191], v[118:121]
	v_mfma_f32_16x16x32_bf16 v[110:113], v[148:151], v[196:199], v[110:113]
	v_mfma_f32_16x16x32_bf16 v[102:105], v[164:167], v[196:199], v[102:105]
	v_mfma_f32_16x16x32_bf16 v[94:97], v[148:151], v[204:207], v[94:97]
	v_mfma_f32_16x16x32_bf16 v[86:89], v[164:167], v[204:207], v[86:89]
	v_mfma_f32_16x16x32_bf16 v[78:81], v[148:151], v[212:215], v[78:81]
	v_mfma_f32_16x16x32_bf16 v[70:73], v[164:167], v[212:215], v[70:73]
	v_mfma_f32_16x16x32_bf16 v[126:129], v[160:163], v[192:195], v[126:129]
	v_mfma_f32_16x16x32_bf16 v[118:121], v[168:171], v[192:195], v[118:121]
	v_mfma_f32_16x16x32_bf16 v[110:113], v[160:163], v[200:203], v[110:113]
	v_mfma_f32_16x16x32_bf16 v[102:105], v[168:171], v[200:203], v[102:105]
	v_mfma_f32_16x16x32_bf16 v[94:97], v[160:163], v[208:211], v[94:97]
	v_mfma_f32_16x16x32_bf16 v[86:89], v[168:171], v[208:211], v[86:89]
	v_mfma_f32_16x16x32_bf16 v[78:81], v[160:163], v[216:219], v[78:81]
	v_mfma_f32_16x16x32_bf16 v[70:73], v[168:171], v[216:219], v[70:73]
	s_setprio 0
	s_setprio 1
	v_mfma_f32_16x16x32_bf16 v[122:125], v[172:175], v[188:191], v[122:125]
	v_mfma_f32_16x16x32_bf16 v[114:117], v[180:183], v[188:191], v[114:117]
	v_mfma_f32_16x16x32_bf16 v[106:109], v[172:175], v[196:199], v[106:109]
	v_mfma_f32_16x16x32_bf16 v[98:101], v[180:183], v[196:199], v[98:101]
	v_mfma_f32_16x16x32_bf16 v[90:93], v[172:175], v[204:207], v[90:93]
	v_mfma_f32_16x16x32_bf16 v[82:85], v[180:183], v[204:207], v[82:85]
	v_mfma_f32_16x16x32_bf16 v[74:77], v[172:175], v[212:215], v[74:77]
	v_mfma_f32_16x16x32_bf16 v[66:69], v[180:183], v[212:215], v[66:69]
	v_mfma_f32_16x16x32_bf16 v[122:125], v[176:179], v[192:195], v[122:125]
	v_mfma_f32_16x16x32_bf16 v[114:117], v[184:187], v[192:195], v[114:117]
	v_mfma_f32_16x16x32_bf16 v[106:109], v[176:179], v[200:203], v[106:109]
	v_mfma_f32_16x16x32_bf16 v[98:101], v[184:187], v[200:203], v[98:101]
	v_mfma_f32_16x16x32_bf16 v[90:93], v[176:179], v[208:211], v[90:93]
	v_mfma_f32_16x16x32_bf16 v[82:85], v[184:187], v[208:211], v[82:85]
	v_mfma_f32_16x16x32_bf16 v[74:77], v[176:179], v[216:219], v[74:77]
	v_mfma_f32_16x16x32_bf16 v[66:69], v[184:187], v[216:219], v[66:69]
	s_setprio 0
	s_barrier
	s_add_i32 s49, s39, s29
	v_lshl_add_u64 v[220:221], s[24:25], 0, v[136:137]
	s_mov_b32 m0, s49
	ds_read_b128 v[188:191], v156 offset:16384
	ds_read_b128 v[192:195], v156 offset:17408
	ds_read_b128 v[196:199], v156 offset:18432
	ds_read_b128 v[200:203], v156 offset:19456
	ds_read_b128 v[204:207], v156 offset:20480
	ds_read_b128 v[208:211], v156 offset:21504
	ds_read_b128 v[212:215], v156 offset:22528
	ds_read_b128 v[216:219], v156 offset:23552
	global_load_lds_dwordx4 v[220:221], off
	s_add_i32 m0, s49, 0x2000
	s_add_u32 s50, s24, 0x80000
	v_lshl_add_u64 v[222:223], s[24:25], 0, v[132:133]
	s_addc_u32 s51, s25, 0
	s_add_i32 s49, s40, s29
	global_load_lds_dwordx4 v[222:223], off
	v_lshl_add_u64 v[224:225], s[50:51], 0, v[136:137]
	s_mov_b32 m0, s49
	v_lshl_add_u64 v[226:227], s[26:27], 0, v[134:135]
	global_load_lds_dwordx4 v[224:225], off
	v_lshl_add_u64 v[224:225], s[50:51], 0, v[132:133]
	s_add_i32 m0, s49, 0x2000
	s_nop 0
	global_load_lds_dwordx4 v[224:225], off
	v_lshl_add_u64 v[224:225], s[26:27], 0, v[138:139]
	s_mov_b32 m0, s21
	s_nop 0
	global_load_lds_dwordx4 v[224:225], off
	s_mov_b32 m0, s31
	s_nop 0
	global_load_lds_dwordx4 v[226:227], off
	s_waitcnt vmcnt(8)
	s_waitcnt lgkmcnt(0)
	s_setprio 1
	s_barrier
; #define PG8_STAGE(bufoff, gbase, voff) do { _Pragma("unroll") for (int _i = 0; _i < 2; ++_i) \
;         __builtin_amdgcn_global_load_lds((const unsigned*)((const char*)(gbase) + (voff)[_i]), (PG8_LAS unsigned*)(lds + (bufoff) + ldsw + _i * 8192), 16, 0, 0); } while (0)
; #define PG8_WAIT_V(n) asm volatile("s_waitcnt vmcnt(" #n ")" ::: "memory")
; #define PG8_WAIT_L(n) asm volatile("s_waitcnt lgkmcnt(" #n ")" ::: "memory")
; #define PG8_BAR __builtin_amdgcn_s_barrier()
; #define PG8_SCHED __builtin_amdgcn_sched_barrier(0)
; template <class Epi, class Sched, bool ALIGN_EPI = true, bool SP2 = true>
; __device__ __forceinline__ void gemm_phase(PG8_LAS unsigned char* lds, const int K  , const Sched& S, const Epi& E) {
;     ...
;             PG8_WAIT_V(8); PG8_WAIT_L(0); PG8_BAR; PG8_MMA(1, 0, At, B0); PG8_MMA(1, 1, At, B1); PG8_BAR; PG8_SCHED;
;             PG8_LDB(B0, 1, 0); PG8_LDB(B1, 1, 1); PG8_SCHED; PG8_LDA(At, 1, 0); PG8_STAGE(PG8_SA(0, 1), a2 + hstep, voffA);
;             PG8_WAIT_V(8); PG8_WAIT_L(0); PG8_BAR; PG8_MMA(0, 0, At, B0); PG8_MMA(0, 1, At, B1); PG8_BAR; PG8_SCHED;
	v_mfma_f32_16x16x32_bf16 v[62:65], v[148:151], v[188:191], v[62:65]
	v_mfma_f32_16x16x32_bf16 v[54:57], v[164:167], v[188:191], v[54:57]
	v_mfma_f32_16x16x32_bf16 v[46:49], v[148:151], v[196:199], v[46:49]
	v_mfma_f32_16x16x32_bf16 v[38:41], v[164:167], v[196:199], v[38:41]
	v_mfma_f32_16x16x32_bf16 v[30:33], v[148:151], v[204:207], v[30:33]
	v_mfma_f32_16x16x32_bf16 v[22:25], v[164:167], v[204:207], v[22:25]
	v_mfma_f32_16x16x32_bf16 v[14:17], v[148:151], v[212:215], v[14:17]
	v_mfma_f32_16x16x32_bf16 v[6:9], v[164:167], v[212:215], v[6:9]
	v_mfma_f32_16x16x32_bf16 v[62:65], v[160:163], v[192:195], v[62:65]
	v_mfma_f32_16x16x32_bf16 v[54:57], v[168:171], v[192:195], v[54:57]
	v_mfma_f32_16x16x32_bf16 v[46:49], v[160:163], v[200:203], v[46:49]
	v_mfma_f32_16x16x32_bf16 v[38:41], v[168:171], v[200:203], v[38:41]
	v_mfma_f32_16x16x32_bf16 v[30:33], v[160:163], v[208:211], v[30:33]
	v_mfma_f32_16x16x32_bf16 v[22:25], v[168:171], v[208:211], v[22:25]
	v_mfma_f32_16x16x32_bf16 v[14:17], v[160:163], v[216:219], v[14:17]
	v_mfma_f32_16x16x32_bf16 v[6:9], v[168:171], v[216:219], v[6:9]
	s_setprio 0
	s_setprio 1
	v_mfma_f32_16x16x32_bf16 v[58:61], v[172:175], v[188:191], v[58:61]
	v_mfma_f32_16x16x32_bf16 v[50:53], v[180:183], v[188:191], v[50:53]
	v_mfma_f32_16x16x32_bf16 v[42:45], v[172:175], v[196:199], v[42:45]
	v_mfma_f32_16x16x32_bf16 v[34:37], v[180:183], v[196:199], v[34:37]
	v_mfma_f32_16x16x32_bf16 v[26:29], v[172:175], v[204:207], v[26:29]
	v_mfma_f32_16x16x32_bf16 v[18:21], v[180:183], v[204:207], v[18:21]
	v_mfma_f32_16x16x32_bf16 v[10:13], v[172:175], v[212:215], v[10:13]
	v_mfma_f32_16x16x32_bf16 v[2:5], v[180:183], v[212:215], v[2:5]
	v_mfma_f32_16x16x32_bf16 v[58:61], v[176:179], v[192:195], v[58:61]
	v_mfma_f32_16x16x32_bf16 v[50:53], v[184:187], v[192:195], v[50:53]
	v_mfma_f32_16x16x32_bf16 v[42:45], v[176:179], v[200:203], v[42:45]
	v_mfma_f32_16x16x32_bf16 v[34:37], v[184:187], v[200:203], v[34:37]
	v_mfma_f32_16x16x32_bf16 v[26:29], v[176:179], v[208:211], v[26:29]
	v_mfma_f32_16x16x32_bf16 v[18:21], v[184:187], v[208:211], v[18:21]
	v_mfma_f32_16x16x32_bf16 v[10:13], v[176:179], v[216:219], v[10:13]
	v_mfma_f32_16x16x32_bf16 v[2:5], v[184:187], v[216:219], v[2:5]
	s_setprio 0
	s_barrier
	s_add_i32 s49, 0, 0x18000
	v_add_u32_e32 v159, s49, v152
	s_add_i32 s50, 0, 0x1c000
	ds_read_b128 v[148:151], v159
	ds_read_b128 v[160:163], v159 offset:1024
	ds_read_b128 v[164:167], v159 offset:2048
	ds_read_b128 v[168:171], v159 offset:3072
	v_add_u32_e32 v159, s50, v152
	ds_read_b128 v[172:175], v159
	ds_read_b128 v[176:179], v159 offset:1024
	ds_read_b128 v[180:183], v159 offset:2048
	ds_read_b128 v[184:187], v159 offset:3072
	s_add_u32 s26, s26, 0x80000
	s_addc_u32 s27, s27, 0
	s_mov_b32 m0, s33
	v_lshl_add_u64 v[230:231], s[26:27], 0, v[138:139]
	ds_read_b128 v[188:191], v156 offset:32768
	ds_read_b128 v[192:195], v156 offset:33792
	ds_read_b128 v[196:199], v156 offset:34816
	ds_read_b128 v[200:203], v156 offset:35840
	ds_read_b128 v[204:207], v156 offset:36864
	ds_read_b128 v[208:211], v156 offset:37888
	ds_read_b128 v[212:215], v156 offset:38912
	ds_read_b128 v[216:219], v156 offset:39936
	global_load_lds_dwordx4 v[230:231], off
	v_lshl_add_u64 v[230:231], s[26:27], 0, v[134:135]
	s_mov_b32 m0, s34
	s_nop 0
	global_load_lds_dwordx4 v[230:231], off
	s_waitcnt vmcnt(8)
	s_waitcnt lgkmcnt(0)
	s_setprio 1
	s_barrier
	v_mfma_f32_16x16x32_bf16 v[126:129], v[148:151], v[188:191], v[126:129]
	v_mfma_f32_16x16x32_bf16 v[118:121], v[164:167], v[188:191], v[118:121]
	v_mfma_f32_16x16x32_bf16 v[110:113], v[148:151], v[196:199], v[110:113]
	v_mfma_f32_16x16x32_bf16 v[102:105], v[164:167], v[196:199], v[102:105]
	v_mfma_f32_16x16x32_bf16 v[94:97], v[148:151], v[204:207], v[94:97]
	v_mfma_f32_16x16x32_bf16 v[86:89], v[164:167], v[204:207], v[86:89]
	v_mfma_f32_16x16x32_bf16 v[78:81], v[148:151], v[212:215], v[78:81]
	v_mfma_f32_16x16x32_bf16 v[70:73], v[164:167], v[212:215], v[70:73]
	v_mfma_f32_16x16x32_bf16 v[126:129], v[160:163], v[192:195], v[126:129]
	v_mfma_f32_16x16x32_bf16 v[118:121], v[168:171], v[192:195], v[118:121]
	v_mfma_f32_16x16x32_bf16 v[110:113], v[160:163], v[200:203], v[110:113]
	v_mfma_f32_16x16x32_bf16 v[102:105], v[168:171], v[200:203], v[102:105]
	v_mfma_f32_16x16x32_bf16 v[94:97], v[160:163], v[208:211], v[94:97]
	v_mfma_f32_16x16x32_bf16 v[86:89], v[168:171], v[208:211], v[86:89]
	v_mfma_f32_16x16x32_bf16 v[78:81], v[160:163], v[216:219], v[78:81]
	v_mfma_f32_16x16x32_bf16 v[70:73], v[168:171], v[216:219], v[70:73]
	s_setprio 0
	s_setprio 1
	v_mfma_f32_16x16x32_bf16 v[122:125], v[172:175], v[188:191], v[122:125]
	v_mfma_f32_16x16x32_bf16 v[114:117], v[180:183], v[188:191], v[114:117]
	v_mfma_f32_16x16x32_bf16 v[106:109], v[172:175], v[196:199], v[106:109]
	v_mfma_f32_16x16x32_bf16 v[98:101], v[180:183], v[196:199], v[98:101]
	v_mfma_f32_16x16x32_bf16 v[90:93], v[172:175], v[204:207], v[90:93]
	v_mfma_f32_16x16x32_bf16 v[82:85], v[180:183], v[204:207], v[82:85]
	v_mfma_f32_16x16x32_bf16 v[74:77], v[172:175], v[212:215], v[74:77]
	v_mfma_f32_16x16x32_bf16 v[66:69], v[180:183], v[212:215], v[66:69]
	v_mfma_f32_16x16x32_bf16 v[122:125], v[176:179], v[192:195], v[122:125]
	v_mfma_f32_16x16x32_bf16 v[114:117], v[184:187], v[192:195], v[114:117]
	v_mfma_f32_16x16x32_bf16 v[106:109], v[176:179], v[200:203], v[106:109]
	v_mfma_f32_16x16x32_bf16 v[98:101], v[184:187], v[200:203], v[98:101]
	v_mfma_f32_16x16x32_bf16 v[90:93], v[176:179], v[208:211], v[90:93]
	v_mfma_f32_16x16x32_bf16 v[82:85], v[184:187], v[208:211], v[82:85]
	v_mfma_f32_16x16x32_bf16 v[74:77], v[176:179], v[216:219], v[74:77]
	v_mfma_f32_16x16x32_bf16 v[66:69], v[184:187], v[216:219], v[66:69]
	s_setprio 0
	s_barrier
; #define PG8_STAGE(bufoff, gbase, voff) do { _Pragma("unroll") for (int _i = 0; _i < 2; ++_i) \
;         __builtin_amdgcn_global_load_lds((const unsigned*)((const char*)(gbase) + (voff)[_i]), (PG8_LAS unsigned*)(lds + (bufoff) + ldsw + _i * 8192), 16, 0, 0); } while (0)
; #define PG8_WAIT_V(n) asm volatile("s_waitcnt vmcnt(" #n ")" ::: "memory")
; #define PG8_WAIT_L(n) asm volatile("s_waitcnt lgkmcnt(" #n ")" ::: "memory")
; #define PG8_BAR __builtin_amdgcn_s_barrier()
; #define PG8_SCHED __builtin_amdgcn_sched_barrier(0)
; template <class Epi, class Sched, bool ALIGN_EPI = true, bool SP2 = true>
; __device__ __forceinline__ void gemm_phase(PG8_LAS unsigned char* lds, const int K  , const Sched& S, const Epi& E) {
;     ...
;             PG8_LDA(At, 1, 1); PG8_STAGE(PG8_SB(1, 0), b3, voffB); PG8_STAGE(PG8_SB(1, 1), b3 + hstep, voffB); PG8_STAGE(PG8_SA(1, 0), a3, voffA);
;             PG8_WAIT_V(8); PG8_WAIT_L(0); PG8_BAR; PG8_MMA(1, 0, At, B0); PG8_MMA(1, 1, At, B1); PG8_BAR; PG8_SCHED;
;     ...
;         if constexpr (ALIGN_EPI) { if (wr == 0) PG8_BAR; }
	s_add_i32 s26, s49, s29
	v_lshl_add_u64 v[220:221], v[220:221], 0, s[4:5]
	s_mov_b32 m0, s26
	ds_read_b128 v[188:191], v156 offset:49152
	ds_read_b128 v[192:195], v156 offset:50176
	ds_read_b128 v[196:199], v156 offset:51200
	ds_read_b128 v[200:203], v156 offset:52224
	ds_read_b128 v[204:207], v156 offset:53248
	ds_read_b128 v[208:211], v156 offset:54272
	ds_read_b128 v[212:215], v156 offset:55296
	ds_read_b128 v[216:219], v156 offset:56320
	global_load_lds_dwordx4 v[220:221], off
	s_add_i32 m0, s26, 0x2000
	s_add_u32 s24, s24, 0x80080
	v_lshl_add_u64 v[220:221], v[222:223], 0, s[4:5]
	s_addc_u32 s25, s25, 0
	s_add_i32 s26, s50, s29
	global_load_lds_dwordx4 v[220:221], off
	v_lshl_add_u64 v[220:221], s[24:25], 0, v[136:137]
	s_mov_b32 m0, s26
	s_nop 0
	global_load_lds_dwordx4 v[220:221], off
	v_lshl_add_u64 v[220:221], s[24:25], 0, v[132:133]
	s_add_i32 m0, s26, 0x2000
	s_nop 0
	global_load_lds_dwordx4 v[220:221], off
	v_lshl_add_u64 v[220:221], v[224:225], 0, s[4:5]
	s_mov_b32 m0, s36
	s_nop 0
	global_load_lds_dwordx4 v[220:221], off
	v_lshl_add_u64 v[220:221], v[226:227], 0, s[4:5]
	s_mov_b32 m0, s37
	s_nop 0
	global_load_lds_dwordx4 v[220:221], off
	s_waitcnt vmcnt(8)
	s_waitcnt lgkmcnt(0)
	s_setprio 1
	s_barrier
	v_mfma_f32_16x16x32_bf16 v[62:65], v[148:151], v[188:191], v[62:65]
	v_mfma_f32_16x16x32_bf16 v[54:57], v[164:167], v[188:191], v[54:57]
	v_mfma_f32_16x16x32_bf16 v[46:49], v[148:151], v[196:199], v[46:49]
	v_mfma_f32_16x16x32_bf16 v[38:41], v[164:167], v[196:199], v[38:41]
	v_mfma_f32_16x16x32_bf16 v[30:33], v[148:151], v[204:207], v[30:33]
	v_mfma_f32_16x16x32_bf16 v[22:25], v[164:167], v[204:207], v[22:25]
	v_mfma_f32_16x16x32_bf16 v[14:17], v[148:151], v[212:215], v[14:17]
	v_mfma_f32_16x16x32_bf16 v[6:9], v[164:167], v[212:215], v[6:9]
	v_mfma_f32_16x16x32_bf16 v[62:65], v[160:163], v[192:195], v[62:65]
	v_mfma_f32_16x16x32_bf16 v[54:57], v[168:171], v[192:195], v[54:57]
	v_mfma_f32_16x16x32_bf16 v[46:49], v[160:163], v[200:203], v[46:49]
	v_mfma_f32_16x16x32_bf16 v[38:41], v[168:171], v[200:203], v[38:41]
	v_mfma_f32_16x16x32_bf16 v[30:33], v[160:163], v[208:211], v[30:33]
	v_mfma_f32_16x16x32_bf16 v[22:25], v[168:171], v[208:211], v[22:25]
	v_mfma_f32_16x16x32_bf16 v[14:17], v[160:163], v[216:219], v[14:17]
	v_mfma_f32_16x16x32_bf16 v[6:9], v[168:171], v[216:219], v[6:9]
	s_setprio 0
	s_setprio 1
	v_mfma_f32_16x16x32_bf16 v[58:61], v[172:175], v[188:191], v[58:61]
	v_mfma_f32_16x16x32_bf16 v[50:53], v[180:183], v[188:191], v[50:53]
	v_mfma_f32_16x16x32_bf16 v[42:45], v[172:175], v[196:199], v[42:45]
	v_mfma_f32_16x16x32_bf16 v[34:37], v[180:183], v[196:199], v[34:37]
	v_mfma_f32_16x16x32_bf16 v[26:29], v[172:175], v[204:207], v[26:29]
	v_mfma_f32_16x16x32_bf16 v[18:21], v[180:183], v[204:207], v[18:21]
	v_mfma_f32_16x16x32_bf16 v[10:13], v[172:175], v[212:215], v[10:13]
	v_mfma_f32_16x16x32_bf16 v[2:5], v[180:183], v[212:215], v[2:5]
	v_mfma_f32_16x16x32_bf16 v[58:61], v[176:179], v[192:195], v[58:61]
	v_mfma_f32_16x16x32_bf16 v[50:53], v[184:187], v[192:195], v[50:53]
	v_mfma_f32_16x16x32_bf16 v[42:45], v[176:179], v[200:203], v[42:45]
	v_mfma_f32_16x16x32_bf16 v[34:37], v[184:187], v[200:203], v[34:37]
	v_mfma_f32_16x16x32_bf16 v[26:29], v[176:179], v[208:211], v[26:29]
	v_mfma_f32_16x16x32_bf16 v[18:21], v[184:187], v[208:211], v[18:21]
	v_mfma_f32_16x16x32_bf16 v[10:13], v[176:179], v[216:219], v[10:13]
	v_mfma_f32_16x16x32_bf16 v[2:5], v[184:187], v[216:219], v[2:5]
	s_setprio 0
	s_barrier
	s_add_i32 s48, s48, 2
	s_add_u32 s22, s22, 0x100
	s_addc_u32 s23, s23, 0
	s_add_u32 s46, s46, 0x100
	s_addc_u32 s47, s47, 0
	s_cmp_gt_u32 s48, 29
	s_cbranch_scc0 .LBB0_1099
	s_and_b64 vcc, exec, s[8:9]
	s_cbranch_vccz .LBB0_1102
	s_barrier

; #define PG8_STAGE(bufoff, gbase, voff) do { _Pragma("unroll") for (int _i = 0; _i < 2; ++_i) \
;         __builtin_amdgcn_global_load_lds((const unsigned*)((const char*)(gbase) + (voff)[_i]), (PG8_LAS unsigned*)(lds + (bufoff) + ldsw + _i * 8192), 16, 0, 0); } while (0)
; #define PG8_WAIT_V(n) asm volatile("s_waitcnt vmcnt(" #n ")" ::: "memory")
; #define PG8_WAIT_L(n) asm volatile("s_waitcnt lgkmcnt(" #n ")" ::: "memory")
; #define PG8_BAR __builtin_amdgcn_s_barrier()
; #define PG8_SCHED __builtin_amdgcn_sched_barrier(0)
; template <class Epi, class Sched, bool ALIGN_EPI = true, bool SP2 = true>
; __device__ __forceinline__ void gemm_phase(PG8_LAS unsigned char* lds, const int K  , const Sched& S, const Epi& E) {
;     ...
;             PG8_LDB(B0, 0, 0); PG8_LDB(B1, 0, 1); PG8_SCHED; PG8_LDA(At, 0, 0); PG8_STAGE(PG8_SA(1, 1), a1 + hstep, voffA);
;             PG8_WAIT_V(8); PG8_WAIT_L(0); PG8_BAR; PG8_MMA(0, 0, At, B0); PG8_MMA(0, 1, At, B1); PG8_BAR; PG8_SCHED;
;             PG8_LDA(At, 0, 1); PG8_STAGE(PG8_SB(0, 0), b2, voffB); PG8_STAGE(PG8_SB(0, 1), b2 + hstep, voffB); PG8_STAGE(PG8_SA(0, 0), a2, voffA);
;             PG8_WAIT_V(8); PG8_WAIT_L(0); PG8_BAR; PG8_MMA(1, 0, At, B0); PG8_MMA(1, 1, At, B1); PG8_BAR; PG8_SCHED;
.LBB0_1304:
	ds_read_b128 v[18:21], v233
	ds_read_b128 v[22:25], v233 offset:1024
	ds_read_b128 v[26:29], v233 offset:2048
	ds_read_b128 v[30:33], v233 offset:3072
	ds_read_b128 v[2:5], v234
	ds_read_b128 v[6:9], v234 offset:1024
	ds_read_b128 v[10:13], v234 offset:2048
	ds_read_b128 v[14:17], v234 offset:3072
	s_add_i32 s74, s22, 2
	s_add_u32 s20, s18, 0xfff50080
	s_addc_u32 s21, s19, -1
	s_cmp_eq_u32 s71, s22
	s_cselect_b32 s22, s14, s20
	s_cselect_b32 s23, s15, s21
	s_cselect_b32 s21, s17, s73
	s_cselect_b32 s20, s16, s72
	v_lshl_add_u64 v[186:187], s[18:19], 0, v[198:199]
	s_add_i32 m0, s26, 0xc000
	ds_read_b128 v[162:165], v235
	ds_read_b128 v[166:169], v235 offset:1024
	ds_read_b128 v[170:173], v235 offset:2048
	ds_read_b128 v[174:177], v235 offset:3072
	ds_read_b128 v[178:181], v235 offset:4096
	ds_read_b128 v[182:185], v235 offset:5120
	ds_read_b128 v[206:209], v235 offset:6144
	ds_read_b128 v[210:213], v235 offset:7168
	global_load_lds_dwordx4 v[186:187], off
	v_lshl_add_u64 v[186:187], s[18:19], 0, v[200:201]
	s_add_i32 m0, s26, 0xe000
	s_nop 0
	global_load_lds_dwordx4 v[186:187], off
	s_waitcnt vmcnt(8)
	s_waitcnt lgkmcnt(0)
	s_setprio 1
	s_barrier
	v_mfma_scale_f32_16x16x128_f8f6f4 v[158:161], v[18:25], v[162:169], v[158:161], v229, v229 op_sel_hi:[0,0,0]
	v_mfma_scale_f32_16x16x128_f8f6f4 v[154:157], v[26:33], v[162:169], v[154:157], v229, v229 op_sel_hi:[0,0,0]
	v_mfma_scale_f32_16x16x128_f8f6f4 v[150:153], v[18:25], v[170:177], v[150:153], v229, v229 op_sel_hi:[0,0,0]
	v_mfma_scale_f32_16x16x128_f8f6f4 v[142:145], v[26:33], v[170:177], v[142:145], v229, v229 op_sel_hi:[0,0,0]
	v_mfma_scale_f32_16x16x128_f8f6f4 v[134:137], v[18:25], v[178:185], v[134:137], v229, v229 op_sel_hi:[0,0,0]
	v_mfma_scale_f32_16x16x128_f8f6f4 v[126:129], v[26:33], v[178:185], v[126:129], v229, v229 op_sel_hi:[0,0,0]
	v_mfma_scale_f32_16x16x128_f8f6f4 v[118:121], v[18:25], v[206:213], v[118:121], v229, v229 op_sel_hi:[0,0,0]
	v_mfma_scale_f32_16x16x128_f8f6f4 v[110:113], v[26:33], v[206:213], v[110:113], v229, v229 op_sel_hi:[0,0,0]
	s_setprio 0
	s_setprio 1
	v_mfma_scale_f32_16x16x128_f8f6f4 v[146:149], v[2:9], v[162:169], v[146:149], v229, v229 op_sel_hi:[0,0,0]
	v_mfma_scale_f32_16x16x128_f8f6f4 v[138:141], v[10:17], v[162:169], v[138:141], v229, v229 op_sel_hi:[0,0,0]
	v_mfma_scale_f32_16x16x128_f8f6f4 v[130:133], v[2:9], v[170:177], v[130:133], v229, v229 op_sel_hi:[0,0,0]
	v_mfma_scale_f32_16x16x128_f8f6f4 v[122:125], v[10:17], v[170:177], v[122:125], v229, v229 op_sel_hi:[0,0,0]
	v_mfma_scale_f32_16x16x128_f8f6f4 v[114:117], v[2:9], v[178:185], v[114:117], v229, v229 op_sel_hi:[0,0,0]
	v_mfma_scale_f32_16x16x128_f8f6f4 v[106:109], v[10:17], v[178:185], v[106:109], v229, v229 op_sel_hi:[0,0,0]
	v_mfma_scale_f32_16x16x128_f8f6f4 v[102:105], v[2:9], v[206:213], v[102:105], v229, v229 op_sel_hi:[0,0,0]
	v_mfma_scale_f32_16x16x128_f8f6f4 v[98:101], v[10:17], v[206:213], v[98:101], v229, v229 op_sel_hi:[0,0,0]
	s_setprio 0
	s_barrier
	s_add_i32 s75, s40, s25
	v_lshl_add_u64 v[162:163], s[20:21], 0, v[192:193]
	s_mov_b32 m0, s75
	ds_read_b128 v[170:173], v235 offset:16384
	ds_read_b128 v[174:177], v235 offset:17408
	ds_read_b128 v[178:181], v235 offset:18432
	ds_read_b128 v[182:185], v235 offset:19456
	ds_read_b128 v[206:209], v235 offset:20480
	ds_read_b128 v[210:213], v235 offset:21504
	ds_read_b128 v[214:217], v235 offset:22528
	ds_read_b128 v[218:221], v235 offset:23552
	global_load_lds_dwordx4 v[162:163], off
	s_add_i32 m0, s75, 0x2000
	s_add_u32 s76, s20, 0xb0000
	v_lshl_add_u64 v[164:165], s[20:21], 0, v[196:197]
	s_addc_u32 s77, s21, 0
	s_add_i32 s75, s41, s25
	global_load_lds_dwordx4 v[164:165], off
	v_lshl_add_u64 v[166:167], s[76:77], 0, v[192:193]
	s_mov_b32 m0, s75
	v_lshl_add_u64 v[168:169], s[22:23], 0, v[194:195]
	global_load_lds_dwordx4 v[166:167], off
	v_lshl_add_u64 v[166:167], s[76:77], 0, v[196:197]
	s_add_i32 m0, s75, 0x2000
	s_nop 0
	global_load_lds_dwordx4 v[166:167], off
	v_lshl_add_u64 v[166:167], s[22:23], 0, v[190:191]
	s_mov_b32 m0, s26
	s_nop 0
	global_load_lds_dwordx4 v[166:167], off
	s_mov_b32 m0, s27
	s_nop 0
	global_load_lds_dwordx4 v[168:169], off
	s_waitcnt vmcnt(8)
	s_waitcnt lgkmcnt(0)
	s_setprio 1
	s_barrier
	v_mfma_scale_f32_16x16x128_f8f6f4 v[94:97], v[18:25], v[170:177], v[94:97], v229, v229 op_sel_hi:[0,0,0]
	v_mfma_scale_f32_16x16x128_f8f6f4 v[90:93], v[26:33], v[170:177], v[90:93], v229, v229 op_sel_hi:[0,0,0]
	v_mfma_scale_f32_16x16x128_f8f6f4 v[86:89], v[18:25], v[178:185], v[86:89], v229, v229 op_sel_hi:[0,0,0]
	v_mfma_scale_f32_16x16x128_f8f6f4 v[78:81], v[26:33], v[178:185], v[78:81], v229, v229 op_sel_hi:[0,0,0]
	v_mfma_scale_f32_16x16x128_f8f6f4 v[70:73], v[18:25], v[206:213], v[70:73], v229, v229 op_sel_hi:[0,0,0]
	v_mfma_scale_f32_16x16x128_f8f6f4 v[62:65], v[26:33], v[206:213], v[62:65], v229, v229 op_sel_hi:[0,0,0]
	v_mfma_scale_f32_16x16x128_f8f6f4 v[54:57], v[18:25], v[214:221], v[54:57], v229, v229 op_sel_hi:[0,0,0]
	v_mfma_scale_f32_16x16x128_f8f6f4 v[46:49], v[26:33], v[214:221], v[46:49], v229, v229 op_sel_hi:[0,0,0]
	s_setprio 0
	s_setprio 1
	v_mfma_scale_f32_16x16x128_f8f6f4 v[82:85], v[2:9], v[170:177], v[82:85], v229, v229 op_sel_hi:[0,0,0]
	v_mfma_scale_f32_16x16x128_f8f6f4 v[74:77], v[10:17], v[170:177], v[74:77], v229, v229 op_sel_hi:[0,0,0]
	v_mfma_scale_f32_16x16x128_f8f6f4 v[66:69], v[2:9], v[178:185], v[66:69], v229, v229 op_sel_hi:[0,0,0]
	v_mfma_scale_f32_16x16x128_f8f6f4 v[58:61], v[10:17], v[178:185], v[58:61], v229, v229 op_sel_hi:[0,0,0]
	v_mfma_scale_f32_16x16x128_f8f6f4 v[50:53], v[2:9], v[206:213], v[50:53], v229, v229 op_sel_hi:[0,0,0]
	v_mfma_scale_f32_16x16x128_f8f6f4 v[42:45], v[10:17], v[206:213], v[42:45], v229, v229 op_sel_hi:[0,0,0]
	v_mfma_scale_f32_16x16x128_f8f6f4 v[38:41], v[2:9], v[214:221], v[38:41], v229, v229 op_sel_hi:[0,0,0]
	v_mfma_scale_f32_16x16x128_f8f6f4 v[34:37], v[10:17], v[214:221], v[34:37], v229, v229 op_sel_hi:[0,0,0]
	s_setprio 0
	s_barrier
; #define PG8_STAGE(bufoff, gbase, voff) do { _Pragma("unroll") for (int _i = 0; _i < 2; ++_i) \
;         __builtin_amdgcn_global_load_lds((const unsigned*)((const char*)(gbase) + (voff)[_i]), (PG8_LAS unsigned*)(lds + (bufoff) + ldsw + _i * 8192), 16, 0, 0); } while (0)
; #define PG8_WAIT_V(n) asm volatile("s_waitcnt vmcnt(" #n ")" ::: "memory")
; #define PG8_WAIT_L(n) asm volatile("s_waitcnt lgkmcnt(" #n ")" ::: "memory")
; #define PG8_BAR __builtin_amdgcn_s_barrier()
; #define PG8_SCHED __builtin_amdgcn_sched_barrier(0)
; template <class Epi, class Sched, bool ALIGN_EPI = true, bool SP2 = true>
; __device__ __forceinline__ void gemm_phase(PG8_LAS unsigned char* lds, const int K  , const Sched& S, const Epi& E) {
;     ...
;             PG8_LDB(B0, 1, 0); PG8_LDB(B1, 1, 1); PG8_SCHED; PG8_LDA(At, 1, 0); PG8_STAGE(PG8_SA(0, 1), a2 + hstep, voffA);
;             PG8_WAIT_V(8); PG8_WAIT_L(0); PG8_BAR; PG8_MMA(0, 0, At, B0); PG8_MMA(0, 1, At, B1); PG8_BAR; PG8_SCHED;
;             PG8_LDA(At, 1, 1); PG8_STAGE(PG8_SB(1, 0), b3, voffB); PG8_STAGE(PG8_SB(1, 1), b3 + hstep, voffB); PG8_STAGE(PG8_SA(1, 0), a3, voffA);
;             PG8_WAIT_V(8); PG8_WAIT_L(0); PG8_BAR; PG8_MMA(1, 0, At, B0); PG8_MMA(1, 1, At, B1); PG8_BAR; PG8_SCHED;
;     ...
;         if constexpr (Epi::FP8) asm volatile("s_nop 15\n\ts_nop 15\n\ts_nop 15\n\ts_nop 15\n\ts_nop 15" ::: "memory");
;         if constexpr (ALIGN_EPI) { if (wr == 0) PG8_BAR; }
	s_add_i32 s75, 0, 0x18000
	s_add_i32 s76, 0, 0x1c000
	v_add_u32_e32 v14, s75, v231
	v_add_u32_e32 v30, s76, v231
	ds_read_b128 v[2:5], v14
	ds_read_b128 v[6:9], v14 offset:1024
	ds_read_b128 v[10:13], v14 offset:2048
	ds_read_b128 v[14:17], v14 offset:3072
	ds_read_b128 v[18:21], v30
	ds_read_b128 v[22:25], v30 offset:1024
	ds_read_b128 v[26:29], v30 offset:2048
	ds_read_b128 v[30:33], v30 offset:3072
	s_add_u32 s22, s22, 0xb0000
	s_addc_u32 s23, s23, 0
	s_mov_b32 m0, s28
	v_lshl_add_u64 v[186:187], s[22:23], 0, v[190:191]
	ds_read_b128 v[170:173], v235 offset:32768
	ds_read_b128 v[174:177], v235 offset:33792
	ds_read_b128 v[178:181], v235 offset:34816
	ds_read_b128 v[182:185], v235 offset:35840
	ds_read_b128 v[206:209], v235 offset:36864
	ds_read_b128 v[210:213], v235 offset:37888
	ds_read_b128 v[214:217], v235 offset:38912
	ds_read_b128 v[218:221], v235 offset:39936
	global_load_lds_dwordx4 v[186:187], off
	v_lshl_add_u64 v[186:187], s[22:23], 0, v[194:195]
	s_mov_b32 m0, s29
	s_nop 0
	global_load_lds_dwordx4 v[186:187], off
	s_waitcnt vmcnt(8)
	s_waitcnt lgkmcnt(0)
	s_setprio 1
	s_barrier
	v_mfma_scale_f32_16x16x128_f8f6f4 v[158:161], v[2:9], v[170:177], v[158:161], v229, v229 op_sel_hi:[0,0,0]
	v_mfma_scale_f32_16x16x128_f8f6f4 v[154:157], v[10:17], v[170:177], v[154:157], v229, v229 op_sel_hi:[0,0,0]
	v_mfma_scale_f32_16x16x128_f8f6f4 v[150:153], v[2:9], v[178:185], v[150:153], v229, v229 op_sel_hi:[0,0,0]
	v_mfma_scale_f32_16x16x128_f8f6f4 v[142:145], v[10:17], v[178:185], v[142:145], v229, v229 op_sel_hi:[0,0,0]
	v_mfma_scale_f32_16x16x128_f8f6f4 v[134:137], v[2:9], v[206:213], v[134:137], v229, v229 op_sel_hi:[0,0,0]
	v_mfma_scale_f32_16x16x128_f8f6f4 v[126:129], v[10:17], v[206:213], v[126:129], v229, v229 op_sel_hi:[0,0,0]
	v_mfma_scale_f32_16x16x128_f8f6f4 v[118:121], v[2:9], v[214:221], v[118:121], v229, v229 op_sel_hi:[0,0,0]
	v_mfma_scale_f32_16x16x128_f8f6f4 v[110:113], v[10:17], v[214:221], v[110:113], v229, v229 op_sel_hi:[0,0,0]
	s_setprio 0
	s_setprio 1
	v_mfma_scale_f32_16x16x128_f8f6f4 v[146:149], v[18:25], v[170:177], v[146:149], v229, v229 op_sel_hi:[0,0,0]
	v_mfma_scale_f32_16x16x128_f8f6f4 v[138:141], v[26:33], v[170:177], v[138:141], v229, v229 op_sel_hi:[0,0,0]
	v_mfma_scale_f32_16x16x128_f8f6f4 v[130:133], v[18:25], v[178:185], v[130:133], v229, v229 op_sel_hi:[0,0,0]
	v_mfma_scale_f32_16x16x128_f8f6f4 v[122:125], v[26:33], v[178:185], v[122:125], v229, v229 op_sel_hi:[0,0,0]
	v_mfma_scale_f32_16x16x128_f8f6f4 v[114:117], v[18:25], v[206:213], v[114:117], v229, v229 op_sel_hi:[0,0,0]
	v_mfma_scale_f32_16x16x128_f8f6f4 v[106:109], v[26:33], v[206:213], v[106:109], v229, v229 op_sel_hi:[0,0,0]
	v_mfma_scale_f32_16x16x128_f8f6f4 v[102:105], v[18:25], v[214:221], v[102:105], v229, v229 op_sel_hi:[0,0,0]
	v_mfma_scale_f32_16x16x128_f8f6f4 v[98:101], v[26:33], v[214:221], v[98:101], v229, v229 op_sel_hi:[0,0,0]
	s_setprio 0
	s_barrier
	s_add_i32 s22, s75, s25
	v_lshl_add_u64 v[162:163], v[162:163], 0, s[8:9]
	s_mov_b32 m0, s22
	ds_read_b128 v[170:173], v235 offset:49152
	ds_read_b128 v[174:177], v235 offset:50176
	ds_read_b128 v[178:181], v235 offset:51200
	ds_read_b128 v[182:185], v235 offset:52224
	ds_read_b128 v[206:209], v235 offset:53248
	ds_read_b128 v[210:213], v235 offset:54272
	ds_read_b128 v[214:217], v235 offset:55296
	ds_read_b128 v[218:221], v235 offset:56320
	global_load_lds_dwordx4 v[162:163], off
	s_add_i32 m0, s22, 0x2000
	s_add_u32 s20, s20, 0xb0080
	v_lshl_add_u64 v[162:163], v[164:165], 0, s[8:9]
	s_addc_u32 s21, s21, 0
	s_add_i32 s22, s76, s25
	global_load_lds_dwordx4 v[162:163], off
	v_lshl_add_u64 v[162:163], s[20:21], 0, v[192:193]
	s_mov_b32 m0, s22
	s_nop 0
	global_load_lds_dwordx4 v[162:163], off
	v_lshl_add_u64 v[162:163], s[20:21], 0, v[196:197]
	s_add_i32 m0, s22, 0x2000
	s_nop 0
	global_load_lds_dwordx4 v[162:163], off
	v_lshl_add_u64 v[162:163], v[166:167], 0, s[8:9]
	s_mov_b32 m0, s36
	s_nop 0
	global_load_lds_dwordx4 v[162:163], off
	v_lshl_add_u64 v[162:163], v[168:169], 0, s[8:9]
	s_mov_b32 m0, s37
	s_nop 0
	global_load_lds_dwordx4 v[162:163], off
	s_waitcnt vmcnt(8)
	s_waitcnt lgkmcnt(0)
	s_setprio 1
	s_barrier
	v_mfma_scale_f32_16x16x128_f8f6f4 v[94:97], v[2:9], v[170:177], v[94:97], v229, v229 op_sel_hi:[0,0,0]
	v_mfma_scale_f32_16x16x128_f8f6f4 v[90:93], v[10:17], v[170:177], v[90:93], v229, v229 op_sel_hi:[0,0,0]
	v_mfma_scale_f32_16x16x128_f8f6f4 v[86:89], v[2:9], v[178:185], v[86:89], v229, v229 op_sel_hi:[0,0,0]
	v_mfma_scale_f32_16x16x128_f8f6f4 v[78:81], v[10:17], v[178:185], v[78:81], v229, v229 op_sel_hi:[0,0,0]
	v_mfma_scale_f32_16x16x128_f8f6f4 v[70:73], v[2:9], v[206:213], v[70:73], v229, v229 op_sel_hi:[0,0,0]
	v_mfma_scale_f32_16x16x128_f8f6f4 v[62:65], v[10:17], v[206:213], v[62:65], v229, v229 op_sel_hi:[0,0,0]
	v_mfma_scale_f32_16x16x128_f8f6f4 v[54:57], v[2:9], v[214:221], v[54:57], v229, v229 op_sel_hi:[0,0,0]
	v_mfma_scale_f32_16x16x128_f8f6f4 v[46:49], v[10:17], v[214:221], v[46:49], v229, v229 op_sel_hi:[0,0,0]
	s_setprio 0
	s_setprio 1
	v_mfma_scale_f32_16x16x128_f8f6f4 v[82:85], v[18:25], v[170:177], v[82:85], v229, v229 op_sel_hi:[0,0,0]
	v_mfma_scale_f32_16x16x128_f8f6f4 v[74:77], v[26:33], v[170:177], v[74:77], v229, v229 op_sel_hi:[0,0,0]
	v_mfma_scale_f32_16x16x128_f8f6f4 v[66:69], v[18:25], v[178:185], v[66:69], v229, v229 op_sel_hi:[0,0,0]
	v_mfma_scale_f32_16x16x128_f8f6f4 v[58:61], v[26:33], v[178:185], v[58:61], v229, v229 op_sel_hi:[0,0,0]
	v_mfma_scale_f32_16x16x128_f8f6f4 v[50:53], v[18:25], v[206:213], v[50:53], v229, v229 op_sel_hi:[0,0,0]
	v_mfma_scale_f32_16x16x128_f8f6f4 v[42:45], v[26:33], v[206:213], v[42:45], v229, v229 op_sel_hi:[0,0,0]
	v_mfma_scale_f32_16x16x128_f8f6f4 v[38:41], v[18:25], v[214:221], v[38:41], v229, v229 op_sel_hi:[0,0,0]
	v_mfma_scale_f32_16x16x128_f8f6f4 v[34:37], v[26:33], v[214:221], v[34:37], v229, v229 op_sel_hi:[0,0,0]
	s_setprio 0
	s_barrier
	s_add_u32 s18, s18, 0x100
	s_addc_u32 s19, s19, 0
	s_add_u32 s72, s72, 0x100
	s_addc_u32 s73, s73, 0
	s_cmp_ge_u32 s74, s4
	s_mov_b32 s22, s74
	s_cbranch_scc0 .LBB0_1304
	s_nop 15
	s_nop 15
	s_nop 15
	s_nop 15
	s_nop 15
	s_and_b64 vcc, exec, s[10:11]
	s_cbranch_vccz .LBB0_1307
	s_barrier

; #define PG8_STAGE(bufoff, gbase, voff) do { _Pragma("unroll") for (int _i = 0; _i < 2; ++_i) \
;         __builtin_amdgcn_global_load_lds((const unsigned*)((const char*)(gbase) + (voff)[_i]), (PG8_LAS unsigned*)(lds + (bufoff) + ldsw + _i * 8192), 16, 0, 0); } while (0)
; #define PG8_WAIT_V(n) asm volatile("s_waitcnt vmcnt(" #n ")" ::: "memory")
; #define PG8_WAIT_L(n) asm volatile("s_waitcnt lgkmcnt(" #n ")" ::: "memory")
; #define PG8_BAR __builtin_amdgcn_s_barrier()
; #define PG8_SCHED __builtin_amdgcn_sched_barrier(0)
; template <class Epi, class Sched, bool ALIGN_EPI = true, bool SP2 = true>
; __device__ __forceinline__ void gemm_phase(PG8_LAS unsigned char* lds, const int K  , const Sched& S, const Epi& E) {
;     ...
;             PG8_LDB(B0, 0, 0); PG8_LDB(B1, 0, 1); PG8_SCHED; PG8_LDA(At, 0, 0); PG8_STAGE(PG8_SA(1, 1), a1 + hstep, voffA);
;             PG8_WAIT_V(8); PG8_WAIT_L(0); PG8_BAR; PG8_MMA(0, 0, At, B0); PG8_MMA(0, 1, At, B1); PG8_BAR; PG8_SCHED;
;             PG8_LDA(At, 0, 1); PG8_STAGE(PG8_SB(0, 0), b2, voffB); PG8_STAGE(PG8_SB(0, 1), b2 + hstep, voffB); PG8_STAGE(PG8_SA(0, 0), a2, voffA);
.LBB0_1448:
	ds_read_b128 v[148:151], v154
	ds_read_b128 v[160:163], v154 offset:1024
	ds_read_b128 v[164:167], v154 offset:2048
	ds_read_b128 v[168:171], v154 offset:3072
	ds_read_b128 v[172:175], v155
	ds_read_b128 v[176:179], v155 offset:1024
	ds_read_b128 v[180:183], v155 offset:2048
	ds_read_b128 v[184:187], v155 offset:3072
	s_add_u32 s26, s24, 0xfff80080
	s_addc_u32 s27, s25, -1
	s_cmp_eq_u32 s50, 28
	s_cselect_b32 s29, s17, s27
	s_cselect_b32 s28, s46, s26
	s_cselect_b32 s27, s11, s49
	s_cselect_b32 s26, s47, s48
	v_lshl_add_u64 v[220:221], s[24:25], 0, v[140:141]
	s_add_i32 m0, s23, 0xc000
	ds_read_b128 v[188:191], v156
	ds_read_b128 v[192:195], v156 offset:1024
	ds_read_b128 v[196:199], v156 offset:2048
	ds_read_b128 v[200:203], v156 offset:3072
	ds_read_b128 v[204:207], v156 offset:4096
	ds_read_b128 v[208:211], v156 offset:5120
	ds_read_b128 v[212:215], v156 offset:6144
	ds_read_b128 v[216:219], v156 offset:7168
	global_load_lds_dwordx4 v[220:221], off
	v_lshl_add_u64 v[220:221], s[24:25], 0, v[142:143]
	s_add_i32 m0, s23, 0xe000
	s_nop 0
	global_load_lds_dwordx4 v[220:221], off
	s_waitcnt vmcnt(8)
	s_waitcnt lgkmcnt(0)
	s_setprio 1
	s_barrier
	v_mfma_f32_16x16x32_bf16 v[126:129], v[148:151], v[188:191], v[126:129]
	v_mfma_f32_16x16x32_bf16 v[118:121], v[164:167], v[188:191], v[118:121]
	v_mfma_f32_16x16x32_bf16 v[110:113], v[148:151], v[196:199], v[110:113]
	v_mfma_f32_16x16x32_bf16 v[102:105], v[164:167], v[196:199], v[102:105]
	v_mfma_f32_16x16x32_bf16 v[94:97], v[148:151], v[204:207], v[94:97]
	v_mfma_f32_16x16x32_bf16 v[86:89], v[164:167], v[204:207], v[86:89]
	v_mfma_f32_16x16x32_bf16 v[78:81], v[148:151], v[212:215], v[78:81]
	v_mfma_f32_16x16x32_bf16 v[70:73], v[164:167], v[212:215], v[70:73]
	v_mfma_f32_16x16x32_bf16 v[126:129], v[160:163], v[192:195], v[126:129]
	v_mfma_f32_16x16x32_bf16 v[118:121], v[168:171], v[192:195], v[118:121]
	v_mfma_f32_16x16x32_bf16 v[110:113], v[160:163], v[200:203], v[110:113]
	v_mfma_f32_16x16x32_bf16 v[102:105], v[168:171], v[200:203], v[102:105]
	v_mfma_f32_16x16x32_bf16 v[94:97], v[160:163], v[208:211], v[94:97]
	v_mfma_f32_16x16x32_bf16 v[86:89], v[168:171], v[208:211], v[86:89]
	v_mfma_f32_16x16x32_bf16 v[78:81], v[160:163], v[216:219], v[78:81]
	v_mfma_f32_16x16x32_bf16 v[70:73], v[168:171], v[216:219], v[70:73]
	s_setprio 0
	s_setprio 1
	v_mfma_f32_16x16x32_bf16 v[122:125], v[172:175], v[188:191], v[122:125]
	v_mfma_f32_16x16x32_bf16 v[114:117], v[180:183], v[188:191], v[114:117]
	v_mfma_f32_16x16x32_bf16 v[106:109], v[172:175], v[196:199], v[106:109]
	v_mfma_f32_16x16x32_bf16 v[98:101], v[180:183], v[196:199], v[98:101]
	v_mfma_f32_16x16x32_bf16 v[90:93], v[172:175], v[204:207], v[90:93]
	v_mfma_f32_16x16x32_bf16 v[82:85], v[180:183], v[204:207], v[82:85]
	v_mfma_f32_16x16x32_bf16 v[74:77], v[172:175], v[212:215], v[74:77]
	v_mfma_f32_16x16x32_bf16 v[66:69], v[180:183], v[212:215], v[66:69]
	v_mfma_f32_16x16x32_bf16 v[122:125], v[176:179], v[192:195], v[122:125]
	v_mfma_f32_16x16x32_bf16 v[114:117], v[184:187], v[192:195], v[114:117]
	v_mfma_f32_16x16x32_bf16 v[106:109], v[176:179], v[200:203], v[106:109]
	v_mfma_f32_16x16x32_bf16 v[98:101], v[184:187], v[200:203], v[98:101]
	v_mfma_f32_16x16x32_bf16 v[90:93], v[176:179], v[208:211], v[90:93]
	v_mfma_f32_16x16x32_bf16 v[82:85], v[184:187], v[208:211], v[82:85]
	v_mfma_f32_16x16x32_bf16 v[74:77], v[176:179], v[216:219], v[74:77]
	v_mfma_f32_16x16x32_bf16 v[66:69], v[184:187], v[216:219], v[66:69]
	s_setprio 0
	s_barrier
	s_add_i32 s51, s41, s31
	v_lshl_add_u64 v[220:221], s[26:27], 0, v[136:137]
	s_mov_b32 m0, s51
	ds_read_b128 v[188:191], v156 offset:16384
	ds_read_b128 v[192:195], v156 offset:17408
	ds_read_b128 v[196:199], v156 offset:18432
	ds_read_b128 v[200:203], v156 offset:19456
	ds_read_b128 v[204:207], v156 offset:20480
	ds_read_b128 v[208:211], v156 offset:21504
	ds_read_b128 v[212:215], v156 offset:22528
	ds_read_b128 v[216:219], v156 offset:23552
	global_load_lds_dwordx4 v[220:221], off
	s_add_i32 m0, s51, 0x2000
	s_add_u32 s68, s26, 0x80000
	v_lshl_add_u64 v[222:223], s[26:27], 0, v[132:133]
	s_addc_u32 s69, s27, 0
	s_add_i32 s51, s42, s31
	global_load_lds_dwordx4 v[222:223], off
	v_lshl_add_u64 v[224:225], s[68:69], 0, v[136:137]
	s_mov_b32 m0, s51
	v_lshl_add_u64 v[226:227], s[28:29], 0, v[134:135]
	global_load_lds_dwordx4 v[224:225], off
	v_lshl_add_u64 v[224:225], s[68:69], 0, v[132:133]
	s_add_i32 m0, s51, 0x2000
	s_nop 0
	global_load_lds_dwordx4 v[224:225], off
	v_lshl_add_u64 v[224:225], s[28:29], 0, v[138:139]
	s_mov_b32 m0, s23
	s_nop 0
	global_load_lds_dwordx4 v[224:225], off
	s_mov_b32 m0, s34
	s_nop 0
	global_load_lds_dwordx4 v[226:227], off
	s_waitcnt vmcnt(8)
	s_waitcnt lgkmcnt(0)
	s_setprio 1
	s_barrier
; #define PG8_STAGE(bufoff, gbase, voff) do { _Pragma("unroll") for (int _i = 0; _i < 2; ++_i) \
;         __builtin_amdgcn_global_load_lds((const unsigned*)((const char*)(gbase) + (voff)[_i]), (PG8_LAS unsigned*)(lds + (bufoff) + ldsw + _i * 8192), 16, 0, 0); } while (0)
; #define PG8_WAIT_V(n) asm volatile("s_waitcnt vmcnt(" #n ")" ::: "memory")
; #define PG8_WAIT_L(n) asm volatile("s_waitcnt lgkmcnt(" #n ")" ::: "memory")
; #define PG8_BAR __builtin_amdgcn_s_barrier()
; #define PG8_SCHED __builtin_amdgcn_sched_barrier(0)
; template <class Epi, class Sched, bool ALIGN_EPI = true, bool SP2 = true>
; __device__ __forceinline__ void gemm_phase(PG8_LAS unsigned char* lds, const int K  , const Sched& S, const Epi& E) {
;     ...
;             PG8_WAIT_V(8); PG8_WAIT_L(0); PG8_BAR; PG8_MMA(1, 0, At, B0); PG8_MMA(1, 1, At, B1); PG8_BAR; PG8_SCHED;
;             PG8_LDB(B0, 1, 0); PG8_LDB(B1, 1, 1); PG8_SCHED; PG8_LDA(At, 1, 0); PG8_STAGE(PG8_SA(0, 1), a2 + hstep, voffA);
;             PG8_WAIT_V(8); PG8_WAIT_L(0); PG8_BAR; PG8_MMA(0, 0, At, B0); PG8_MMA(0, 1, At, B1); PG8_BAR; PG8_SCHED;
	v_mfma_f32_16x16x32_bf16 v[62:65], v[148:151], v[188:191], v[62:65]
	v_mfma_f32_16x16x32_bf16 v[54:57], v[164:167], v[188:191], v[54:57]
	v_mfma_f32_16x16x32_bf16 v[46:49], v[148:151], v[196:199], v[46:49]
	v_mfma_f32_16x16x32_bf16 v[38:41], v[164:167], v[196:199], v[38:41]
	v_mfma_f32_16x16x32_bf16 v[30:33], v[148:151], v[204:207], v[30:33]
	v_mfma_f32_16x16x32_bf16 v[22:25], v[164:167], v[204:207], v[22:25]
	v_mfma_f32_16x16x32_bf16 v[14:17], v[148:151], v[212:215], v[14:17]
	v_mfma_f32_16x16x32_bf16 v[6:9], v[164:167], v[212:215], v[6:9]
	v_mfma_f32_16x16x32_bf16 v[62:65], v[160:163], v[192:195], v[62:65]
	v_mfma_f32_16x16x32_bf16 v[54:57], v[168:171], v[192:195], v[54:57]
	v_mfma_f32_16x16x32_bf16 v[46:49], v[160:163], v[200:203], v[46:49]
	v_mfma_f32_16x16x32_bf16 v[38:41], v[168:171], v[200:203], v[38:41]
	v_mfma_f32_16x16x32_bf16 v[30:33], v[160:163], v[208:211], v[30:33]
	v_mfma_f32_16x16x32_bf16 v[22:25], v[168:171], v[208:211], v[22:25]
	v_mfma_f32_16x16x32_bf16 v[14:17], v[160:163], v[216:219], v[14:17]
	v_mfma_f32_16x16x32_bf16 v[6:9], v[168:171], v[216:219], v[6:9]
	s_setprio 0
	s_setprio 1
	v_mfma_f32_16x16x32_bf16 v[58:61], v[172:175], v[188:191], v[58:61]
	v_mfma_f32_16x16x32_bf16 v[50:53], v[180:183], v[188:191], v[50:53]
	v_mfma_f32_16x16x32_bf16 v[42:45], v[172:175], v[196:199], v[42:45]
	v_mfma_f32_16x16x32_bf16 v[34:37], v[180:183], v[196:199], v[34:37]
	v_mfma_f32_16x16x32_bf16 v[26:29], v[172:175], v[204:207], v[26:29]
	v_mfma_f32_16x16x32_bf16 v[18:21], v[180:183], v[204:207], v[18:21]
	v_mfma_f32_16x16x32_bf16 v[10:13], v[172:175], v[212:215], v[10:13]
	v_mfma_f32_16x16x32_bf16 v[2:5], v[180:183], v[212:215], v[2:5]
	v_mfma_f32_16x16x32_bf16 v[58:61], v[176:179], v[192:195], v[58:61]
	v_mfma_f32_16x16x32_bf16 v[50:53], v[184:187], v[192:195], v[50:53]
	v_mfma_f32_16x16x32_bf16 v[42:45], v[176:179], v[200:203], v[42:45]
	v_mfma_f32_16x16x32_bf16 v[34:37], v[184:187], v[200:203], v[34:37]
	v_mfma_f32_16x16x32_bf16 v[26:29], v[176:179], v[208:211], v[26:29]
	v_mfma_f32_16x16x32_bf16 v[18:21], v[184:187], v[208:211], v[18:21]
	v_mfma_f32_16x16x32_bf16 v[10:13], v[176:179], v[216:219], v[10:13]
	v_mfma_f32_16x16x32_bf16 v[2:5], v[184:187], v[216:219], v[2:5]
	s_setprio 0
	s_barrier
	s_add_i32 s51, 0, 0x18000
	v_add_u32_e32 v159, s51, v152
	s_add_i32 s68, 0, 0x1c000
	ds_read_b128 v[148:151], v159
	ds_read_b128 v[160:163], v159 offset:1024
	ds_read_b128 v[164:167], v159 offset:2048
	ds_read_b128 v[168:171], v159 offset:3072
	v_add_u32_e32 v159, s68, v152
	ds_read_b128 v[172:175], v159
	ds_read_b128 v[176:179], v159 offset:1024
	ds_read_b128 v[180:183], v159 offset:2048
	ds_read_b128 v[184:187], v159 offset:3072
	s_add_u32 s28, s28, 0x80000
	s_addc_u32 s29, s29, 0
	s_mov_b32 m0, s35
	v_lshl_add_u64 v[230:231], s[28:29], 0, v[138:139]
	ds_read_b128 v[188:191], v156 offset:32768
	ds_read_b128 v[192:195], v156 offset:33792
	ds_read_b128 v[196:199], v156 offset:34816
	ds_read_b128 v[200:203], v156 offset:35840
	ds_read_b128 v[204:207], v156 offset:36864
	ds_read_b128 v[208:211], v156 offset:37888
	ds_read_b128 v[212:215], v156 offset:38912
	ds_read_b128 v[216:219], v156 offset:39936
	global_load_lds_dwordx4 v[230:231], off
	v_lshl_add_u64 v[230:231], s[28:29], 0, v[134:135]
	s_mov_b32 m0, s36
	s_nop 0
	global_load_lds_dwordx4 v[230:231], off
	s_waitcnt vmcnt(8)
	s_waitcnt lgkmcnt(0)
	s_setprio 1
	s_barrier
	v_mfma_f32_16x16x32_bf16 v[126:129], v[148:151], v[188:191], v[126:129]
	v_mfma_f32_16x16x32_bf16 v[118:121], v[164:167], v[188:191], v[118:121]
	v_mfma_f32_16x16x32_bf16 v[110:113], v[148:151], v[196:199], v[110:113]
	v_mfma_f32_16x16x32_bf16 v[102:105], v[164:167], v[196:199], v[102:105]
	v_mfma_f32_16x16x32_bf16 v[94:97], v[148:151], v[204:207], v[94:97]
	v_mfma_f32_16x16x32_bf16 v[86:89], v[164:167], v[204:207], v[86:89]
	v_mfma_f32_16x16x32_bf16 v[78:81], v[148:151], v[212:215], v[78:81]
	v_mfma_f32_16x16x32_bf16 v[70:73], v[164:167], v[212:215], v[70:73]
	v_mfma_f32_16x16x32_bf16 v[126:129], v[160:163], v[192:195], v[126:129]
	v_mfma_f32_16x16x32_bf16 v[118:121], v[168:171], v[192:195], v[118:121]
	v_mfma_f32_16x16x32_bf16 v[110:113], v[160:163], v[200:203], v[110:113]
	v_mfma_f32_16x16x32_bf16 v[102:105], v[168:171], v[200:203], v[102:105]
	v_mfma_f32_16x16x32_bf16 v[94:97], v[160:163], v[208:211], v[94:97]
	v_mfma_f32_16x16x32_bf16 v[86:89], v[168:171], v[208:211], v[86:89]
	v_mfma_f32_16x16x32_bf16 v[78:81], v[160:163], v[216:219], v[78:81]
	v_mfma_f32_16x16x32_bf16 v[70:73], v[168:171], v[216:219], v[70:73]
	s_setprio 0
	s_setprio 1
	v_mfma_f32_16x16x32_bf16 v[122:125], v[172:175], v[188:191], v[122:125]
	v_mfma_f32_16x16x32_bf16 v[114:117], v[180:183], v[188:191], v[114:117]
	v_mfma_f32_16x16x32_bf16 v[106:109], v[172:175], v[196:199], v[106:109]
	v_mfma_f32_16x16x32_bf16 v[98:101], v[180:183], v[196:199], v[98:101]
	v_mfma_f32_16x16x32_bf16 v[90:93], v[172:175], v[204:207], v[90:93]
	v_mfma_f32_16x16x32_bf16 v[82:85], v[180:183], v[204:207], v[82:85]
	v_mfma_f32_16x16x32_bf16 v[74:77], v[172:175], v[212:215], v[74:77]
	v_mfma_f32_16x16x32_bf16 v[66:69], v[180:183], v[212:215], v[66:69]
	v_mfma_f32_16x16x32_bf16 v[122:125], v[176:179], v[192:195], v[122:125]
	v_mfma_f32_16x16x32_bf16 v[114:117], v[184:187], v[192:195], v[114:117]
	v_mfma_f32_16x16x32_bf16 v[106:109], v[176:179], v[200:203], v[106:109]
	v_mfma_f32_16x16x32_bf16 v[98:101], v[184:187], v[200:203], v[98:101]
	v_mfma_f32_16x16x32_bf16 v[90:93], v[176:179], v[208:211], v[90:93]
	v_mfma_f32_16x16x32_bf16 v[82:85], v[184:187], v[208:211], v[82:85]
	v_mfma_f32_16x16x32_bf16 v[74:77], v[176:179], v[216:219], v[74:77]
	v_mfma_f32_16x16x32_bf16 v[66:69], v[184:187], v[216:219], v[66:69]
	s_setprio 0
	s_barrier
; #define PG8_STAGE(bufoff, gbase, voff) do { _Pragma("unroll") for (int _i = 0; _i < 2; ++_i) \
;         __builtin_amdgcn_global_load_lds((const unsigned*)((const char*)(gbase) + (voff)[_i]), (PG8_LAS unsigned*)(lds + (bufoff) + ldsw + _i * 8192), 16, 0, 0); } while (0)
; #define PG8_WAIT_V(n) asm volatile("s_waitcnt vmcnt(" #n ")" ::: "memory")
; #define PG8_WAIT_L(n) asm volatile("s_waitcnt lgkmcnt(" #n ")" ::: "memory")
; #define PG8_BAR __builtin_amdgcn_s_barrier()
; #define PG8_SCHED __builtin_amdgcn_sched_barrier(0)
; template <class Epi, class Sched, bool ALIGN_EPI = true, bool SP2 = true>
; __device__ __forceinline__ void gemm_phase(PG8_LAS unsigned char* lds, const int K  , const Sched& S, const Epi& E) {
;     ...
;             PG8_LDA(At, 1, 1); PG8_STAGE(PG8_SB(1, 0), b3, voffB); PG8_STAGE(PG8_SB(1, 1), b3 + hstep, voffB); PG8_STAGE(PG8_SA(1, 0), a3, voffA);
;             PG8_WAIT_V(8); PG8_WAIT_L(0); PG8_BAR; PG8_MMA(1, 0, At, B0); PG8_MMA(1, 1, At, B1); PG8_BAR; PG8_SCHED;
;     ...
;         if constexpr (ALIGN_EPI) { if (wr == 0) PG8_BAR; }
	s_add_i32 s28, s51, s31
	v_lshl_add_u64 v[220:221], v[220:221], 0, s[4:5]
	s_mov_b32 m0, s28
	ds_read_b128 v[188:191], v156 offset:49152
	ds_read_b128 v[192:195], v156 offset:50176
	ds_read_b128 v[196:199], v156 offset:51200
	ds_read_b128 v[200:203], v156 offset:52224
	ds_read_b128 v[204:207], v156 offset:53248
	ds_read_b128 v[208:211], v156 offset:54272
	ds_read_b128 v[212:215], v156 offset:55296
	ds_read_b128 v[216:219], v156 offset:56320
	global_load_lds_dwordx4 v[220:221], off
	s_add_i32 m0, s28, 0x2000
	s_add_u32 s26, s26, 0x80080
	v_lshl_add_u64 v[220:221], v[222:223], 0, s[4:5]
	s_addc_u32 s27, s27, 0
	s_add_i32 s28, s68, s31
	global_load_lds_dwordx4 v[220:221], off
	v_lshl_add_u64 v[220:221], s[26:27], 0, v[136:137]
	s_mov_b32 m0, s28
	s_nop 0
	global_load_lds_dwordx4 v[220:221], off
	v_lshl_add_u64 v[220:221], s[26:27], 0, v[132:133]
	s_add_i32 m0, s28, 0x2000
	s_nop 0
	global_load_lds_dwordx4 v[220:221], off
	v_lshl_add_u64 v[220:221], v[224:225], 0, s[4:5]
	s_mov_b32 m0, s38
	s_nop 0
	global_load_lds_dwordx4 v[220:221], off
	v_lshl_add_u64 v[220:221], v[226:227], 0, s[4:5]
	s_mov_b32 m0, s39
	s_nop 0
	global_load_lds_dwordx4 v[220:221], off
	s_waitcnt vmcnt(8)
	s_waitcnt lgkmcnt(0)
	s_setprio 1
	s_barrier
	v_mfma_f32_16x16x32_bf16 v[62:65], v[148:151], v[188:191], v[62:65]
	v_mfma_f32_16x16x32_bf16 v[54:57], v[164:167], v[188:191], v[54:57]
	v_mfma_f32_16x16x32_bf16 v[46:49], v[148:151], v[196:199], v[46:49]
	v_mfma_f32_16x16x32_bf16 v[38:41], v[164:167], v[196:199], v[38:41]
	v_mfma_f32_16x16x32_bf16 v[30:33], v[148:151], v[204:207], v[30:33]
	v_mfma_f32_16x16x32_bf16 v[22:25], v[164:167], v[204:207], v[22:25]
	v_mfma_f32_16x16x32_bf16 v[14:17], v[148:151], v[212:215], v[14:17]
	v_mfma_f32_16x16x32_bf16 v[6:9], v[164:167], v[212:215], v[6:9]
	v_mfma_f32_16x16x32_bf16 v[62:65], v[160:163], v[192:195], v[62:65]
	v_mfma_f32_16x16x32_bf16 v[54:57], v[168:171], v[192:195], v[54:57]
	v_mfma_f32_16x16x32_bf16 v[46:49], v[160:163], v[200:203], v[46:49]
	v_mfma_f32_16x16x32_bf16 v[38:41], v[168:171], v[200:203], v[38:41]
	v_mfma_f32_16x16x32_bf16 v[30:33], v[160:163], v[208:211], v[30:33]
	v_mfma_f32_16x16x32_bf16 v[22:25], v[168:171], v[208:211], v[22:25]
	v_mfma_f32_16x16x32_bf16 v[14:17], v[160:163], v[216:219], v[14:17]
	v_mfma_f32_16x16x32_bf16 v[6:9], v[168:171], v[216:219], v[6:9]
	s_setprio 0
	s_setprio 1
	v_mfma_f32_16x16x32_bf16 v[58:61], v[172:175], v[188:191], v[58:61]
	v_mfma_f32_16x16x32_bf16 v[50:53], v[180:183], v[188:191], v[50:53]
	v_mfma_f32_16x16x32_bf16 v[42:45], v[172:175], v[196:199], v[42:45]
	v_mfma_f32_16x16x32_bf16 v[34:37], v[180:183], v[196:199], v[34:37]
	v_mfma_f32_16x16x32_bf16 v[26:29], v[172:175], v[204:207], v[26:29]
	v_mfma_f32_16x16x32_bf16 v[18:21], v[180:183], v[204:207], v[18:21]
	v_mfma_f32_16x16x32_bf16 v[10:13], v[172:175], v[212:215], v[10:13]
	v_mfma_f32_16x16x32_bf16 v[2:5], v[180:183], v[212:215], v[2:5]
	v_mfma_f32_16x16x32_bf16 v[58:61], v[176:179], v[192:195], v[58:61]
	v_mfma_f32_16x16x32_bf16 v[50:53], v[184:187], v[192:195], v[50:53]
	v_mfma_f32_16x16x32_bf16 v[42:45], v[176:179], v[200:203], v[42:45]
	v_mfma_f32_16x16x32_bf16 v[34:37], v[184:187], v[200:203], v[34:37]
	v_mfma_f32_16x16x32_bf16 v[26:29], v[176:179], v[208:211], v[26:29]
	v_mfma_f32_16x16x32_bf16 v[18:21], v[184:187], v[208:211], v[18:21]
	v_mfma_f32_16x16x32_bf16 v[10:13], v[176:179], v[216:219], v[10:13]
	v_mfma_f32_16x16x32_bf16 v[2:5], v[184:187], v[216:219], v[2:5]
	s_setprio 0
	s_barrier
	s_add_i32 s50, s50, 2
	s_add_u32 s24, s24, 0x100
	s_addc_u32 s25, s25, 0
	s_add_u32 s48, s48, 0x100
	s_addc_u32 s49, s49, 0
	s_cmp_gt_u32 s50, 29
	s_cbranch_scc0 .LBB0_1448
	s_and_b64 vcc, exec, s[8:9]
	s_cbranch_vccz .LBB0_1451
	s_barrier

; #define PG8_STAGE(bufoff, gbase, voff) do { _Pragma("unroll") for (int _i = 0; _i < 2; ++_i) \
;         __builtin_amdgcn_global_load_lds((const unsigned*)((const char*)(gbase) + (voff)[_i]), (PG8_LAS unsigned*)(lds + (bufoff) + ldsw + _i * 8192), 16, 0, 0); } while (0)
; #define PG8_WAIT_V(n) asm volatile("s_waitcnt vmcnt(" #n ")" ::: "memory")
; #define PG8_WAIT_L(n) asm volatile("s_waitcnt lgkmcnt(" #n ")" ::: "memory")
; #define PG8_BAR __builtin_amdgcn_s_barrier()
; #define PG8_SCHED __builtin_amdgcn_sched_barrier(0)
;     __device__ __forceinline__ int nt(const pg8::Unit& u) const { return u.kind == 0 ? ntiles : q_nt(u.kind - 1); }
; template <class Epi, class Sched, bool ALIGN_EPI = true, bool SP2 = true>
; __device__ __forceinline__ void gemm_phase(PG8_LAS unsigned char* lds, const int K  , const Sched& S, const Epi& E) {
;     ...
;             const bool last = (t == nt - 2);
;             const char* a1 = cA + (size_t)(t + 1) * kstep;
;             const char* a2 = last ? nA : cA + (size_t)(t + 2) * kstep; const char* b2 = last ? nB : cB + (size_t)(t + 2) * kstep;
;             const char* a3 = a2 + kstep; const char* b3 = b2 + kstep;
;             if constexpr (SP2) {
;             PG8_LDB(B0, 0, 0); PG8_LDB(B1, 0, 1); PG8_SCHED; PG8_LDA(At, 0, 0); PG8_STAGE(PG8_SA(1, 1), a1 + hstep, voffA);
;             PG8_WAIT_V(8); PG8_WAIT_L(0); PG8_BAR; PG8_MMA(0, 0, At, B0); PG8_MMA(0, 1, At, B1); PG8_BAR; PG8_SCHED;
;             PG8_LDA(At, 0, 1); PG8_STAGE(PG8_SB(0, 0), b2, voffB); PG8_STAGE(PG8_SB(0, 1), b2 + hstep, voffB); PG8_STAGE(PG8_SA(0, 0), a2, voffA);
;             PG8_WAIT_V(8); PG8_WAIT_L(0); PG8_BAR; PG8_MMA(1, 0, At, B0); PG8_MMA(1, 1, At, B1); PG8_BAR; PG8_SCHED;
.LBB0_1695:
	ds_read_b128 v[18:21], v233
	ds_read_b128 v[22:25], v233 offset:1024
	ds_read_b128 v[26:29], v233 offset:2048
	ds_read_b128 v[30:33], v233 offset:3072
	ds_read_b128 v[2:5], v234
	ds_read_b128 v[6:9], v234 offset:1024
	ds_read_b128 v[10:13], v234 offset:2048
	ds_read_b128 v[14:17], v234 offset:3072
	s_add_i32 s74, s24, 2
	s_add_u32 s22, s20, 0xfff50080
	s_addc_u32 s23, s21, -1
	s_cmp_eq_u32 s71, s24
	s_cselect_b32 s24, s16, s22
	s_cselect_b32 s25, s17, s23
	s_cselect_b32 s23, s19, s73
	s_cselect_b32 s22, s18, s72
	v_lshl_add_u64 v[186:187], s[20:21], 0, v[198:199]
	s_add_i32 m0, s28, 0xc000
	ds_read_b128 v[162:165], v235
	ds_read_b128 v[166:169], v235 offset:1024
	ds_read_b128 v[170:173], v235 offset:2048
	ds_read_b128 v[174:177], v235 offset:3072
	ds_read_b128 v[178:181], v235 offset:4096
	ds_read_b128 v[182:185], v235 offset:5120
	ds_read_b128 v[206:209], v235 offset:6144
	ds_read_b128 v[210:213], v235 offset:7168
	global_load_lds_dwordx4 v[186:187], off
	v_lshl_add_u64 v[186:187], s[20:21], 0, v[200:201]
	s_add_i32 m0, s28, 0xe000
	s_nop 0
	global_load_lds_dwordx4 v[186:187], off
	s_waitcnt vmcnt(8)
	s_waitcnt lgkmcnt(0)
	s_setprio 1
	s_barrier
	v_mfma_scale_f32_16x16x128_f8f6f4 v[158:161], v[18:25], v[162:169], v[158:161], v229, v229 op_sel_hi:[0,0,0]
	v_mfma_scale_f32_16x16x128_f8f6f4 v[154:157], v[26:33], v[162:169], v[154:157], v229, v229 op_sel_hi:[0,0,0]
	v_mfma_scale_f32_16x16x128_f8f6f4 v[150:153], v[18:25], v[170:177], v[150:153], v229, v229 op_sel_hi:[0,0,0]
	v_mfma_scale_f32_16x16x128_f8f6f4 v[142:145], v[26:33], v[170:177], v[142:145], v229, v229 op_sel_hi:[0,0,0]
	v_mfma_scale_f32_16x16x128_f8f6f4 v[134:137], v[18:25], v[178:185], v[134:137], v229, v229 op_sel_hi:[0,0,0]
	v_mfma_scale_f32_16x16x128_f8f6f4 v[126:129], v[26:33], v[178:185], v[126:129], v229, v229 op_sel_hi:[0,0,0]
	v_mfma_scale_f32_16x16x128_f8f6f4 v[118:121], v[18:25], v[206:213], v[118:121], v229, v229 op_sel_hi:[0,0,0]
	v_mfma_scale_f32_16x16x128_f8f6f4 v[110:113], v[26:33], v[206:213], v[110:113], v229, v229 op_sel_hi:[0,0,0]
	s_setprio 0
	s_setprio 1
	v_mfma_scale_f32_16x16x128_f8f6f4 v[146:149], v[2:9], v[162:169], v[146:149], v229, v229 op_sel_hi:[0,0,0]
	v_mfma_scale_f32_16x16x128_f8f6f4 v[138:141], v[10:17], v[162:169], v[138:141], v229, v229 op_sel_hi:[0,0,0]
	v_mfma_scale_f32_16x16x128_f8f6f4 v[130:133], v[2:9], v[170:177], v[130:133], v229, v229 op_sel_hi:[0,0,0]
	v_mfma_scale_f32_16x16x128_f8f6f4 v[122:125], v[10:17], v[170:177], v[122:125], v229, v229 op_sel_hi:[0,0,0]
	v_mfma_scale_f32_16x16x128_f8f6f4 v[114:117], v[2:9], v[178:185], v[114:117], v229, v229 op_sel_hi:[0,0,0]
	v_mfma_scale_f32_16x16x128_f8f6f4 v[106:109], v[10:17], v[178:185], v[106:109], v229, v229 op_sel_hi:[0,0,0]
	v_mfma_scale_f32_16x16x128_f8f6f4 v[102:105], v[2:9], v[206:213], v[102:105], v229, v229 op_sel_hi:[0,0,0]
	v_mfma_scale_f32_16x16x128_f8f6f4 v[98:101], v[10:17], v[206:213], v[98:101], v229, v229 op_sel_hi:[0,0,0]
	s_setprio 0
	s_barrier
	s_add_i32 s75, s40, s27
	v_lshl_add_u64 v[162:163], s[22:23], 0, v[192:193]
	s_mov_b32 m0, s75
	ds_read_b128 v[170:173], v235 offset:16384
	ds_read_b128 v[174:177], v235 offset:17408
	ds_read_b128 v[178:181], v235 offset:18432
	ds_read_b128 v[182:185], v235 offset:19456
	ds_read_b128 v[206:209], v235 offset:20480
	ds_read_b128 v[210:213], v235 offset:21504
	ds_read_b128 v[214:217], v235 offset:22528
	ds_read_b128 v[218:221], v235 offset:23552
	global_load_lds_dwordx4 v[162:163], off
	s_add_i32 m0, s75, 0x2000
	s_add_u32 s78, s22, 0xb0000
	v_lshl_add_u64 v[164:165], s[22:23], 0, v[196:197]
	s_addc_u32 s79, s23, 0
	s_add_i32 s75, s41, s27
	global_load_lds_dwordx4 v[164:165], off
	v_lshl_add_u64 v[166:167], s[78:79], 0, v[192:193]
	s_mov_b32 m0, s75
	v_lshl_add_u64 v[168:169], s[24:25], 0, v[194:195]
	global_load_lds_dwordx4 v[166:167], off
	v_lshl_add_u64 v[166:167], s[78:79], 0, v[196:197]
	s_add_i32 m0, s75, 0x2000
	s_nop 0
	global_load_lds_dwordx4 v[166:167], off
	v_lshl_add_u64 v[166:167], s[24:25], 0, v[190:191]
	s_mov_b32 m0, s28
	s_nop 0
	global_load_lds_dwordx4 v[166:167], off
	s_mov_b32 m0, s29
	s_nop 0
	global_load_lds_dwordx4 v[168:169], off
	s_waitcnt vmcnt(8)
	s_waitcnt lgkmcnt(0)
	s_setprio 1
	s_barrier
	v_mfma_scale_f32_16x16x128_f8f6f4 v[94:97], v[18:25], v[170:177], v[94:97], v229, v229 op_sel_hi:[0,0,0]
	v_mfma_scale_f32_16x16x128_f8f6f4 v[90:93], v[26:33], v[170:177], v[90:93], v229, v229 op_sel_hi:[0,0,0]
	v_mfma_scale_f32_16x16x128_f8f6f4 v[86:89], v[18:25], v[178:185], v[86:89], v229, v229 op_sel_hi:[0,0,0]
	v_mfma_scale_f32_16x16x128_f8f6f4 v[78:81], v[26:33], v[178:185], v[78:81], v229, v229 op_sel_hi:[0,0,0]
	v_mfma_scale_f32_16x16x128_f8f6f4 v[70:73], v[18:25], v[206:213], v[70:73], v229, v229 op_sel_hi:[0,0,0]
	v_mfma_scale_f32_16x16x128_f8f6f4 v[62:65], v[26:33], v[206:213], v[62:65], v229, v229 op_sel_hi:[0,0,0]
	v_mfma_scale_f32_16x16x128_f8f6f4 v[54:57], v[18:25], v[214:221], v[54:57], v229, v229 op_sel_hi:[0,0,0]
	v_mfma_scale_f32_16x16x128_f8f6f4 v[46:49], v[26:33], v[214:221], v[46:49], v229, v229 op_sel_hi:[0,0,0]
	s_setprio 0
	s_setprio 1
	v_mfma_scale_f32_16x16x128_f8f6f4 v[82:85], v[2:9], v[170:177], v[82:85], v229, v229 op_sel_hi:[0,0,0]
	v_mfma_scale_f32_16x16x128_f8f6f4 v[74:77], v[10:17], v[170:177], v[74:77], v229, v229 op_sel_hi:[0,0,0]
	v_mfma_scale_f32_16x16x128_f8f6f4 v[66:69], v[2:9], v[178:185], v[66:69], v229, v229 op_sel_hi:[0,0,0]
	v_mfma_scale_f32_16x16x128_f8f6f4 v[58:61], v[10:17], v[178:185], v[58:61], v229, v229 op_sel_hi:[0,0,0]
	v_mfma_scale_f32_16x16x128_f8f6f4 v[50:53], v[2:9], v[206:213], v[50:53], v229, v229 op_sel_hi:[0,0,0]
	v_mfma_scale_f32_16x16x128_f8f6f4 v[42:45], v[10:17], v[206:213], v[42:45], v229, v229 op_sel_hi:[0,0,0]
	v_mfma_scale_f32_16x16x128_f8f6f4 v[38:41], v[2:9], v[214:221], v[38:41], v229, v229 op_sel_hi:[0,0,0]
	v_mfma_scale_f32_16x16x128_f8f6f4 v[34:37], v[10:17], v[214:221], v[34:37], v229, v229 op_sel_hi:[0,0,0]
	s_setprio 0
	s_barrier
; #define PG8_STAGE(bufoff, gbase, voff) do { _Pragma("unroll") for (int _i = 0; _i < 2; ++_i) \
;         __builtin_amdgcn_global_load_lds((const unsigned*)((const char*)(gbase) + (voff)[_i]), (PG8_LAS unsigned*)(lds + (bufoff) + ldsw + _i * 8192), 16, 0, 0); } while (0)
; #define PG8_WAIT_V(n) asm volatile("s_waitcnt vmcnt(" #n ")" ::: "memory")
; #define PG8_WAIT_L(n) asm volatile("s_waitcnt lgkmcnt(" #n ")" ::: "memory")
; #define PG8_BAR __builtin_amdgcn_s_barrier()
; #define PG8_SCHED __builtin_amdgcn_sched_barrier(0)
; template <class Epi, class Sched, bool ALIGN_EPI = true, bool SP2 = true>
; __device__ __forceinline__ void gemm_phase(PG8_LAS unsigned char* lds, const int K  , const Sched& S, const Epi& E) {
;     ...
;             PG8_LDB(B0, 1, 0); PG8_LDB(B1, 1, 1); PG8_SCHED; PG8_LDA(At, 1, 0); PG8_STAGE(PG8_SA(0, 1), a2 + hstep, voffA);
;             PG8_WAIT_V(8); PG8_WAIT_L(0); PG8_BAR; PG8_MMA(0, 0, At, B0); PG8_MMA(0, 1, At, B1); PG8_BAR; PG8_SCHED;
;             PG8_LDA(At, 1, 1); PG8_STAGE(PG8_SB(1, 0), b3, voffB); PG8_STAGE(PG8_SB(1, 1), b3 + hstep, voffB); PG8_STAGE(PG8_SA(1, 0), a3, voffA);
;             PG8_WAIT_V(8); PG8_WAIT_L(0); PG8_BAR; PG8_MMA(1, 0, At, B0); PG8_MMA(1, 1, At, B1); PG8_BAR; PG8_SCHED;
;     ...
;         if constexpr (Epi::FP8) asm volatile("s_nop 15\n\ts_nop 15\n\ts_nop 15\n\ts_nop 15\n\ts_nop 15" ::: "memory");
;         if constexpr (ALIGN_EPI) { if (wr == 0) PG8_BAR; }
	s_add_i32 s75, 0, 0x18000
	s_add_i32 s78, 0, 0x1c000
	v_add_u32_e32 v14, s75, v231
	v_add_u32_e32 v30, s78, v231
	ds_read_b128 v[2:5], v14
	ds_read_b128 v[6:9], v14 offset:1024
	ds_read_b128 v[10:13], v14 offset:2048
	ds_read_b128 v[14:17], v14 offset:3072
	ds_read_b128 v[18:21], v30
	ds_read_b128 v[22:25], v30 offset:1024
	ds_read_b128 v[26:29], v30 offset:2048
	ds_read_b128 v[30:33], v30 offset:3072
	s_add_u32 s24, s24, 0xb0000
	s_addc_u32 s25, s25, 0
	s_mov_b32 m0, s30
	v_lshl_add_u64 v[186:187], s[24:25], 0, v[190:191]
	ds_read_b128 v[170:173], v235 offset:32768
	ds_read_b128 v[174:177], v235 offset:33792
	ds_read_b128 v[178:181], v235 offset:34816
	ds_read_b128 v[182:185], v235 offset:35840
	ds_read_b128 v[206:209], v235 offset:36864
	ds_read_b128 v[210:213], v235 offset:37888
	ds_read_b128 v[214:217], v235 offset:38912
	ds_read_b128 v[218:221], v235 offset:39936
	global_load_lds_dwordx4 v[186:187], off
	v_lshl_add_u64 v[186:187], s[24:25], 0, v[194:195]
	s_mov_b32 m0, s31
	s_nop 0
	global_load_lds_dwordx4 v[186:187], off
	s_waitcnt vmcnt(8)
	s_waitcnt lgkmcnt(0)
	s_setprio 1
	s_barrier
	v_mfma_scale_f32_16x16x128_f8f6f4 v[158:161], v[2:9], v[170:177], v[158:161], v229, v229 op_sel_hi:[0,0,0]
	v_mfma_scale_f32_16x16x128_f8f6f4 v[154:157], v[10:17], v[170:177], v[154:157], v229, v229 op_sel_hi:[0,0,0]
	v_mfma_scale_f32_16x16x128_f8f6f4 v[150:153], v[2:9], v[178:185], v[150:153], v229, v229 op_sel_hi:[0,0,0]
	v_mfma_scale_f32_16x16x128_f8f6f4 v[142:145], v[10:17], v[178:185], v[142:145], v229, v229 op_sel_hi:[0,0,0]
	v_mfma_scale_f32_16x16x128_f8f6f4 v[134:137], v[2:9], v[206:213], v[134:137], v229, v229 op_sel_hi:[0,0,0]
	v_mfma_scale_f32_16x16x128_f8f6f4 v[126:129], v[10:17], v[206:213], v[126:129], v229, v229 op_sel_hi:[0,0,0]
	v_mfma_scale_f32_16x16x128_f8f6f4 v[118:121], v[2:9], v[214:221], v[118:121], v229, v229 op_sel_hi:[0,0,0]
	v_mfma_scale_f32_16x16x128_f8f6f4 v[110:113], v[10:17], v[214:221], v[110:113], v229, v229 op_sel_hi:[0,0,0]
	s_setprio 0
	s_setprio 1
	v_mfma_scale_f32_16x16x128_f8f6f4 v[146:149], v[18:25], v[170:177], v[146:149], v229, v229 op_sel_hi:[0,0,0]
	v_mfma_scale_f32_16x16x128_f8f6f4 v[138:141], v[26:33], v[170:177], v[138:141], v229, v229 op_sel_hi:[0,0,0]
	v_mfma_scale_f32_16x16x128_f8f6f4 v[130:133], v[18:25], v[178:185], v[130:133], v229, v229 op_sel_hi:[0,0,0]
	v_mfma_scale_f32_16x16x128_f8f6f4 v[122:125], v[26:33], v[178:185], v[122:125], v229, v229 op_sel_hi:[0,0,0]
	v_mfma_scale_f32_16x16x128_f8f6f4 v[114:117], v[18:25], v[206:213], v[114:117], v229, v229 op_sel_hi:[0,0,0]
	v_mfma_scale_f32_16x16x128_f8f6f4 v[106:109], v[26:33], v[206:213], v[106:109], v229, v229 op_sel_hi:[0,0,0]
	v_mfma_scale_f32_16x16x128_f8f6f4 v[102:105], v[18:25], v[214:221], v[102:105], v229, v229 op_sel_hi:[0,0,0]
	v_mfma_scale_f32_16x16x128_f8f6f4 v[98:101], v[26:33], v[214:221], v[98:101], v229, v229 op_sel_hi:[0,0,0]
	s_setprio 0
	s_barrier
	s_add_i32 s24, s75, s27
	v_lshl_add_u64 v[162:163], v[162:163], 0, s[10:11]
	s_mov_b32 m0, s24
	ds_read_b128 v[170:173], v235 offset:49152
	ds_read_b128 v[174:177], v235 offset:50176
	ds_read_b128 v[178:181], v235 offset:51200
	ds_read_b128 v[182:185], v235 offset:52224
	ds_read_b128 v[206:209], v235 offset:53248
	ds_read_b128 v[210:213], v235 offset:54272
	ds_read_b128 v[214:217], v235 offset:55296
	ds_read_b128 v[218:221], v235 offset:56320
	global_load_lds_dwordx4 v[162:163], off
	s_add_i32 m0, s24, 0x2000
	s_add_u32 s22, s22, 0xb0080
	v_lshl_add_u64 v[162:163], v[164:165], 0, s[10:11]
	s_addc_u32 s23, s23, 0
	s_add_i32 s24, s78, s27
	global_load_lds_dwordx4 v[162:163], off
	v_lshl_add_u64 v[162:163], s[22:23], 0, v[192:193]
	s_mov_b32 m0, s24
	s_nop 0
	global_load_lds_dwordx4 v[162:163], off
	v_lshl_add_u64 v[162:163], s[22:23], 0, v[196:197]
	s_add_i32 m0, s24, 0x2000
	s_nop 0
	global_load_lds_dwordx4 v[162:163], off
	v_lshl_add_u64 v[162:163], v[166:167], 0, s[10:11]
	s_mov_b32 m0, s36
	s_nop 0
	global_load_lds_dwordx4 v[162:163], off
	v_lshl_add_u64 v[162:163], v[168:169], 0, s[10:11]
	s_mov_b32 m0, s37
	s_nop 0
	global_load_lds_dwordx4 v[162:163], off
	s_waitcnt vmcnt(8)
	s_waitcnt lgkmcnt(0)
	s_setprio 1
	s_barrier
	v_mfma_scale_f32_16x16x128_f8f6f4 v[94:97], v[2:9], v[170:177], v[94:97], v229, v229 op_sel_hi:[0,0,0]
	v_mfma_scale_f32_16x16x128_f8f6f4 v[90:93], v[10:17], v[170:177], v[90:93], v229, v229 op_sel_hi:[0,0,0]
	v_mfma_scale_f32_16x16x128_f8f6f4 v[86:89], v[2:9], v[178:185], v[86:89], v229, v229 op_sel_hi:[0,0,0]
	v_mfma_scale_f32_16x16x128_f8f6f4 v[78:81], v[10:17], v[178:185], v[78:81], v229, v229 op_sel_hi:[0,0,0]
	v_mfma_scale_f32_16x16x128_f8f6f4 v[70:73], v[2:9], v[206:213], v[70:73], v229, v229 op_sel_hi:[0,0,0]
	v_mfma_scale_f32_16x16x128_f8f6f4 v[62:65], v[10:17], v[206:213], v[62:65], v229, v229 op_sel_hi:[0,0,0]
	v_mfma_scale_f32_16x16x128_f8f6f4 v[54:57], v[2:9], v[214:221], v[54:57], v229, v229 op_sel_hi:[0,0,0]
	v_mfma_scale_f32_16x16x128_f8f6f4 v[46:49], v[10:17], v[214:221], v[46:49], v229, v229 op_sel_hi:[0,0,0]
	s_setprio 0
	s_setprio 1
	v_mfma_scale_f32_16x16x128_f8f6f4 v[82:85], v[18:25], v[170:177], v[82:85], v229, v229 op_sel_hi:[0,0,0]
	v_mfma_scale_f32_16x16x128_f8f6f4 v[74:77], v[26:33], v[170:177], v[74:77], v229, v229 op_sel_hi:[0,0,0]
	v_mfma_scale_f32_16x16x128_f8f6f4 v[66:69], v[18:25], v[178:185], v[66:69], v229, v229 op_sel_hi:[0,0,0]
	v_mfma_scale_f32_16x16x128_f8f6f4 v[58:61], v[26:33], v[178:185], v[58:61], v229, v229 op_sel_hi:[0,0,0]
	v_mfma_scale_f32_16x16x128_f8f6f4 v[50:53], v[18:25], v[206:213], v[50:53], v229, v229 op_sel_hi:[0,0,0]
	v_mfma_scale_f32_16x16x128_f8f6f4 v[42:45], v[26:33], v[206:213], v[42:45], v229, v229 op_sel_hi:[0,0,0]
	v_mfma_scale_f32_16x16x128_f8f6f4 v[38:41], v[18:25], v[214:221], v[38:41], v229, v229 op_sel_hi:[0,0,0]
	v_mfma_scale_f32_16x16x128_f8f6f4 v[34:37], v[26:33], v[214:221], v[34:37], v229, v229 op_sel_hi:[0,0,0]
	s_setprio 0
	s_barrier
	s_add_u32 s20, s20, 0x100
	s_addc_u32 s21, s21, 0
	s_add_u32 s72, s72, 0x100
	s_addc_u32 s73, s73, 0
	s_cmp_ge_u32 s74, s4
	s_mov_b32 s24, s74
	s_cbranch_scc0 .LBB0_1695
	s_nop 15
	s_nop 15
	s_nop 15
	s_nop 15
	s_nop 15
	s_and_b64 vcc, exec, s[12:13]
	s_cbranch_vccz .LBB0_1698
	s_barrier

; #define PG8_STAGE(bufoff, gbase, voff) do { _Pragma("unroll") for (int _i = 0; _i < 2; ++_i) \
;         __builtin_amdgcn_global_load_lds((const unsigned*)((const char*)(gbase) + (voff)[_i]), (PG8_LAS unsigned*)(lds + (bufoff) + ldsw + _i * 8192), 16, 0, 0); } while (0)
; #define PG8_WAIT_V(n) asm volatile("s_waitcnt vmcnt(" #n ")" ::: "memory")
; #define PG8_WAIT_L(n) asm volatile("s_waitcnt lgkmcnt(" #n ")" ::: "memory")
; #define PG8_BAR __builtin_amdgcn_s_barrier()
; #define PG8_SCHED __builtin_amdgcn_sched_barrier(0)
;     __device__ __forceinline__ int nt(const pg8::Unit& u) const { return u.kind == 0 ? ntiles : q_nt(u.kind - 1); }
; template <class Epi, class Sched, bool ALIGN_EPI = true, bool SP2 = true>
; __device__ __forceinline__ void gemm_phase(PG8_LAS unsigned char* lds, const int K  , const Sched& S, const Epi& E) {
;     ...
;             const bool last = (t == nt - 2);
;             const char* a1 = cA + (size_t)(t + 1) * kstep;
;             const char* a2 = last ? nA : cA + (size_t)(t + 2) * kstep; const char* b2 = last ? nB : cB + (size_t)(t + 2) * kstep;
;             const char* a3 = a2 + kstep; const char* b3 = b2 + kstep;
;             if constexpr (SP2) {
;             PG8_LDB(B0, 0, 0); PG8_LDB(B1, 0, 1); PG8_SCHED; PG8_LDA(At, 0, 0); PG8_STAGE(PG8_SA(1, 1), a1 + hstep, voffA);
;             PG8_WAIT_V(8); PG8_WAIT_L(0); PG8_BAR; PG8_MMA(0, 0, At, B0); PG8_MMA(0, 1, At, B1); PG8_BAR; PG8_SCHED;
;             PG8_LDA(At, 0, 1); PG8_STAGE(PG8_SB(0, 0), b2, voffB); PG8_STAGE(PG8_SB(0, 1), b2 + hstep, voffB); PG8_STAGE(PG8_SA(0, 0), a2, voffA);
;             PG8_WAIT_V(8); PG8_WAIT_L(0); PG8_BAR; PG8_MMA(1, 0, At, B0); PG8_MMA(1, 1, At, B1); PG8_BAR; PG8_SCHED;
.LBB0_1847:
	ds_read_b128 v[130:133], v176
	ds_read_b128 v[134:137], v176 offset:1024
	ds_read_b128 v[138:141], v176 offset:2048
	ds_read_b128 v[142:145], v176 offset:3072
	ds_read_b128 v[168:171], v177
	ds_read_b128 v[184:187], v177 offset:1024
	ds_read_b128 v[188:191], v177 offset:2048
	ds_read_b128 v[192:195], v177 offset:3072
	s_add_u32 s22, s0, 0xfff80080
	s_addc_u32 s23, s1, -1
	s_cmp_eq_u32 s51, 28
	s_cselect_b32 s25, s7, s23
	s_cselect_b32 s24, s47, s22
	s_cselect_b32 s23, s11, s50
	s_cselect_b32 s22, s48, s49
	v_lshl_add_u64 v[230:231], s[0:1], 0, v[160:161]
	s_add_i32 m0, s27, 0xc000
	ds_read_b128 v[196:199], v178
	ds_read_b128 v[200:203], v178 offset:1024
	ds_read_b128 v[204:207], v178 offset:2048
	ds_read_b128 v[208:211], v178 offset:3072
	ds_read_b128 v[212:215], v178 offset:4096
	ds_read_b128 v[216:219], v178 offset:5120
	ds_read_b128 v[220:223], v178 offset:6144
	ds_read_b128 v[224:227], v178 offset:7168
	global_load_lds_dwordx4 v[230:231], off
	v_lshl_add_u64 v[230:231], s[0:1], 0, v[162:163]
	s_add_i32 m0, s27, 0xe000
	s_nop 0
	global_load_lds_dwordx4 v[230:231], off
	s_waitcnt vmcnt(8)
	s_waitcnt lgkmcnt(0)
	s_setprio 1
	s_barrier
	v_mfma_f32_16x16x32_bf16 v[126:129], v[130:133], v[196:199], v[126:129]
	v_mfma_f32_16x16x32_bf16 v[122:125], v[138:141], v[196:199], v[122:125]
	v_mfma_f32_16x16x32_bf16 v[110:113], v[130:133], v[204:207], v[110:113]
	v_mfma_f32_16x16x32_bf16 v[106:109], v[138:141], v[204:207], v[106:109]
	v_mfma_f32_16x16x32_bf16 v[94:97], v[130:133], v[212:215], v[94:97]
	v_mfma_f32_16x16x32_bf16 v[90:93], v[138:141], v[212:215], v[90:93]
	v_mfma_f32_16x16x32_bf16 v[78:81], v[130:133], v[220:223], v[78:81]
	v_mfma_f32_16x16x32_bf16 v[74:77], v[138:141], v[220:223], v[74:77]
	v_mfma_f32_16x16x32_bf16 v[126:129], v[134:137], v[200:203], v[126:129]
	v_mfma_f32_16x16x32_bf16 v[122:125], v[142:145], v[200:203], v[122:125]
	v_mfma_f32_16x16x32_bf16 v[110:113], v[134:137], v[208:211], v[110:113]
	v_mfma_f32_16x16x32_bf16 v[106:109], v[142:145], v[208:211], v[106:109]
	v_mfma_f32_16x16x32_bf16 v[94:97], v[134:137], v[216:219], v[94:97]
	v_mfma_f32_16x16x32_bf16 v[90:93], v[142:145], v[216:219], v[90:93]
	v_mfma_f32_16x16x32_bf16 v[78:81], v[134:137], v[224:227], v[78:81]
	v_mfma_f32_16x16x32_bf16 v[74:77], v[142:145], v[224:227], v[74:77]
	s_setprio 0
	s_setprio 1
	v_mfma_f32_16x16x32_bf16 v[118:121], v[168:171], v[196:199], v[118:121]
	v_mfma_f32_16x16x32_bf16 v[114:117], v[188:191], v[196:199], v[114:117]
	v_mfma_f32_16x16x32_bf16 v[102:105], v[168:171], v[204:207], v[102:105]
	v_mfma_f32_16x16x32_bf16 v[98:101], v[188:191], v[204:207], v[98:101]
	v_mfma_f32_16x16x32_bf16 v[86:89], v[168:171], v[212:215], v[86:89]
	v_mfma_f32_16x16x32_bf16 v[82:85], v[188:191], v[212:215], v[82:85]
	v_mfma_f32_16x16x32_bf16 v[70:73], v[168:171], v[220:223], v[70:73]
	v_mfma_f32_16x16x32_bf16 v[66:69], v[188:191], v[220:223], v[66:69]
	v_mfma_f32_16x16x32_bf16 v[118:121], v[184:187], v[200:203], v[118:121]
	v_mfma_f32_16x16x32_bf16 v[114:117], v[192:195], v[200:203], v[114:117]
	v_mfma_f32_16x16x32_bf16 v[102:105], v[184:187], v[208:211], v[102:105]
	v_mfma_f32_16x16x32_bf16 v[98:101], v[192:195], v[208:211], v[98:101]
	v_mfma_f32_16x16x32_bf16 v[86:89], v[184:187], v[216:219], v[86:89]
	v_mfma_f32_16x16x32_bf16 v[82:85], v[192:195], v[216:219], v[82:85]
	v_mfma_f32_16x16x32_bf16 v[70:73], v[184:187], v[224:227], v[70:73]
	v_mfma_f32_16x16x32_bf16 v[66:69], v[192:195], v[224:227], v[66:69]
	s_setprio 0
	s_barrier
	s_add_i32 s68, s39, s26
	v_lshl_add_u64 v[230:231], s[22:23], 0, v[150:151]
	s_mov_b32 m0, s68
	ds_read_b128 v[196:199], v178 offset:16384
	ds_read_b128 v[200:203], v178 offset:17408
	ds_read_b128 v[204:207], v178 offset:18432
	ds_read_b128 v[208:211], v178 offset:19456
	ds_read_b128 v[212:215], v178 offset:20480
	ds_read_b128 v[216:219], v178 offset:21504
	ds_read_b128 v[220:223], v178 offset:22528
	ds_read_b128 v[224:227], v178 offset:23552
	global_load_lds_dwordx4 v[230:231], off
	s_add_i32 m0, s68, 0x2000
	s_add_u32 s68, s22, 0x80000
	v_lshl_add_u64 v[232:233], s[22:23], 0, v[154:155]
	s_addc_u32 s69, s23, 0
	s_add_i32 s70, s40, s26
	global_load_lds_dwordx4 v[232:233], off
	v_lshl_add_u64 v[234:235], s[68:69], 0, v[150:151]
	s_mov_b32 m0, s70
	v_lshl_add_u64 v[236:237], s[24:25], 0, v[152:153]
	global_load_lds_dwordx4 v[234:235], off
	v_lshl_add_u64 v[234:235], s[68:69], 0, v[154:155]
	s_add_i32 m0, s70, 0x2000
	s_nop 0
	global_load_lds_dwordx4 v[234:235], off
	v_lshl_add_u64 v[234:235], s[24:25], 0, v[148:149]
	s_mov_b32 m0, s27
	s_nop 0
	global_load_lds_dwordx4 v[234:235], off
	s_mov_b32 m0, s28
	s_nop 0
	global_load_lds_dwordx4 v[236:237], off
	s_waitcnt vmcnt(8)
	s_waitcnt lgkmcnt(0)
	s_setprio 1
	s_barrier
; #define PG8_STAGE(bufoff, gbase, voff) do { _Pragma("unroll") for (int _i = 0; _i < 2; ++_i) \
;         __builtin_amdgcn_global_load_lds((const unsigned*)((const char*)(gbase) + (voff)[_i]), (PG8_LAS unsigned*)(lds + (bufoff) + ldsw + _i * 8192), 16, 0, 0); } while (0)
; #define PG8_WAIT_V(n) asm volatile("s_waitcnt vmcnt(" #n ")" ::: "memory")
; #define PG8_WAIT_L(n) asm volatile("s_waitcnt lgkmcnt(" #n ")" ::: "memory")
; #define PG8_BAR __builtin_amdgcn_s_barrier()
; #define PG8_SCHED __builtin_amdgcn_sched_barrier(0)
; template <class Epi, class Sched, bool ALIGN_EPI = true, bool SP2 = true>
; __device__ __forceinline__ void gemm_phase(PG8_LAS unsigned char* lds, const int K  , const Sched& S, const Epi& E) {
;     ...
;             PG8_WAIT_V(8); PG8_WAIT_L(0); PG8_BAR; PG8_MMA(1, 0, At, B0); PG8_MMA(1, 1, At, B1); PG8_BAR; PG8_SCHED;
;             PG8_LDB(B0, 1, 0); PG8_LDB(B1, 1, 1); PG8_SCHED; PG8_LDA(At, 1, 0); PG8_STAGE(PG8_SA(0, 1), a2 + hstep, voffA);
;             PG8_WAIT_V(8); PG8_WAIT_L(0); PG8_BAR; PG8_MMA(0, 0, At, B0); PG8_MMA(0, 1, At, B1); PG8_BAR; PG8_SCHED;
	v_mfma_f32_16x16x32_bf16 v[62:65], v[130:133], v[196:199], v[62:65]
	v_mfma_f32_16x16x32_bf16 v[58:61], v[138:141], v[196:199], v[58:61]
	v_mfma_f32_16x16x32_bf16 v[46:49], v[130:133], v[204:207], v[46:49]
	v_mfma_f32_16x16x32_bf16 v[42:45], v[138:141], v[204:207], v[42:45]
	v_mfma_f32_16x16x32_bf16 v[30:33], v[130:133], v[212:215], v[30:33]
	v_mfma_f32_16x16x32_bf16 v[26:29], v[138:141], v[212:215], v[26:29]
	v_mfma_f32_16x16x32_bf16 v[14:17], v[130:133], v[220:223], v[14:17]
	v_mfma_f32_16x16x32_bf16 v[10:13], v[138:141], v[220:223], v[10:13]
	v_mfma_f32_16x16x32_bf16 v[62:65], v[134:137], v[200:203], v[62:65]
	v_mfma_f32_16x16x32_bf16 v[58:61], v[142:145], v[200:203], v[58:61]
	v_mfma_f32_16x16x32_bf16 v[46:49], v[134:137], v[208:211], v[46:49]
	v_mfma_f32_16x16x32_bf16 v[42:45], v[142:145], v[208:211], v[42:45]
	v_mfma_f32_16x16x32_bf16 v[30:33], v[134:137], v[216:219], v[30:33]
	v_mfma_f32_16x16x32_bf16 v[26:29], v[142:145], v[216:219], v[26:29]
	v_mfma_f32_16x16x32_bf16 v[14:17], v[134:137], v[224:227], v[14:17]
	v_mfma_f32_16x16x32_bf16 v[10:13], v[142:145], v[224:227], v[10:13]
	s_setprio 0
	s_setprio 1
	v_mfma_f32_16x16x32_bf16 v[54:57], v[168:171], v[196:199], v[54:57]
	v_mfma_f32_16x16x32_bf16 v[50:53], v[188:191], v[196:199], v[50:53]
	v_mfma_f32_16x16x32_bf16 v[38:41], v[168:171], v[204:207], v[38:41]
	v_mfma_f32_16x16x32_bf16 v[34:37], v[188:191], v[204:207], v[34:37]
	v_mfma_f32_16x16x32_bf16 v[22:25], v[168:171], v[212:215], v[22:25]
	v_mfma_f32_16x16x32_bf16 v[18:21], v[188:191], v[212:215], v[18:21]
	v_mfma_f32_16x16x32_bf16 v[6:9], v[168:171], v[220:223], v[6:9]
	v_mfma_f32_16x16x32_bf16 v[2:5], v[188:191], v[220:223], v[2:5]
	v_mfma_f32_16x16x32_bf16 v[54:57], v[184:187], v[200:203], v[54:57]
	v_mfma_f32_16x16x32_bf16 v[50:53], v[192:195], v[200:203], v[50:53]
	v_mfma_f32_16x16x32_bf16 v[38:41], v[184:187], v[208:211], v[38:41]
	v_mfma_f32_16x16x32_bf16 v[34:37], v[192:195], v[208:211], v[34:37]
	v_mfma_f32_16x16x32_bf16 v[22:25], v[184:187], v[216:219], v[22:25]
	v_mfma_f32_16x16x32_bf16 v[18:21], v[192:195], v[216:219], v[18:21]
	v_mfma_f32_16x16x32_bf16 v[6:9], v[184:187], v[224:227], v[6:9]
	v_mfma_f32_16x16x32_bf16 v[2:5], v[192:195], v[224:227], v[2:5]
	s_setprio 0
	s_barrier
	s_add_i32 s68, 0, 0x18000
	s_add_i32 s69, 0, 0x1c000
	v_add_u32_e32 v142, s68, v172
	v_add_u32_e32 v192, s69, v172
	ds_read_b128 v[130:133], v142
	ds_read_b128 v[134:137], v142 offset:1024
	ds_read_b128 v[138:141], v142 offset:2048
	ds_read_b128 v[142:145], v142 offset:3072
	ds_read_b128 v[168:171], v192
	ds_read_b128 v[184:187], v192 offset:1024
	ds_read_b128 v[188:191], v192 offset:2048
	ds_read_b128 v[192:195], v192 offset:3072
	s_add_u32 s24, s24, 0x80000
	s_addc_u32 s25, s25, 0
	s_mov_b32 m0, s29
	v_lshl_add_u64 v[238:239], s[24:25], 0, v[148:149]
	ds_read_b128 v[196:199], v178 offset:32768
	ds_read_b128 v[200:203], v178 offset:33792
	ds_read_b128 v[204:207], v178 offset:34816
	ds_read_b128 v[208:211], v178 offset:35840
	ds_read_b128 v[212:215], v178 offset:36864
	ds_read_b128 v[216:219], v178 offset:37888
	ds_read_b128 v[220:223], v178 offset:38912
	ds_read_b128 v[224:227], v178 offset:39936
	global_load_lds_dwordx4 v[238:239], off
	v_lshl_add_u64 v[238:239], s[24:25], 0, v[152:153]
	s_mov_b32 m0, s30
	s_nop 0
	global_load_lds_dwordx4 v[238:239], off
	s_waitcnt vmcnt(8)
	s_waitcnt lgkmcnt(0)
	s_setprio 1
	s_barrier
	v_mfma_f32_16x16x32_bf16 v[126:129], v[130:133], v[196:199], v[126:129]
	v_mfma_f32_16x16x32_bf16 v[122:125], v[138:141], v[196:199], v[122:125]
	v_mfma_f32_16x16x32_bf16 v[110:113], v[130:133], v[204:207], v[110:113]
	v_mfma_f32_16x16x32_bf16 v[106:109], v[138:141], v[204:207], v[106:109]
	v_mfma_f32_16x16x32_bf16 v[94:97], v[130:133], v[212:215], v[94:97]
	v_mfma_f32_16x16x32_bf16 v[90:93], v[138:141], v[212:215], v[90:93]
	v_mfma_f32_16x16x32_bf16 v[78:81], v[130:133], v[220:223], v[78:81]
	v_mfma_f32_16x16x32_bf16 v[74:77], v[138:141], v[220:223], v[74:77]
	v_mfma_f32_16x16x32_bf16 v[126:129], v[134:137], v[200:203], v[126:129]
	v_mfma_f32_16x16x32_bf16 v[122:125], v[142:145], v[200:203], v[122:125]
	v_mfma_f32_16x16x32_bf16 v[110:113], v[134:137], v[208:211], v[110:113]
	v_mfma_f32_16x16x32_bf16 v[106:109], v[142:145], v[208:211], v[106:109]
	v_mfma_f32_16x16x32_bf16 v[94:97], v[134:137], v[216:219], v[94:97]
	v_mfma_f32_16x16x32_bf16 v[90:93], v[142:145], v[216:219], v[90:93]
	v_mfma_f32_16x16x32_bf16 v[78:81], v[134:137], v[224:227], v[78:81]
	v_mfma_f32_16x16x32_bf16 v[74:77], v[142:145], v[224:227], v[74:77]
	s_setprio 0
	s_setprio 1
	v_mfma_f32_16x16x32_bf16 v[118:121], v[168:171], v[196:199], v[118:121]
	v_mfma_f32_16x16x32_bf16 v[114:117], v[188:191], v[196:199], v[114:117]
	v_mfma_f32_16x16x32_bf16 v[102:105], v[168:171], v[204:207], v[102:105]
	v_mfma_f32_16x16x32_bf16 v[98:101], v[188:191], v[204:207], v[98:101]
	v_mfma_f32_16x16x32_bf16 v[86:89], v[168:171], v[212:215], v[86:89]
	v_mfma_f32_16x16x32_bf16 v[82:85], v[188:191], v[212:215], v[82:85]
	v_mfma_f32_16x16x32_bf16 v[70:73], v[168:171], v[220:223], v[70:73]
	v_mfma_f32_16x16x32_bf16 v[66:69], v[188:191], v[220:223], v[66:69]
	v_mfma_f32_16x16x32_bf16 v[118:121], v[184:187], v[200:203], v[118:121]
	v_mfma_f32_16x16x32_bf16 v[114:117], v[192:195], v[200:203], v[114:117]
	v_mfma_f32_16x16x32_bf16 v[102:105], v[184:187], v[208:211], v[102:105]
	v_mfma_f32_16x16x32_bf16 v[98:101], v[192:195], v[208:211], v[98:101]
	v_mfma_f32_16x16x32_bf16 v[86:89], v[184:187], v[216:219], v[86:89]
	v_mfma_f32_16x16x32_bf16 v[82:85], v[192:195], v[216:219], v[82:85]
	v_mfma_f32_16x16x32_bf16 v[70:73], v[184:187], v[224:227], v[70:73]
	v_mfma_f32_16x16x32_bf16 v[66:69], v[192:195], v[224:227], v[66:69]
	s_setprio 0
	s_barrier
; #define PG8_STAGE(bufoff, gbase, voff) do { _Pragma("unroll") for (int _i = 0; _i < 2; ++_i) \
;         __builtin_amdgcn_global_load_lds((const unsigned*)((const char*)(gbase) + (voff)[_i]), (PG8_LAS unsigned*)(lds + (bufoff) + ldsw + _i * 8192), 16, 0, 0); } while (0)
; #define PG8_WAIT_V(n) asm volatile("s_waitcnt vmcnt(" #n ")" ::: "memory")
; #define PG8_WAIT_L(n) asm volatile("s_waitcnt lgkmcnt(" #n ")" ::: "memory")
; #define PG8_BAR __builtin_amdgcn_s_barrier()
; #define PG8_SCHED __builtin_amdgcn_sched_barrier(0)
; template <class Epi, class Sched, bool ALIGN_EPI = true, bool SP2 = true>
; __device__ __forceinline__ void gemm_phase(PG8_LAS unsigned char* lds, const int K  , const Sched& S, const Epi& E) {
;     ...
;             PG8_LDA(At, 1, 1); PG8_STAGE(PG8_SB(1, 0), b3, voffB); PG8_STAGE(PG8_SB(1, 1), b3 + hstep, voffB); PG8_STAGE(PG8_SA(1, 0), a3, voffA);
;             PG8_WAIT_V(8); PG8_WAIT_L(0); PG8_BAR; PG8_MMA(1, 0, At, B0); PG8_MMA(1, 1, At, B1); PG8_BAR; PG8_SCHED;
;     ...
;         if constexpr (ALIGN_EPI) { if (wr == 0) PG8_BAR; }
	s_add_i32 s24, s68, s26
	v_lshl_add_u64 v[230:231], v[230:231], 0, s[4:5]
	s_mov_b32 m0, s24
	ds_read_b128 v[196:199], v178 offset:49152
	ds_read_b128 v[200:203], v178 offset:50176
	ds_read_b128 v[204:207], v178 offset:51200
	ds_read_b128 v[208:211], v178 offset:52224
	ds_read_b128 v[212:215], v178 offset:53248
	ds_read_b128 v[216:219], v178 offset:54272
	ds_read_b128 v[220:223], v178 offset:55296
	ds_read_b128 v[224:227], v178 offset:56320
	global_load_lds_dwordx4 v[230:231], off
	s_add_i32 m0, s24, 0x2000
	s_add_u32 s22, s22, 0x80080
	v_lshl_add_u64 v[230:231], v[232:233], 0, s[4:5]
	s_addc_u32 s23, s23, 0
	s_add_i32 s24, s69, s26
	global_load_lds_dwordx4 v[230:231], off
	v_lshl_add_u64 v[230:231], s[22:23], 0, v[150:151]
	s_mov_b32 m0, s24
	s_nop 0
	global_load_lds_dwordx4 v[230:231], off
	v_lshl_add_u64 v[230:231], s[22:23], 0, v[154:155]
	s_add_i32 m0, s24, 0x2000
	s_nop 0
	global_load_lds_dwordx4 v[230:231], off
	v_lshl_add_u64 v[230:231], v[234:235], 0, s[4:5]
	s_mov_b32 m0, s35
	s_nop 0
	global_load_lds_dwordx4 v[230:231], off
	v_lshl_add_u64 v[230:231], v[236:237], 0, s[4:5]
	s_mov_b32 m0, s36
	s_nop 0
	global_load_lds_dwordx4 v[230:231], off
	s_waitcnt vmcnt(8)
	s_waitcnt lgkmcnt(0)
	s_setprio 1
	s_barrier
	v_mfma_f32_16x16x32_bf16 v[62:65], v[130:133], v[196:199], v[62:65]
	v_mfma_f32_16x16x32_bf16 v[58:61], v[138:141], v[196:199], v[58:61]
	v_mfma_f32_16x16x32_bf16 v[46:49], v[130:133], v[204:207], v[46:49]
	v_mfma_f32_16x16x32_bf16 v[42:45], v[138:141], v[204:207], v[42:45]
	v_mfma_f32_16x16x32_bf16 v[30:33], v[130:133], v[212:215], v[30:33]
	v_mfma_f32_16x16x32_bf16 v[26:29], v[138:141], v[212:215], v[26:29]
	v_mfma_f32_16x16x32_bf16 v[14:17], v[130:133], v[220:223], v[14:17]
	v_mfma_f32_16x16x32_bf16 v[10:13], v[138:141], v[220:223], v[10:13]
	v_mfma_f32_16x16x32_bf16 v[62:65], v[134:137], v[200:203], v[62:65]
	v_mfma_f32_16x16x32_bf16 v[58:61], v[142:145], v[200:203], v[58:61]
	v_mfma_f32_16x16x32_bf16 v[46:49], v[134:137], v[208:211], v[46:49]
	v_mfma_f32_16x16x32_bf16 v[42:45], v[142:145], v[208:211], v[42:45]
	v_mfma_f32_16x16x32_bf16 v[30:33], v[134:137], v[216:219], v[30:33]
	v_mfma_f32_16x16x32_bf16 v[26:29], v[142:145], v[216:219], v[26:29]
	v_mfma_f32_16x16x32_bf16 v[14:17], v[134:137], v[224:227], v[14:17]
	v_mfma_f32_16x16x32_bf16 v[10:13], v[142:145], v[224:227], v[10:13]
	s_setprio 0
	s_setprio 1
	v_mfma_f32_16x16x32_bf16 v[54:57], v[168:171], v[196:199], v[54:57]
	v_mfma_f32_16x16x32_bf16 v[50:53], v[188:191], v[196:199], v[50:53]
	v_mfma_f32_16x16x32_bf16 v[38:41], v[168:171], v[204:207], v[38:41]
	v_mfma_f32_16x16x32_bf16 v[34:37], v[188:191], v[204:207], v[34:37]
	v_mfma_f32_16x16x32_bf16 v[22:25], v[168:171], v[212:215], v[22:25]
	v_mfma_f32_16x16x32_bf16 v[18:21], v[188:191], v[212:215], v[18:21]
	v_mfma_f32_16x16x32_bf16 v[6:9], v[168:171], v[220:223], v[6:9]
	v_mfma_f32_16x16x32_bf16 v[2:5], v[188:191], v[220:223], v[2:5]
	v_mfma_f32_16x16x32_bf16 v[54:57], v[184:187], v[200:203], v[54:57]
	v_mfma_f32_16x16x32_bf16 v[50:53], v[192:195], v[200:203], v[50:53]
	v_mfma_f32_16x16x32_bf16 v[38:41], v[184:187], v[208:211], v[38:41]
	v_mfma_f32_16x16x32_bf16 v[34:37], v[192:195], v[208:211], v[34:37]
	v_mfma_f32_16x16x32_bf16 v[22:25], v[184:187], v[216:219], v[22:25]
	v_mfma_f32_16x16x32_bf16 v[18:21], v[192:195], v[216:219], v[18:21]
	v_mfma_f32_16x16x32_bf16 v[6:9], v[184:187], v[224:227], v[6:9]
	v_mfma_f32_16x16x32_bf16 v[2:5], v[192:195], v[224:227], v[2:5]
	s_setprio 0
	s_barrier
	s_add_i32 s51, s51, 2
	s_add_u32 s0, s0, 0x100
	s_addc_u32 s1, s1, 0
	s_add_u32 s49, s49, 0x100
	s_addc_u32 s50, s50, 0
	s_cmp_gt_u32 s51, 29
	s_cbranch_scc0 .LBB0_1847
	s_and_b64 vcc, exec, s[8:9]
	s_cbranch_vccz .LBB0_1850
	s_barrier

; #define PG8_STAGE(bufoff, gbase, voff) do { _Pragma("unroll") for (int _i = 0; _i < 2; ++_i) \
;         __builtin_amdgcn_global_load_lds((const unsigned*)((const char*)(gbase) + (voff)[_i]), (PG8_LAS unsigned*)(lds + (bufoff) + ldsw + _i * 8192), 16, 0, 0); } while (0)
; #define PG8_WAIT_V(n) asm volatile("s_waitcnt vmcnt(" #n ")" ::: "memory")
; #define PG8_WAIT_L(n) asm volatile("s_waitcnt lgkmcnt(" #n ")" ::: "memory")
; #define PG8_BAR __builtin_amdgcn_s_barrier()
; #define PG8_SCHED __builtin_amdgcn_sched_barrier(0)
;     __device__ __forceinline__ int nt(const pg8::Unit& u) const { return u.kind == 0 ? ntiles : q_nt(u.kind - 1); }
; template <class Epi, class Sched, bool ALIGN_EPI = true, bool SP2 = true>
; __device__ __forceinline__ void gemm_phase(PG8_LAS unsigned char* lds, const int K  , const Sched& S, const Epi& E) {
;     ...
;             const bool last = (t == nt - 2);
;             const char* a1 = cA + (size_t)(t + 1) * kstep;
;             const char* a2 = last ? nA : cA + (size_t)(t + 2) * kstep; const char* b2 = last ? nB : cB + (size_t)(t + 2) * kstep;
;             const char* a3 = a2 + kstep; const char* b3 = b2 + kstep;
;             if constexpr (SP2) {
;             PG8_LDB(B0, 0, 0); PG8_LDB(B1, 0, 1); PG8_SCHED; PG8_LDA(At, 0, 0); PG8_STAGE(PG8_SA(1, 1), a1 + hstep, voffA);
;             PG8_WAIT_V(8); PG8_WAIT_L(0); PG8_BAR; PG8_MMA(0, 0, At, B0); PG8_MMA(0, 1, At, B1); PG8_BAR; PG8_SCHED;
;             PG8_LDA(At, 0, 1); PG8_STAGE(PG8_SB(0, 0), b2, voffB); PG8_STAGE(PG8_SB(0, 1), b2 + hstep, voffB); PG8_STAGE(PG8_SA(0, 0), a2, voffA);
;             PG8_WAIT_V(8); PG8_WAIT_L(0); PG8_BAR; PG8_MMA(1, 0, At, B0); PG8_MMA(1, 1, At, B1); PG8_BAR; PG8_SCHED;
.LBB0_2296:
	ds_read_b128 v[130:133], v203
	ds_read_b128 v[134:137], v203 offset:1024
	ds_read_b128 v[138:141], v203 offset:2048
	ds_read_b128 v[142:145], v203 offset:3072
	ds_read_b128 v[146:149], v204
	ds_read_b128 v[150:153], v204 offset:1024
	ds_read_b128 v[154:157], v204 offset:2048
	ds_read_b128 v[158:161], v204 offset:3072
	s_add_u32 s22, s20, 0xfff80080
	s_addc_u32 s23, s21, -1
	s_cmp_eq_u32 s54, 28
	s_cselect_b32 s25, s13, s23
	s_cselect_b32 s24, s50, s22
	s_cselect_b32 s23, s11, s53
	s_cselect_b32 s22, s51, s52
	v_lshl_add_u64 v[198:199], s[20:21], 0, v[190:191]
	s_add_i32 m0, s19, 0xc000
	ds_read_b128 v[162:165], v205
	ds_read_b128 v[166:169], v205 offset:1024
	ds_read_b128 v[170:173], v205 offset:2048
	ds_read_b128 v[174:177], v205 offset:3072
	ds_read_b128 v[178:181], v205 offset:4096
	ds_read_b128 v[206:209], v205 offset:5120
	ds_read_b128 v[210:213], v205 offset:6144
	ds_read_b128 v[214:217], v205 offset:7168
	global_load_lds_dwordx4 v[198:199], off
	v_lshl_add_u64 v[198:199], s[20:21], 0, v[192:193]
	s_add_i32 m0, s19, 0xe000
	s_nop 0
	global_load_lds_dwordx4 v[198:199], off
	s_waitcnt vmcnt(8)
	s_waitcnt lgkmcnt(0)
	s_setprio 1
	s_barrier
	v_mfma_f32_16x16x32_bf16 v[126:129], v[130:133], v[162:165], v[126:129]
	v_mfma_f32_16x16x32_bf16 v[122:125], v[138:141], v[162:165], v[122:125]
	v_mfma_f32_16x16x32_bf16 v[114:117], v[130:133], v[170:173], v[114:117]
	v_mfma_f32_16x16x32_bf16 v[106:109], v[138:141], v[170:173], v[106:109]
	v_mfma_f32_16x16x32_bf16 v[98:101], v[130:133], v[178:181], v[98:101]
	v_mfma_f32_16x16x32_bf16 v[90:93], v[138:141], v[178:181], v[90:93]
	v_mfma_f32_16x16x32_bf16 v[82:85], v[130:133], v[210:213], v[82:85]
	v_mfma_f32_16x16x32_bf16 v[74:77], v[138:141], v[210:213], v[74:77]
	v_mfma_f32_16x16x32_bf16 v[126:129], v[134:137], v[166:169], v[126:129]
	v_mfma_f32_16x16x32_bf16 v[122:125], v[142:145], v[166:169], v[122:125]
	v_mfma_f32_16x16x32_bf16 v[114:117], v[134:137], v[174:177], v[114:117]
	v_mfma_f32_16x16x32_bf16 v[106:109], v[142:145], v[174:177], v[106:109]
	v_mfma_f32_16x16x32_bf16 v[98:101], v[134:137], v[206:209], v[98:101]
	v_mfma_f32_16x16x32_bf16 v[90:93], v[142:145], v[206:209], v[90:93]
	v_mfma_f32_16x16x32_bf16 v[82:85], v[134:137], v[214:217], v[82:85]
	v_mfma_f32_16x16x32_bf16 v[74:77], v[142:145], v[214:217], v[74:77]
	s_setprio 0
	s_setprio 1
	v_mfma_f32_16x16x32_bf16 v[118:121], v[146:149], v[162:165], v[118:121]
	v_mfma_f32_16x16x32_bf16 v[110:113], v[154:157], v[162:165], v[110:113]
	v_mfma_f32_16x16x32_bf16 v[102:105], v[146:149], v[170:173], v[102:105]
	v_mfma_f32_16x16x32_bf16 v[94:97], v[154:157], v[170:173], v[94:97]
	v_mfma_f32_16x16x32_bf16 v[86:89], v[146:149], v[178:181], v[86:89]
	v_mfma_f32_16x16x32_bf16 v[78:81], v[154:157], v[178:181], v[78:81]
	v_mfma_f32_16x16x32_bf16 v[70:73], v[146:149], v[210:213], v[70:73]
	v_mfma_f32_16x16x32_bf16 v[66:69], v[154:157], v[210:213], v[66:69]
	v_mfma_f32_16x16x32_bf16 v[118:121], v[150:153], v[166:169], v[118:121]
	v_mfma_f32_16x16x32_bf16 v[110:113], v[158:161], v[166:169], v[110:113]
	v_mfma_f32_16x16x32_bf16 v[102:105], v[150:153], v[174:177], v[102:105]
	v_mfma_f32_16x16x32_bf16 v[94:97], v[158:161], v[174:177], v[94:97]
	v_mfma_f32_16x16x32_bf16 v[86:89], v[150:153], v[206:209], v[86:89]
	v_mfma_f32_16x16x32_bf16 v[78:81], v[158:161], v[206:209], v[78:81]
	v_mfma_f32_16x16x32_bf16 v[70:73], v[150:153], v[214:217], v[70:73]
	v_mfma_f32_16x16x32_bf16 v[66:69], v[158:161], v[214:217], v[66:69]
	s_setprio 0
	s_barrier
	s_add_i32 s55, s42, s29
	v_lshl_add_u64 v[198:199], s[22:23], 0, v[184:185]
	s_mov_b32 m0, s55
	ds_read_b128 v[162:165], v205 offset:16384
	ds_read_b128 v[166:169], v205 offset:17408
	ds_read_b128 v[170:173], v205 offset:18432
	ds_read_b128 v[174:177], v205 offset:19456
	ds_read_b128 v[178:181], v205 offset:20480
	ds_read_b128 v[206:209], v205 offset:21504
	ds_read_b128 v[210:213], v205 offset:22528
	ds_read_b128 v[214:217], v205 offset:23552
	global_load_lds_dwordx4 v[198:199], off
	s_add_i32 m0, s55, 0x2000
	s_add_u32 s56, s22, 0x80000
	v_lshl_add_u64 v[218:219], s[22:23], 0, v[188:189]
	s_addc_u32 s57, s23, 0
	s_add_i32 s55, s43, s29
	global_load_lds_dwordx4 v[218:219], off
	v_lshl_add_u64 v[220:221], s[56:57], 0, v[184:185]
	s_mov_b32 m0, s55
	v_lshl_add_u64 v[222:223], s[24:25], 0, v[186:187]
	global_load_lds_dwordx4 v[220:221], off
	v_lshl_add_u64 v[220:221], s[56:57], 0, v[188:189]
	s_add_i32 m0, s55, 0x2000
	s_nop 0
	global_load_lds_dwordx4 v[220:221], off
	v_lshl_add_u64 v[220:221], s[24:25], 0, v[182:183]
	s_mov_b32 m0, s19
	s_nop 0
	global_load_lds_dwordx4 v[220:221], off
	s_mov_b32 m0, s30
	s_nop 0
	global_load_lds_dwordx4 v[222:223], off
	s_waitcnt vmcnt(8)
	s_waitcnt lgkmcnt(0)
	s_setprio 1
	s_barrier
; #define PG8_STAGE(bufoff, gbase, voff) do { _Pragma("unroll") for (int _i = 0; _i < 2; ++_i) \
;         __builtin_amdgcn_global_load_lds((const unsigned*)((const char*)(gbase) + (voff)[_i]), (PG8_LAS unsigned*)(lds + (bufoff) + ldsw + _i * 8192), 16, 0, 0); } while (0)
; #define PG8_WAIT_V(n) asm volatile("s_waitcnt vmcnt(" #n ")" ::: "memory")
; #define PG8_WAIT_L(n) asm volatile("s_waitcnt lgkmcnt(" #n ")" ::: "memory")
; #define PG8_BAR __builtin_amdgcn_s_barrier()
; #define PG8_SCHED __builtin_amdgcn_sched_barrier(0)
; template <class Epi, class Sched, bool ALIGN_EPI = true, bool SP2 = true>
; __device__ __forceinline__ void gemm_phase(PG8_LAS unsigned char* lds, const int K  , const Sched& S, const Epi& E) {
;     ...
;             PG8_WAIT_V(8); PG8_WAIT_L(0); PG8_BAR; PG8_MMA(1, 0, At, B0); PG8_MMA(1, 1, At, B1); PG8_BAR; PG8_SCHED;
;             PG8_LDB(B0, 1, 0); PG8_LDB(B1, 1, 1); PG8_SCHED; PG8_LDA(At, 1, 0); PG8_STAGE(PG8_SA(0, 1), a2 + hstep, voffA);
;             PG8_WAIT_V(8); PG8_WAIT_L(0); PG8_BAR; PG8_MMA(0, 0, At, B0); PG8_MMA(0, 1, At, B1); PG8_BAR; PG8_SCHED;
	v_mfma_f32_16x16x32_bf16 v[62:65], v[130:133], v[162:165], v[62:65]
	v_mfma_f32_16x16x32_bf16 v[58:61], v[138:141], v[162:165], v[58:61]
	v_mfma_f32_16x16x32_bf16 v[50:53], v[130:133], v[170:173], v[50:53]
	v_mfma_f32_16x16x32_bf16 v[42:45], v[138:141], v[170:173], v[42:45]
	v_mfma_f32_16x16x32_bf16 v[34:37], v[130:133], v[178:181], v[34:37]
	v_mfma_f32_16x16x32_bf16 v[26:29], v[138:141], v[178:181], v[26:29]
	v_mfma_f32_16x16x32_bf16 v[18:21], v[130:133], v[210:213], v[18:21]
	v_mfma_f32_16x16x32_bf16 v[10:13], v[138:141], v[210:213], v[10:13]
	v_mfma_f32_16x16x32_bf16 v[62:65], v[134:137], v[166:169], v[62:65]
	v_mfma_f32_16x16x32_bf16 v[58:61], v[142:145], v[166:169], v[58:61]
	v_mfma_f32_16x16x32_bf16 v[50:53], v[134:137], v[174:177], v[50:53]
	v_mfma_f32_16x16x32_bf16 v[42:45], v[142:145], v[174:177], v[42:45]
	v_mfma_f32_16x16x32_bf16 v[34:37], v[134:137], v[206:209], v[34:37]
	v_mfma_f32_16x16x32_bf16 v[26:29], v[142:145], v[206:209], v[26:29]
	v_mfma_f32_16x16x32_bf16 v[18:21], v[134:137], v[214:217], v[18:21]
	v_mfma_f32_16x16x32_bf16 v[10:13], v[142:145], v[214:217], v[10:13]
	s_setprio 0
	s_setprio 1
	v_mfma_f32_16x16x32_bf16 v[54:57], v[146:149], v[162:165], v[54:57]
	v_mfma_f32_16x16x32_bf16 v[46:49], v[154:157], v[162:165], v[46:49]
	v_mfma_f32_16x16x32_bf16 v[38:41], v[146:149], v[170:173], v[38:41]
	v_mfma_f32_16x16x32_bf16 v[30:33], v[154:157], v[170:173], v[30:33]
	v_mfma_f32_16x16x32_bf16 v[22:25], v[146:149], v[178:181], v[22:25]
	v_mfma_f32_16x16x32_bf16 v[14:17], v[154:157], v[178:181], v[14:17]
	v_mfma_f32_16x16x32_bf16 v[6:9], v[146:149], v[210:213], v[6:9]
	v_mfma_f32_16x16x32_bf16 v[2:5], v[154:157], v[210:213], v[2:5]
	v_mfma_f32_16x16x32_bf16 v[54:57], v[150:153], v[166:169], v[54:57]
	v_mfma_f32_16x16x32_bf16 v[46:49], v[158:161], v[166:169], v[46:49]
	v_mfma_f32_16x16x32_bf16 v[38:41], v[150:153], v[174:177], v[38:41]
	v_mfma_f32_16x16x32_bf16 v[30:33], v[158:161], v[174:177], v[30:33]
	v_mfma_f32_16x16x32_bf16 v[22:25], v[150:153], v[206:209], v[22:25]
	v_mfma_f32_16x16x32_bf16 v[14:17], v[158:161], v[206:209], v[14:17]
	v_mfma_f32_16x16x32_bf16 v[6:9], v[150:153], v[214:217], v[6:9]
	v_mfma_f32_16x16x32_bf16 v[2:5], v[158:161], v[214:217], v[2:5]
	s_setprio 0
	s_barrier
	s_add_i32 s55, 0, 0x18000
	s_add_i32 s56, 0, 0x1c000
	v_add_u32_e32 v142, s55, v201
	v_add_u32_e32 v158, s56, v201
	ds_read_b128 v[130:133], v142
	ds_read_b128 v[134:137], v142 offset:1024
	ds_read_b128 v[138:141], v142 offset:2048
	ds_read_b128 v[142:145], v142 offset:3072
	ds_read_b128 v[146:149], v158
	ds_read_b128 v[150:153], v158 offset:1024
	ds_read_b128 v[154:157], v158 offset:2048
	ds_read_b128 v[158:161], v158 offset:3072
	s_add_u32 s24, s24, 0x80000
	s_addc_u32 s25, s25, 0
	s_mov_b32 m0, s31
	v_lshl_add_u64 v[224:225], s[24:25], 0, v[182:183]
	ds_read_b128 v[162:165], v205 offset:32768
	ds_read_b128 v[166:169], v205 offset:33792
	ds_read_b128 v[170:173], v205 offset:34816
	ds_read_b128 v[174:177], v205 offset:35840
	ds_read_b128 v[178:181], v205 offset:36864
	ds_read_b128 v[206:209], v205 offset:37888
	ds_read_b128 v[210:213], v205 offset:38912
	ds_read_b128 v[214:217], v205 offset:39936
	global_load_lds_dwordx4 v[224:225], off
	v_lshl_add_u64 v[224:225], s[24:25], 0, v[186:187]
	s_mov_b32 m0, s33
	s_nop 0
	global_load_lds_dwordx4 v[224:225], off
	s_waitcnt vmcnt(8)
	s_waitcnt lgkmcnt(0)
	s_setprio 1
	s_barrier
	v_mfma_f32_16x16x32_bf16 v[126:129], v[130:133], v[162:165], v[126:129]
	v_mfma_f32_16x16x32_bf16 v[122:125], v[138:141], v[162:165], v[122:125]
	v_mfma_f32_16x16x32_bf16 v[114:117], v[130:133], v[170:173], v[114:117]
	v_mfma_f32_16x16x32_bf16 v[106:109], v[138:141], v[170:173], v[106:109]
	v_mfma_f32_16x16x32_bf16 v[98:101], v[130:133], v[178:181], v[98:101]
	v_mfma_f32_16x16x32_bf16 v[90:93], v[138:141], v[178:181], v[90:93]
	v_mfma_f32_16x16x32_bf16 v[82:85], v[130:133], v[210:213], v[82:85]
	v_mfma_f32_16x16x32_bf16 v[74:77], v[138:141], v[210:213], v[74:77]
	v_mfma_f32_16x16x32_bf16 v[126:129], v[134:137], v[166:169], v[126:129]
	v_mfma_f32_16x16x32_bf16 v[122:125], v[142:145], v[166:169], v[122:125]
	v_mfma_f32_16x16x32_bf16 v[114:117], v[134:137], v[174:177], v[114:117]
	v_mfma_f32_16x16x32_bf16 v[106:109], v[142:145], v[174:177], v[106:109]
	v_mfma_f32_16x16x32_bf16 v[98:101], v[134:137], v[206:209], v[98:101]
	v_mfma_f32_16x16x32_bf16 v[90:93], v[142:145], v[206:209], v[90:93]
	v_mfma_f32_16x16x32_bf16 v[82:85], v[134:137], v[214:217], v[82:85]
	v_mfma_f32_16x16x32_bf16 v[74:77], v[142:145], v[214:217], v[74:77]
	s_setprio 0
	s_setprio 1
	v_mfma_f32_16x16x32_bf16 v[118:121], v[146:149], v[162:165], v[118:121]
	v_mfma_f32_16x16x32_bf16 v[110:113], v[154:157], v[162:165], v[110:113]
	v_mfma_f32_16x16x32_bf16 v[102:105], v[146:149], v[170:173], v[102:105]
	v_mfma_f32_16x16x32_bf16 v[94:97], v[154:157], v[170:173], v[94:97]
	v_mfma_f32_16x16x32_bf16 v[86:89], v[146:149], v[178:181], v[86:89]
	v_mfma_f32_16x16x32_bf16 v[78:81], v[154:157], v[178:181], v[78:81]
	v_mfma_f32_16x16x32_bf16 v[70:73], v[146:149], v[210:213], v[70:73]
	v_mfma_f32_16x16x32_bf16 v[66:69], v[154:157], v[210:213], v[66:69]
	v_mfma_f32_16x16x32_bf16 v[118:121], v[150:153], v[166:169], v[118:121]
	v_mfma_f32_16x16x32_bf16 v[110:113], v[158:161], v[166:169], v[110:113]
	v_mfma_f32_16x16x32_bf16 v[102:105], v[150:153], v[174:177], v[102:105]
	v_mfma_f32_16x16x32_bf16 v[94:97], v[158:161], v[174:177], v[94:97]
	v_mfma_f32_16x16x32_bf16 v[86:89], v[150:153], v[206:209], v[86:89]
	v_mfma_f32_16x16x32_bf16 v[78:81], v[158:161], v[206:209], v[78:81]
	v_mfma_f32_16x16x32_bf16 v[70:73], v[150:153], v[214:217], v[70:73]
	v_mfma_f32_16x16x32_bf16 v[66:69], v[158:161], v[214:217], v[66:69]
	s_setprio 0
	s_barrier
; #define PG8_STAGE(bufoff, gbase, voff) do { _Pragma("unroll") for (int _i = 0; _i < 2; ++_i) \
;         __builtin_amdgcn_global_load_lds((const unsigned*)((const char*)(gbase) + (voff)[_i]), (PG8_LAS unsigned*)(lds + (bufoff) + ldsw + _i * 8192), 16, 0, 0); } while (0)
; #define PG8_WAIT_V(n) asm volatile("s_waitcnt vmcnt(" #n ")" ::: "memory")
; #define PG8_WAIT_L(n) asm volatile("s_waitcnt lgkmcnt(" #n ")" ::: "memory")
; #define PG8_BAR __builtin_amdgcn_s_barrier()
; #define PG8_SCHED __builtin_amdgcn_sched_barrier(0)
; template <class Epi, class Sched, bool ALIGN_EPI = true, bool SP2 = true>
; __device__ __forceinline__ void gemm_phase(PG8_LAS unsigned char* lds, const int K  , const Sched& S, const Epi& E) {
;     ...
;             PG8_LDA(At, 1, 1); PG8_STAGE(PG8_SB(1, 0), b3, voffB); PG8_STAGE(PG8_SB(1, 1), b3 + hstep, voffB); PG8_STAGE(PG8_SA(1, 0), a3, voffA);
;             PG8_WAIT_V(8); PG8_WAIT_L(0); PG8_BAR; PG8_MMA(1, 0, At, B0); PG8_MMA(1, 1, At, B1); PG8_BAR; PG8_SCHED;
;     ...
;         if constexpr (ALIGN_EPI) { if (wr == 0) PG8_BAR; }
	s_add_i32 s24, s55, s29
	v_lshl_add_u64 v[198:199], v[198:199], 0, s[6:7]
	s_mov_b32 m0, s24
	ds_read_b128 v[162:165], v205 offset:49152
	ds_read_b128 v[166:169], v205 offset:50176
	ds_read_b128 v[170:173], v205 offset:51200
	ds_read_b128 v[174:177], v205 offset:52224
	ds_read_b128 v[178:181], v205 offset:53248
	ds_read_b128 v[206:209], v205 offset:54272
	ds_read_b128 v[210:213], v205 offset:55296
	ds_read_b128 v[214:217], v205 offset:56320
	global_load_lds_dwordx4 v[198:199], off
	s_add_i32 m0, s24, 0x2000
	s_add_u32 s22, s22, 0x80080
	v_lshl_add_u64 v[198:199], v[218:219], 0, s[6:7]
	s_addc_u32 s23, s23, 0
	s_add_i32 s24, s56, s29
	global_load_lds_dwordx4 v[198:199], off
	v_lshl_add_u64 v[198:199], s[22:23], 0, v[184:185]
	s_mov_b32 m0, s24
	s_nop 0
	global_load_lds_dwordx4 v[198:199], off
	v_lshl_add_u64 v[198:199], s[22:23], 0, v[188:189]
	s_add_i32 m0, s24, 0x2000
	s_nop 0
	global_load_lds_dwordx4 v[198:199], off
	v_lshl_add_u64 v[198:199], v[220:221], 0, s[6:7]
	s_mov_b32 m0, s38
	s_nop 0
	global_load_lds_dwordx4 v[198:199], off
	v_lshl_add_u64 v[198:199], v[222:223], 0, s[6:7]
	s_mov_b32 m0, s39
	s_nop 0
	global_load_lds_dwordx4 v[198:199], off
	s_waitcnt vmcnt(8)
	s_waitcnt lgkmcnt(0)
	s_setprio 1
	s_barrier
	v_mfma_f32_16x16x32_bf16 v[62:65], v[130:133], v[162:165], v[62:65]
	v_mfma_f32_16x16x32_bf16 v[58:61], v[138:141], v[162:165], v[58:61]
	v_mfma_f32_16x16x32_bf16 v[50:53], v[130:133], v[170:173], v[50:53]
	v_mfma_f32_16x16x32_bf16 v[42:45], v[138:141], v[170:173], v[42:45]
	v_mfma_f32_16x16x32_bf16 v[34:37], v[130:133], v[178:181], v[34:37]
	v_mfma_f32_16x16x32_bf16 v[26:29], v[138:141], v[178:181], v[26:29]
	v_mfma_f32_16x16x32_bf16 v[18:21], v[130:133], v[210:213], v[18:21]
	v_mfma_f32_16x16x32_bf16 v[10:13], v[138:141], v[210:213], v[10:13]
	v_mfma_f32_16x16x32_bf16 v[62:65], v[134:137], v[166:169], v[62:65]
	v_mfma_f32_16x16x32_bf16 v[58:61], v[142:145], v[166:169], v[58:61]
	v_mfma_f32_16x16x32_bf16 v[50:53], v[134:137], v[174:177], v[50:53]
	v_mfma_f32_16x16x32_bf16 v[42:45], v[142:145], v[174:177], v[42:45]
	v_mfma_f32_16x16x32_bf16 v[34:37], v[134:137], v[206:209], v[34:37]
	v_mfma_f32_16x16x32_bf16 v[26:29], v[142:145], v[206:209], v[26:29]
	v_mfma_f32_16x16x32_bf16 v[18:21], v[134:137], v[214:217], v[18:21]
	v_mfma_f32_16x16x32_bf16 v[10:13], v[142:145], v[214:217], v[10:13]
	s_setprio 0
	s_setprio 1
	v_mfma_f32_16x16x32_bf16 v[54:57], v[146:149], v[162:165], v[54:57]
	v_mfma_f32_16x16x32_bf16 v[46:49], v[154:157], v[162:165], v[46:49]
	v_mfma_f32_16x16x32_bf16 v[38:41], v[146:149], v[170:173], v[38:41]
	v_mfma_f32_16x16x32_bf16 v[30:33], v[154:157], v[170:173], v[30:33]
	v_mfma_f32_16x16x32_bf16 v[22:25], v[146:149], v[178:181], v[22:25]
	v_mfma_f32_16x16x32_bf16 v[14:17], v[154:157], v[178:181], v[14:17]
	v_mfma_f32_16x16x32_bf16 v[6:9], v[146:149], v[210:213], v[6:9]
	v_mfma_f32_16x16x32_bf16 v[2:5], v[154:157], v[210:213], v[2:5]
	v_mfma_f32_16x16x32_bf16 v[54:57], v[150:153], v[166:169], v[54:57]
	v_mfma_f32_16x16x32_bf16 v[46:49], v[158:161], v[166:169], v[46:49]
	v_mfma_f32_16x16x32_bf16 v[38:41], v[150:153], v[174:177], v[38:41]
	v_mfma_f32_16x16x32_bf16 v[30:33], v[158:161], v[174:177], v[30:33]
	v_mfma_f32_16x16x32_bf16 v[22:25], v[150:153], v[206:209], v[22:25]
	v_mfma_f32_16x16x32_bf16 v[14:17], v[158:161], v[206:209], v[14:17]
	v_mfma_f32_16x16x32_bf16 v[6:9], v[150:153], v[214:217], v[6:9]
	v_mfma_f32_16x16x32_bf16 v[2:5], v[158:161], v[214:217], v[2:5]
	s_setprio 0
	s_barrier
	s_add_i32 s54, s54, 2
	s_add_u32 s20, s20, 0x100
	s_addc_u32 s21, s21, 0
	s_add_u32 s52, s52, 0x100
	s_addc_u32 s53, s53, 0
	s_cmp_gt_u32 s54, 29
	s_cbranch_scc0 .LBB0_2296
	s_and_b64 vcc, exec, s[8:9]
	s_cbranch_vccz .LBB0_2299
	s_barrier

; #define PG8_STAGE(bufoff, gbase, voff) do { _Pragma("unroll") for (int _i = 0; _i < 2; ++_i) \
;         __builtin_amdgcn_global_load_lds((const unsigned*)((const char*)(gbase) + (voff)[_i]), (PG8_LAS unsigned*)(lds + (bufoff) + ldsw + _i * 8192), 16, 0, 0); } while (0)
; #define PG8_WAIT_V(n) asm volatile("s_waitcnt vmcnt(" #n ")" ::: "memory")
; #define PG8_WAIT_L(n) asm volatile("s_waitcnt lgkmcnt(" #n ")" ::: "memory")
; #define PG8_BAR __builtin_amdgcn_s_barrier()
; #define PG8_SCHED __builtin_amdgcn_sched_barrier(0)
;     __device__ __forceinline__ int nt(const pg8::Unit& u) const { return u.kind == 0 ? ntiles : q_nt(u.kind - 1); }
; template <class Epi, class Sched, bool ALIGN_EPI = true, bool SP2 = true>
; __device__ __forceinline__ void gemm_phase(PG8_LAS unsigned char* lds, const int K  , const Sched& S, const Epi& E) {
;     ...
;             const bool last = (t == nt - 2);
;             const char* a1 = cA + (size_t)(t + 1) * kstep;
;             const char* a2 = last ? nA : cA + (size_t)(t + 2) * kstep; const char* b2 = last ? nB : cB + (size_t)(t + 2) * kstep;
;             const char* a3 = a2 + kstep; const char* b3 = b2 + kstep;
;             if constexpr (SP2) {
;             PG8_LDB(B0, 0, 0); PG8_LDB(B1, 0, 1); PG8_SCHED; PG8_LDA(At, 0, 0); PG8_STAGE(PG8_SA(1, 1), a1 + hstep, voffA);
;             PG8_WAIT_V(8); PG8_WAIT_L(0); PG8_BAR; PG8_MMA(0, 0, At, B0); PG8_MMA(0, 1, At, B1); PG8_BAR; PG8_SCHED;
;             PG8_LDA(At, 0, 1); PG8_STAGE(PG8_SB(0, 0), b2, voffB); PG8_STAGE(PG8_SB(0, 1), b2 + hstep, voffB); PG8_STAGE(PG8_SA(0, 0), a2, voffA);
;             PG8_WAIT_V(8); PG8_WAIT_L(0); PG8_BAR; PG8_MMA(1, 0, At, B0); PG8_MMA(1, 1, At, B1); PG8_BAR; PG8_SCHED;
.LBB0_2433:
	ds_read_b128 v[146:149], v152
	ds_read_b128 v[158:161], v152 offset:1024
	ds_read_b128 v[162:165], v152 offset:2048
	ds_read_b128 v[166:169], v152 offset:3072
	ds_read_b128 v[170:173], v153
	ds_read_b128 v[174:177], v153 offset:1024
	ds_read_b128 v[178:181], v153 offset:2048
	ds_read_b128 v[182:185], v153 offset:3072
	s_add_u32 s22, s20, 0xfff80080
	s_addc_u32 s23, s21, -1
	s_cmp_eq_u32 s48, 28
	s_cselect_b32 s25, s13, s23
	s_cselect_b32 s24, s44, s22
	s_cselect_b32 s23, s11, s47
	s_cselect_b32 s22, s45, s46
	v_lshl_add_u64 v[218:219], s[20:21], 0, v[138:139]
	s_add_i32 m0, s19, 0xc000
	ds_read_b128 v[186:189], v154
	ds_read_b128 v[190:193], v154 offset:1024
	ds_read_b128 v[194:197], v154 offset:2048
	ds_read_b128 v[198:201], v154 offset:3072
	ds_read_b128 v[202:205], v154 offset:4096
	ds_read_b128 v[206:209], v154 offset:5120
	ds_read_b128 v[210:213], v154 offset:6144
	ds_read_b128 v[214:217], v154 offset:7168
	global_load_lds_dwordx4 v[218:219], off
	v_lshl_add_u64 v[218:219], s[20:21], 0, v[140:141]
	s_add_i32 m0, s19, 0xe000
	s_nop 0
	global_load_lds_dwordx4 v[218:219], off
	s_waitcnt vmcnt(8)
	s_waitcnt lgkmcnt(0)
	s_setprio 1
	s_barrier
	v_mfma_f32_16x16x32_bf16 v[126:129], v[146:149], v[186:189], v[126:129]
	v_mfma_f32_16x16x32_bf16 v[118:121], v[162:165], v[186:189], v[118:121]
	v_mfma_f32_16x16x32_bf16 v[110:113], v[146:149], v[194:197], v[110:113]
	v_mfma_f32_16x16x32_bf16 v[102:105], v[162:165], v[194:197], v[102:105]
	v_mfma_f32_16x16x32_bf16 v[94:97], v[146:149], v[202:205], v[94:97]
	v_mfma_f32_16x16x32_bf16 v[86:89], v[162:165], v[202:205], v[86:89]
	v_mfma_f32_16x16x32_bf16 v[78:81], v[146:149], v[210:213], v[78:81]
	v_mfma_f32_16x16x32_bf16 v[70:73], v[162:165], v[210:213], v[70:73]
	v_mfma_f32_16x16x32_bf16 v[126:129], v[158:161], v[190:193], v[126:129]
	v_mfma_f32_16x16x32_bf16 v[118:121], v[166:169], v[190:193], v[118:121]
	v_mfma_f32_16x16x32_bf16 v[110:113], v[158:161], v[198:201], v[110:113]
	v_mfma_f32_16x16x32_bf16 v[102:105], v[166:169], v[198:201], v[102:105]
	v_mfma_f32_16x16x32_bf16 v[94:97], v[158:161], v[206:209], v[94:97]
	v_mfma_f32_16x16x32_bf16 v[86:89], v[166:169], v[206:209], v[86:89]
	v_mfma_f32_16x16x32_bf16 v[78:81], v[158:161], v[214:217], v[78:81]
	v_mfma_f32_16x16x32_bf16 v[70:73], v[166:169], v[214:217], v[70:73]
	s_setprio 0
	s_setprio 1
	v_mfma_f32_16x16x32_bf16 v[122:125], v[170:173], v[186:189], v[122:125]
	v_mfma_f32_16x16x32_bf16 v[114:117], v[178:181], v[186:189], v[114:117]
	v_mfma_f32_16x16x32_bf16 v[106:109], v[170:173], v[194:197], v[106:109]
	v_mfma_f32_16x16x32_bf16 v[98:101], v[178:181], v[194:197], v[98:101]
	v_mfma_f32_16x16x32_bf16 v[90:93], v[170:173], v[202:205], v[90:93]
	v_mfma_f32_16x16x32_bf16 v[82:85], v[178:181], v[202:205], v[82:85]
	v_mfma_f32_16x16x32_bf16 v[74:77], v[170:173], v[210:213], v[74:77]
	v_mfma_f32_16x16x32_bf16 v[66:69], v[178:181], v[210:213], v[66:69]
	v_mfma_f32_16x16x32_bf16 v[122:125], v[174:177], v[190:193], v[122:125]
	v_mfma_f32_16x16x32_bf16 v[114:117], v[182:185], v[190:193], v[114:117]
	v_mfma_f32_16x16x32_bf16 v[106:109], v[174:177], v[198:201], v[106:109]
	v_mfma_f32_16x16x32_bf16 v[98:101], v[182:185], v[198:201], v[98:101]
	v_mfma_f32_16x16x32_bf16 v[90:93], v[174:177], v[206:209], v[90:93]
	v_mfma_f32_16x16x32_bf16 v[82:85], v[182:185], v[206:209], v[82:85]
	v_mfma_f32_16x16x32_bf16 v[74:77], v[174:177], v[214:217], v[74:77]
	v_mfma_f32_16x16x32_bf16 v[66:69], v[182:185], v[214:217], v[66:69]
	s_setprio 0
	s_barrier
	s_add_i32 s49, s39, s28
	v_lshl_add_u64 v[218:219], s[22:23], 0, v[134:135]
	s_mov_b32 m0, s49
	ds_read_b128 v[186:189], v154 offset:16384
	ds_read_b128 v[190:193], v154 offset:17408
	ds_read_b128 v[194:197], v154 offset:18432
	ds_read_b128 v[198:201], v154 offset:19456
	ds_read_b128 v[202:205], v154 offset:20480
	ds_read_b128 v[206:209], v154 offset:21504
	ds_read_b128 v[210:213], v154 offset:22528
	ds_read_b128 v[214:217], v154 offset:23552
	global_load_lds_dwordx4 v[218:219], off
	s_add_i32 m0, s49, 0x2000
	s_add_u32 s50, s22, 0x80000
	v_lshl_add_u64 v[220:221], s[22:23], 0, v[130:131]
	s_addc_u32 s51, s23, 0
	s_add_i32 s49, s40, s28
	global_load_lds_dwordx4 v[220:221], off
	v_lshl_add_u64 v[222:223], s[50:51], 0, v[134:135]
	s_mov_b32 m0, s49
	v_lshl_add_u64 v[224:225], s[24:25], 0, v[132:133]
	global_load_lds_dwordx4 v[222:223], off
	v_lshl_add_u64 v[222:223], s[50:51], 0, v[130:131]
	s_add_i32 m0, s49, 0x2000
	s_nop 0
	global_load_lds_dwordx4 v[222:223], off
	v_lshl_add_u64 v[222:223], s[24:25], 0, v[136:137]
	s_mov_b32 m0, s19
	s_nop 0
	global_load_lds_dwordx4 v[222:223], off
	s_mov_b32 m0, s31
	s_nop 0
	global_load_lds_dwordx4 v[224:225], off
	s_waitcnt vmcnt(8)
	s_waitcnt lgkmcnt(0)
	s_setprio 1
	s_barrier
; #define PG8_STAGE(bufoff, gbase, voff) do { _Pragma("unroll") for (int _i = 0; _i < 2; ++_i) \
;         __builtin_amdgcn_global_load_lds((const unsigned*)((const char*)(gbase) + (voff)[_i]), (PG8_LAS unsigned*)(lds + (bufoff) + ldsw + _i * 8192), 16, 0, 0); } while (0)
; #define PG8_WAIT_V(n) asm volatile("s_waitcnt vmcnt(" #n ")" ::: "memory")
; #define PG8_WAIT_L(n) asm volatile("s_waitcnt lgkmcnt(" #n ")" ::: "memory")
; #define PG8_BAR __builtin_amdgcn_s_barrier()
; #define PG8_SCHED __builtin_amdgcn_sched_barrier(0)
; template <class Epi, class Sched, bool ALIGN_EPI = true, bool SP2 = true>
; __device__ __forceinline__ void gemm_phase(PG8_LAS unsigned char* lds, const int K  , const Sched& S, const Epi& E) {
;     ...
;             PG8_WAIT_V(8); PG8_WAIT_L(0); PG8_BAR; PG8_MMA(1, 0, At, B0); PG8_MMA(1, 1, At, B1); PG8_BAR; PG8_SCHED;
;             PG8_LDB(B0, 1, 0); PG8_LDB(B1, 1, 1); PG8_SCHED; PG8_LDA(At, 1, 0); PG8_STAGE(PG8_SA(0, 1), a2 + hstep, voffA);
;             PG8_WAIT_V(8); PG8_WAIT_L(0); PG8_BAR; PG8_MMA(0, 0, At, B0); PG8_MMA(0, 1, At, B1); PG8_BAR; PG8_SCHED;
	v_mfma_f32_16x16x32_bf16 v[62:65], v[146:149], v[186:189], v[62:65]
	v_mfma_f32_16x16x32_bf16 v[54:57], v[162:165], v[186:189], v[54:57]
	v_mfma_f32_16x16x32_bf16 v[46:49], v[146:149], v[194:197], v[46:49]
	v_mfma_f32_16x16x32_bf16 v[38:41], v[162:165], v[194:197], v[38:41]
	v_mfma_f32_16x16x32_bf16 v[30:33], v[146:149], v[202:205], v[30:33]
	v_mfma_f32_16x16x32_bf16 v[22:25], v[162:165], v[202:205], v[22:25]
	v_mfma_f32_16x16x32_bf16 v[14:17], v[146:149], v[210:213], v[14:17]
	v_mfma_f32_16x16x32_bf16 v[6:9], v[162:165], v[210:213], v[6:9]
	v_mfma_f32_16x16x32_bf16 v[62:65], v[158:161], v[190:193], v[62:65]
	v_mfma_f32_16x16x32_bf16 v[54:57], v[166:169], v[190:193], v[54:57]
	v_mfma_f32_16x16x32_bf16 v[46:49], v[158:161], v[198:201], v[46:49]
	v_mfma_f32_16x16x32_bf16 v[38:41], v[166:169], v[198:201], v[38:41]
	v_mfma_f32_16x16x32_bf16 v[30:33], v[158:161], v[206:209], v[30:33]
	v_mfma_f32_16x16x32_bf16 v[22:25], v[166:169], v[206:209], v[22:25]
	v_mfma_f32_16x16x32_bf16 v[14:17], v[158:161], v[214:217], v[14:17]
	v_mfma_f32_16x16x32_bf16 v[6:9], v[166:169], v[214:217], v[6:9]
	s_setprio 0
	s_setprio 1
	v_mfma_f32_16x16x32_bf16 v[58:61], v[170:173], v[186:189], v[58:61]
	v_mfma_f32_16x16x32_bf16 v[50:53], v[178:181], v[186:189], v[50:53]
	v_mfma_f32_16x16x32_bf16 v[42:45], v[170:173], v[194:197], v[42:45]
	v_mfma_f32_16x16x32_bf16 v[34:37], v[178:181], v[194:197], v[34:37]
	v_mfma_f32_16x16x32_bf16 v[26:29], v[170:173], v[202:205], v[26:29]
	v_mfma_f32_16x16x32_bf16 v[18:21], v[178:181], v[202:205], v[18:21]
	v_mfma_f32_16x16x32_bf16 v[10:13], v[170:173], v[210:213], v[10:13]
	v_mfma_f32_16x16x32_bf16 v[2:5], v[178:181], v[210:213], v[2:5]
	v_mfma_f32_16x16x32_bf16 v[58:61], v[174:177], v[190:193], v[58:61]
	v_mfma_f32_16x16x32_bf16 v[50:53], v[182:185], v[190:193], v[50:53]
	v_mfma_f32_16x16x32_bf16 v[42:45], v[174:177], v[198:201], v[42:45]
	v_mfma_f32_16x16x32_bf16 v[34:37], v[182:185], v[198:201], v[34:37]
	v_mfma_f32_16x16x32_bf16 v[26:29], v[174:177], v[206:209], v[26:29]
	v_mfma_f32_16x16x32_bf16 v[18:21], v[182:185], v[206:209], v[18:21]
	v_mfma_f32_16x16x32_bf16 v[10:13], v[174:177], v[214:217], v[10:13]
	v_mfma_f32_16x16x32_bf16 v[2:5], v[182:185], v[214:217], v[2:5]
	s_setprio 0
	s_barrier
	s_add_i32 s49, 0, 0x18000
	v_add_u32_e32 v157, s49, v150
	s_add_i32 s50, 0, 0x1c000
	ds_read_b128 v[146:149], v157
	ds_read_b128 v[158:161], v157 offset:1024
	ds_read_b128 v[162:165], v157 offset:2048
	ds_read_b128 v[166:169], v157 offset:3072
	v_add_u32_e32 v157, s50, v150
	ds_read_b128 v[170:173], v157
	ds_read_b128 v[174:177], v157 offset:1024
	ds_read_b128 v[178:181], v157 offset:2048
	ds_read_b128 v[182:185], v157 offset:3072
	s_add_u32 s24, s24, 0x80000
	s_addc_u32 s25, s25, 0
	s_mov_b32 m0, s33
	v_lshl_add_u64 v[226:227], s[24:25], 0, v[136:137]
	ds_read_b128 v[186:189], v154 offset:32768
	ds_read_b128 v[190:193], v154 offset:33792
	ds_read_b128 v[194:197], v154 offset:34816
	ds_read_b128 v[198:201], v154 offset:35840
	ds_read_b128 v[202:205], v154 offset:36864
	ds_read_b128 v[206:209], v154 offset:37888
	ds_read_b128 v[210:213], v154 offset:38912
	ds_read_b128 v[214:217], v154 offset:39936
	global_load_lds_dwordx4 v[226:227], off
	v_lshl_add_u64 v[226:227], s[24:25], 0, v[132:133]
	s_mov_b32 m0, s34
	s_nop 0
	global_load_lds_dwordx4 v[226:227], off
	s_waitcnt vmcnt(8)
	s_waitcnt lgkmcnt(0)
	s_setprio 1
	s_barrier
	v_mfma_f32_16x16x32_bf16 v[126:129], v[146:149], v[186:189], v[126:129]
	v_mfma_f32_16x16x32_bf16 v[118:121], v[162:165], v[186:189], v[118:121]
	v_mfma_f32_16x16x32_bf16 v[110:113], v[146:149], v[194:197], v[110:113]
	v_mfma_f32_16x16x32_bf16 v[102:105], v[162:165], v[194:197], v[102:105]
	v_mfma_f32_16x16x32_bf16 v[94:97], v[146:149], v[202:205], v[94:97]
	v_mfma_f32_16x16x32_bf16 v[86:89], v[162:165], v[202:205], v[86:89]
	v_mfma_f32_16x16x32_bf16 v[78:81], v[146:149], v[210:213], v[78:81]
	v_mfma_f32_16x16x32_bf16 v[70:73], v[162:165], v[210:213], v[70:73]
	v_mfma_f32_16x16x32_bf16 v[126:129], v[158:161], v[190:193], v[126:129]
	v_mfma_f32_16x16x32_bf16 v[118:121], v[166:169], v[190:193], v[118:121]
	v_mfma_f32_16x16x32_bf16 v[110:113], v[158:161], v[198:201], v[110:113]
	v_mfma_f32_16x16x32_bf16 v[102:105], v[166:169], v[198:201], v[102:105]
	v_mfma_f32_16x16x32_bf16 v[94:97], v[158:161], v[206:209], v[94:97]
	v_mfma_f32_16x16x32_bf16 v[86:89], v[166:169], v[206:209], v[86:89]
	v_mfma_f32_16x16x32_bf16 v[78:81], v[158:161], v[214:217], v[78:81]
	v_mfma_f32_16x16x32_bf16 v[70:73], v[166:169], v[214:217], v[70:73]
	s_setprio 0
	s_setprio 1
	v_mfma_f32_16x16x32_bf16 v[122:125], v[170:173], v[186:189], v[122:125]
	v_mfma_f32_16x16x32_bf16 v[114:117], v[178:181], v[186:189], v[114:117]
	v_mfma_f32_16x16x32_bf16 v[106:109], v[170:173], v[194:197], v[106:109]
	v_mfma_f32_16x16x32_bf16 v[98:101], v[178:181], v[194:197], v[98:101]
	v_mfma_f32_16x16x32_bf16 v[90:93], v[170:173], v[202:205], v[90:93]
	v_mfma_f32_16x16x32_bf16 v[82:85], v[178:181], v[202:205], v[82:85]
	v_mfma_f32_16x16x32_bf16 v[74:77], v[170:173], v[210:213], v[74:77]
	v_mfma_f32_16x16x32_bf16 v[66:69], v[178:181], v[210:213], v[66:69]
	v_mfma_f32_16x16x32_bf16 v[122:125], v[174:177], v[190:193], v[122:125]
	v_mfma_f32_16x16x32_bf16 v[114:117], v[182:185], v[190:193], v[114:117]
	v_mfma_f32_16x16x32_bf16 v[106:109], v[174:177], v[198:201], v[106:109]
	v_mfma_f32_16x16x32_bf16 v[98:101], v[182:185], v[198:201], v[98:101]
	v_mfma_f32_16x16x32_bf16 v[90:93], v[174:177], v[206:209], v[90:93]
	v_mfma_f32_16x16x32_bf16 v[82:85], v[182:185], v[206:209], v[82:85]
	v_mfma_f32_16x16x32_bf16 v[74:77], v[174:177], v[214:217], v[74:77]
	v_mfma_f32_16x16x32_bf16 v[66:69], v[182:185], v[214:217], v[66:69]
	s_setprio 0
	s_barrier
; #define PG8_STAGE(bufoff, gbase, voff) do { _Pragma("unroll") for (int _i = 0; _i < 2; ++_i) \
;         __builtin_amdgcn_global_load_lds((const unsigned*)((const char*)(gbase) + (voff)[_i]), (PG8_LAS unsigned*)(lds + (bufoff) + ldsw + _i * 8192), 16, 0, 0); } while (0)
; #define PG8_WAIT_V(n) asm volatile("s_waitcnt vmcnt(" #n ")" ::: "memory")
; #define PG8_WAIT_L(n) asm volatile("s_waitcnt lgkmcnt(" #n ")" ::: "memory")
; #define PG8_BAR __builtin_amdgcn_s_barrier()
; #define PG8_SCHED __builtin_amdgcn_sched_barrier(0)
; template <class Epi, class Sched, bool ALIGN_EPI = true, bool SP2 = true>
; __device__ __forceinline__ void gemm_phase(PG8_LAS unsigned char* lds, const int K  , const Sched& S, const Epi& E) {
;     ...
;             PG8_LDA(At, 1, 1); PG8_STAGE(PG8_SB(1, 0), b3, voffB); PG8_STAGE(PG8_SB(1, 1), b3 + hstep, voffB); PG8_STAGE(PG8_SA(1, 0), a3, voffA);
;             PG8_WAIT_V(8); PG8_WAIT_L(0); PG8_BAR; PG8_MMA(1, 0, At, B0); PG8_MMA(1, 1, At, B1); PG8_BAR; PG8_SCHED;
;     ...
;         if constexpr (ALIGN_EPI) { if (wr == 0) PG8_BAR; }
	s_add_i32 s24, s49, s28
	v_lshl_add_u64 v[218:219], v[218:219], 0, s[6:7]
	s_mov_b32 m0, s24
	ds_read_b128 v[186:189], v154 offset:49152
	ds_read_b128 v[190:193], v154 offset:50176
	ds_read_b128 v[194:197], v154 offset:51200
	ds_read_b128 v[198:201], v154 offset:52224
	ds_read_b128 v[202:205], v154 offset:53248
	ds_read_b128 v[206:209], v154 offset:54272
	ds_read_b128 v[210:213], v154 offset:55296
	ds_read_b128 v[214:217], v154 offset:56320
	global_load_lds_dwordx4 v[218:219], off
	s_add_i32 m0, s24, 0x2000
	s_add_u32 s22, s22, 0x80080
	v_lshl_add_u64 v[218:219], v[220:221], 0, s[6:7]
	s_addc_u32 s23, s23, 0
	s_add_i32 s24, s50, s28
	global_load_lds_dwordx4 v[218:219], off
	v_lshl_add_u64 v[218:219], s[22:23], 0, v[134:135]
	s_mov_b32 m0, s24
	s_nop 0
	global_load_lds_dwordx4 v[218:219], off
	v_lshl_add_u64 v[218:219], s[22:23], 0, v[130:131]
	s_add_i32 m0, s24, 0x2000
	s_nop 0
	global_load_lds_dwordx4 v[218:219], off
	v_lshl_add_u64 v[218:219], v[222:223], 0, s[6:7]
	s_mov_b32 m0, s36
	s_nop 0
	global_load_lds_dwordx4 v[218:219], off
	v_lshl_add_u64 v[218:219], v[224:225], 0, s[6:7]
	s_mov_b32 m0, s37
	s_nop 0
	global_load_lds_dwordx4 v[218:219], off
	s_waitcnt vmcnt(8)
	s_waitcnt lgkmcnt(0)
	s_setprio 1
	s_barrier
	v_mfma_f32_16x16x32_bf16 v[62:65], v[146:149], v[186:189], v[62:65]
	v_mfma_f32_16x16x32_bf16 v[54:57], v[162:165], v[186:189], v[54:57]
	v_mfma_f32_16x16x32_bf16 v[46:49], v[146:149], v[194:197], v[46:49]
	v_mfma_f32_16x16x32_bf16 v[38:41], v[162:165], v[194:197], v[38:41]
	v_mfma_f32_16x16x32_bf16 v[30:33], v[146:149], v[202:205], v[30:33]
	v_mfma_f32_16x16x32_bf16 v[22:25], v[162:165], v[202:205], v[22:25]
	v_mfma_f32_16x16x32_bf16 v[14:17], v[146:149], v[210:213], v[14:17]
	v_mfma_f32_16x16x32_bf16 v[6:9], v[162:165], v[210:213], v[6:9]
	v_mfma_f32_16x16x32_bf16 v[62:65], v[158:161], v[190:193], v[62:65]
	v_mfma_f32_16x16x32_bf16 v[54:57], v[166:169], v[190:193], v[54:57]
	v_mfma_f32_16x16x32_bf16 v[46:49], v[158:161], v[198:201], v[46:49]
	v_mfma_f32_16x16x32_bf16 v[38:41], v[166:169], v[198:201], v[38:41]
	v_mfma_f32_16x16x32_bf16 v[30:33], v[158:161], v[206:209], v[30:33]
	v_mfma_f32_16x16x32_bf16 v[22:25], v[166:169], v[206:209], v[22:25]
	v_mfma_f32_16x16x32_bf16 v[14:17], v[158:161], v[214:217], v[14:17]
	v_mfma_f32_16x16x32_bf16 v[6:9], v[166:169], v[214:217], v[6:9]
	s_setprio 0
	s_setprio 1
	v_mfma_f32_16x16x32_bf16 v[58:61], v[170:173], v[186:189], v[58:61]
	v_mfma_f32_16x16x32_bf16 v[50:53], v[178:181], v[186:189], v[50:53]
	v_mfma_f32_16x16x32_bf16 v[42:45], v[170:173], v[194:197], v[42:45]
	v_mfma_f32_16x16x32_bf16 v[34:37], v[178:181], v[194:197], v[34:37]
	v_mfma_f32_16x16x32_bf16 v[26:29], v[170:173], v[202:205], v[26:29]
	v_mfma_f32_16x16x32_bf16 v[18:21], v[178:181], v[202:205], v[18:21]
	v_mfma_f32_16x16x32_bf16 v[10:13], v[170:173], v[210:213], v[10:13]
	v_mfma_f32_16x16x32_bf16 v[2:5], v[178:181], v[210:213], v[2:5]
	v_mfma_f32_16x16x32_bf16 v[58:61], v[174:177], v[190:193], v[58:61]
	v_mfma_f32_16x16x32_bf16 v[50:53], v[182:185], v[190:193], v[50:53]
	v_mfma_f32_16x16x32_bf16 v[42:45], v[174:177], v[198:201], v[42:45]
	v_mfma_f32_16x16x32_bf16 v[34:37], v[182:185], v[198:201], v[34:37]
	v_mfma_f32_16x16x32_bf16 v[26:29], v[174:177], v[206:209], v[26:29]
	v_mfma_f32_16x16x32_bf16 v[18:21], v[182:185], v[206:209], v[18:21]
	v_mfma_f32_16x16x32_bf16 v[10:13], v[174:177], v[214:217], v[10:13]
	v_mfma_f32_16x16x32_bf16 v[2:5], v[182:185], v[214:217], v[2:5]
	s_setprio 0
	s_barrier
	s_add_i32 s48, s48, 2
	s_add_u32 s20, s20, 0x100
	s_addc_u32 s21, s21, 0
	s_add_u32 s46, s46, 0x100
	s_addc_u32 s47, s47, 0
	s_cmp_gt_u32 s48, 29
	s_cbranch_scc0 .LBB0_2433
	s_and_b64 vcc, exec, s[8:9]
	s_cbranch_vccz .LBB0_2436
	s_barrier

; #define PG8_STAGE(bufoff, gbase, voff) do { _Pragma("unroll") for (int _i = 0; _i < 2; ++_i) \
;         __builtin_amdgcn_global_load_lds((const unsigned*)((const char*)(gbase) + (voff)[_i]), (PG8_LAS unsigned*)(lds + (bufoff) + ldsw + _i * 8192), 16, 0, 0); } while (0)
; #define PG8_WAIT_V(n) asm volatile("s_waitcnt vmcnt(" #n ")" ::: "memory")
; #define PG8_WAIT_L(n) asm volatile("s_waitcnt lgkmcnt(" #n ")" ::: "memory")
; #define PG8_BAR __builtin_amdgcn_s_barrier()
; #define PG8_SCHED __builtin_amdgcn_sched_barrier(0)
;     __device__ __forceinline__ int nt(const pg8::Unit& u) const { return u.kind == 0 ? ntiles : q_nt(u.kind - 1); }
; template <class Epi, class Sched, bool ALIGN_EPI = true, bool SP2 = true>
; __device__ __forceinline__ void gemm_phase(PG8_LAS unsigned char* lds, const int K  , const Sched& S, const Epi& E) {
;     ...
;             const bool last = (t == nt - 2);
;             const char* a1 = cA + (size_t)(t + 1) * kstep;
;             const char* a2 = last ? nA : cA + (size_t)(t + 2) * kstep; const char* b2 = last ? nB : cB + (size_t)(t + 2) * kstep;
;             const char* a3 = a2 + kstep; const char* b3 = b2 + kstep;
;             if constexpr (SP2) {
;             PG8_LDB(B0, 0, 0); PG8_LDB(B1, 0, 1); PG8_SCHED; PG8_LDA(At, 0, 0); PG8_STAGE(PG8_SA(1, 1), a1 + hstep, voffA);
;             PG8_WAIT_V(8); PG8_WAIT_L(0); PG8_BAR; PG8_MMA(0, 0, At, B0); PG8_MMA(0, 1, At, B1); PG8_BAR; PG8_SCHED;
;             PG8_LDA(At, 0, 1); PG8_STAGE(PG8_SB(0, 0), b2, voffB); PG8_STAGE(PG8_SB(0, 1), b2 + hstep, voffB); PG8_STAGE(PG8_SA(0, 0), a2, voffA);
;             PG8_WAIT_V(8); PG8_WAIT_L(0); PG8_BAR; PG8_MMA(1, 0, At, B0); PG8_MMA(1, 1, At, B1); PG8_BAR; PG8_SCHED;
.LBB0_2516:
	ds_read_b128 v[16:19], v206
	ds_read_b128 v[20:23], v206 offset:1024
	ds_read_b128 v[24:27], v206 offset:2048
	ds_read_b128 v[28:31], v206 offset:3072
	ds_read_b128 v[0:3], v207
	ds_read_b128 v[4:7], v207 offset:1024
	ds_read_b128 v[8:11], v207 offset:2048
	ds_read_b128 v[12:15], v207 offset:3072
	s_add_u32 s18, s16, 0xfff50080
	s_addc_u32 s19, s17, -1
	s_cmp_eq_u32 s57, 40
	s_cselect_b32 s21, s7, s19
	s_cselect_b32 s20, s6, s18
	s_cselect_b32 s19, s15, s56
	s_cselect_b32 s18, s14, s55
	v_lshl_add_u64 v[200:201], s[16:17], 0, v[176:177]
	s_add_i32 m0, s25, 0xc000
	ds_read_b128 v[160:163], v208
	ds_read_b128 v[164:167], v208 offset:1024
	ds_read_b128 v[184:187], v208 offset:2048
	ds_read_b128 v[188:191], v208 offset:3072
	ds_read_b128 v[192:195], v208 offset:4096
	ds_read_b128 v[196:199], v208 offset:5120
	ds_read_b128 v[210:213], v208 offset:6144
	ds_read_b128 v[214:217], v208 offset:7168
	global_load_lds_dwordx4 v[200:201], off
	v_lshl_add_u64 v[200:201], s[16:17], 0, v[178:179]
	s_add_i32 m0, s25, 0xe000
	s_nop 0
	global_load_lds_dwordx4 v[200:201], off
	s_waitcnt vmcnt(8)
	s_waitcnt lgkmcnt(0)
	s_setprio 1
	s_barrier
	v_mfma_scale_f32_16x16x128_f8f6f4 v[156:159], v[16:23], v[160:167], v[156:159], v202, v202 op_sel_hi:[0,0,0]
	v_mfma_scale_f32_16x16x128_f8f6f4 v[152:155], v[24:31], v[160:167], v[152:155], v202, v202 op_sel_hi:[0,0,0]
	v_mfma_scale_f32_16x16x128_f8f6f4 v[140:143], v[16:23], v[184:191], v[140:143], v202, v202 op_sel_hi:[0,0,0]
	v_mfma_scale_f32_16x16x128_f8f6f4 v[136:139], v[24:31], v[184:191], v[136:139], v202, v202 op_sel_hi:[0,0,0]
	v_mfma_scale_f32_16x16x128_f8f6f4 v[124:127], v[16:23], v[192:199], v[124:127], v202, v202 op_sel_hi:[0,0,0]
	v_mfma_scale_f32_16x16x128_f8f6f4 v[120:123], v[24:31], v[192:199], v[120:123], v202, v202 op_sel_hi:[0,0,0]
	v_mfma_scale_f32_16x16x128_f8f6f4 v[108:111], v[16:23], v[210:217], v[108:111], v202, v202 op_sel_hi:[0,0,0]
	v_mfma_scale_f32_16x16x128_f8f6f4 v[104:107], v[24:31], v[210:217], v[104:107], v202, v202 op_sel_hi:[0,0,0]
	s_setprio 0
	s_setprio 1
	v_mfma_scale_f32_16x16x128_f8f6f4 v[148:151], v[0:7], v[160:167], v[148:151], v202, v202 op_sel_hi:[0,0,0]
	v_mfma_scale_f32_16x16x128_f8f6f4 v[144:147], v[8:15], v[160:167], v[144:147], v202, v202 op_sel_hi:[0,0,0]
	v_mfma_scale_f32_16x16x128_f8f6f4 v[132:135], v[0:7], v[184:191], v[132:135], v202, v202 op_sel_hi:[0,0,0]
	v_mfma_scale_f32_16x16x128_f8f6f4 v[128:131], v[8:15], v[184:191], v[128:131], v202, v202 op_sel_hi:[0,0,0]
	v_mfma_scale_f32_16x16x128_f8f6f4 v[116:119], v[0:7], v[192:199], v[116:119], v202, v202 op_sel_hi:[0,0,0]
	v_mfma_scale_f32_16x16x128_f8f6f4 v[112:115], v[8:15], v[192:199], v[112:115], v202, v202 op_sel_hi:[0,0,0]
	v_mfma_scale_f32_16x16x128_f8f6f4 v[100:103], v[0:7], v[210:217], v[100:103], v202, v202 op_sel_hi:[0,0,0]
	v_mfma_scale_f32_16x16x128_f8f6f4 v[96:99], v[8:15], v[210:217], v[96:99], v202, v202 op_sel_hi:[0,0,0]
	s_setprio 0
	s_barrier
	s_add_i32 s58, s38, s24
	v_lshl_add_u64 v[160:161], s[18:19], 0, v[170:171]
	s_mov_b32 m0, s58
	ds_read_b128 v[184:187], v208 offset:16384
	ds_read_b128 v[188:191], v208 offset:17408
	ds_read_b128 v[192:195], v208 offset:18432
	ds_read_b128 v[196:199], v208 offset:19456
	ds_read_b128 v[210:213], v208 offset:20480
	ds_read_b128 v[214:217], v208 offset:21504
	ds_read_b128 v[218:221], v208 offset:22528
	ds_read_b128 v[222:225], v208 offset:23552
	global_load_lds_dwordx4 v[160:161], off
	s_add_i32 m0, s58, 0x2000
	s_add_u32 s58, s18, 0xb0000
	v_lshl_add_u64 v[162:163], s[18:19], 0, v[174:175]
	s_addc_u32 s59, s19, 0
	s_add_i32 s60, s39, s24
	global_load_lds_dwordx4 v[162:163], off
	v_lshl_add_u64 v[164:165], s[58:59], 0, v[170:171]
	s_mov_b32 m0, s60
	v_lshl_add_u64 v[166:167], s[20:21], 0, v[172:173]
	global_load_lds_dwordx4 v[164:165], off
	v_lshl_add_u64 v[164:165], s[58:59], 0, v[174:175]
	s_add_i32 m0, s60, 0x2000
	s_nop 0
	global_load_lds_dwordx4 v[164:165], off
	v_lshl_add_u64 v[164:165], s[20:21], 0, v[168:169]
	s_mov_b32 m0, s25
	s_nop 0
	global_load_lds_dwordx4 v[164:165], off
	s_mov_b32 m0, s26
	s_nop 0
	global_load_lds_dwordx4 v[166:167], off
	s_waitcnt vmcnt(8)
	s_waitcnt lgkmcnt(0)
	s_setprio 1
	s_barrier
	v_mfma_scale_f32_16x16x128_f8f6f4 v[92:95], v[16:23], v[184:191], v[92:95], v202, v202 op_sel_hi:[0,0,0]
	v_mfma_scale_f32_16x16x128_f8f6f4 v[88:91], v[24:31], v[184:191], v[88:91], v202, v202 op_sel_hi:[0,0,0]
	v_mfma_scale_f32_16x16x128_f8f6f4 v[76:79], v[16:23], v[192:199], v[76:79], v202, v202 op_sel_hi:[0,0,0]
	v_mfma_scale_f32_16x16x128_f8f6f4 v[72:75], v[24:31], v[192:199], v[72:75], v202, v202 op_sel_hi:[0,0,0]
	v_mfma_scale_f32_16x16x128_f8f6f4 v[60:63], v[16:23], v[210:217], v[60:63], v202, v202 op_sel_hi:[0,0,0]
	v_mfma_scale_f32_16x16x128_f8f6f4 v[56:59], v[24:31], v[210:217], v[56:59], v202, v202 op_sel_hi:[0,0,0]
	v_mfma_scale_f32_16x16x128_f8f6f4 v[44:47], v[16:23], v[218:225], v[44:47], v202, v202 op_sel_hi:[0,0,0]
	v_mfma_scale_f32_16x16x128_f8f6f4 v[40:43], v[24:31], v[218:225], v[40:43], v202, v202 op_sel_hi:[0,0,0]
	s_setprio 0
	s_setprio 1
	v_mfma_scale_f32_16x16x128_f8f6f4 v[84:87], v[0:7], v[184:191], v[84:87], v202, v202 op_sel_hi:[0,0,0]
	v_mfma_scale_f32_16x16x128_f8f6f4 v[80:83], v[8:15], v[184:191], v[80:83], v202, v202 op_sel_hi:[0,0,0]
	v_mfma_scale_f32_16x16x128_f8f6f4 v[68:71], v[0:7], v[192:199], v[68:71], v202, v202 op_sel_hi:[0,0,0]
	v_mfma_scale_f32_16x16x128_f8f6f4 v[64:67], v[8:15], v[192:199], v[64:67], v202, v202 op_sel_hi:[0,0,0]
	v_mfma_scale_f32_16x16x128_f8f6f4 v[52:55], v[0:7], v[210:217], v[52:55], v202, v202 op_sel_hi:[0,0,0]
	v_mfma_scale_f32_16x16x128_f8f6f4 v[48:51], v[8:15], v[210:217], v[48:51], v202, v202 op_sel_hi:[0,0,0]
	v_mfma_scale_f32_16x16x128_f8f6f4 v[36:39], v[0:7], v[218:225], v[36:39], v202, v202 op_sel_hi:[0,0,0]
	v_mfma_scale_f32_16x16x128_f8f6f4 v[32:35], v[8:15], v[218:225], v[32:35], v202, v202 op_sel_hi:[0,0,0]
	s_setprio 0
	s_barrier
; #define PG8_STAGE(bufoff, gbase, voff) do { _Pragma("unroll") for (int _i = 0; _i < 2; ++_i) \
;         __builtin_amdgcn_global_load_lds((const unsigned*)((const char*)(gbase) + (voff)[_i]), (PG8_LAS unsigned*)(lds + (bufoff) + ldsw + _i * 8192), 16, 0, 0); } while (0)
; #define PG8_WAIT_V(n) asm volatile("s_waitcnt vmcnt(" #n ")" ::: "memory")
; #define PG8_WAIT_L(n) asm volatile("s_waitcnt lgkmcnt(" #n ")" ::: "memory")
; #define PG8_BAR __builtin_amdgcn_s_barrier()
; #define PG8_SCHED __builtin_amdgcn_sched_barrier(0)
; template <class Epi, class Sched, bool ALIGN_EPI = true, bool SP2 = true>
; __device__ __forceinline__ void gemm_phase(PG8_LAS unsigned char* lds, const int K  , const Sched& S, const Epi& E) {
;     ...
;             PG8_LDB(B0, 1, 0); PG8_LDB(B1, 1, 1); PG8_SCHED; PG8_LDA(At, 1, 0); PG8_STAGE(PG8_SA(0, 1), a2 + hstep, voffA);
;             PG8_WAIT_V(8); PG8_WAIT_L(0); PG8_BAR; PG8_MMA(0, 0, At, B0); PG8_MMA(0, 1, At, B1); PG8_BAR; PG8_SCHED;
;             PG8_LDA(At, 1, 1); PG8_STAGE(PG8_SB(1, 0), b3, voffB); PG8_STAGE(PG8_SB(1, 1), b3 + hstep, voffB); PG8_STAGE(PG8_SA(1, 0), a3, voffA);
;             PG8_WAIT_V(8); PG8_WAIT_L(0); PG8_BAR; PG8_MMA(1, 0, At, B0); PG8_MMA(1, 1, At, B1); PG8_BAR; PG8_SCHED;
;     ...
;         if constexpr (Epi::FP8) asm volatile("s_nop 15\n\ts_nop 15\n\ts_nop 15\n\ts_nop 15\n\ts_nop 15" ::: "memory");
;         if constexpr (ALIGN_EPI) { if (wr == 0) PG8_BAR; }
	s_add_i32 s58, 0, 0x18000
	s_add_i32 s59, 0, 0x1c000
	v_add_u32_e32 v12, s58, v204
	v_add_u32_e32 v28, s59, v204
	ds_read_b128 v[0:3], v12
	ds_read_b128 v[4:7], v12 offset:1024
	ds_read_b128 v[8:11], v12 offset:2048
	ds_read_b128 v[12:15], v12 offset:3072
	ds_read_b128 v[16:19], v28
	ds_read_b128 v[20:23], v28 offset:1024
	ds_read_b128 v[24:27], v28 offset:2048
	ds_read_b128 v[28:31], v28 offset:3072
	s_add_u32 s20, s20, 0xb0000
	s_addc_u32 s21, s21, 0
	s_mov_b32 m0, s27
	v_lshl_add_u64 v[200:201], s[20:21], 0, v[168:169]
	ds_read_b128 v[184:187], v208 offset:32768
	ds_read_b128 v[188:191], v208 offset:33792
	ds_read_b128 v[192:195], v208 offset:34816
	ds_read_b128 v[196:199], v208 offset:35840
	ds_read_b128 v[210:213], v208 offset:36864
	ds_read_b128 v[214:217], v208 offset:37888
	ds_read_b128 v[218:221], v208 offset:38912
	ds_read_b128 v[222:225], v208 offset:39936
	global_load_lds_dwordx4 v[200:201], off
	v_lshl_add_u64 v[200:201], s[20:21], 0, v[172:173]
	s_mov_b32 m0, s28
	s_nop 0
	global_load_lds_dwordx4 v[200:201], off
	s_waitcnt vmcnt(8)
	s_waitcnt lgkmcnt(0)
	s_setprio 1
	s_barrier
	v_mfma_scale_f32_16x16x128_f8f6f4 v[156:159], v[0:7], v[184:191], v[156:159], v202, v202 op_sel_hi:[0,0,0]
	v_mfma_scale_f32_16x16x128_f8f6f4 v[152:155], v[8:15], v[184:191], v[152:155], v202, v202 op_sel_hi:[0,0,0]
	v_mfma_scale_f32_16x16x128_f8f6f4 v[140:143], v[0:7], v[192:199], v[140:143], v202, v202 op_sel_hi:[0,0,0]
	v_mfma_scale_f32_16x16x128_f8f6f4 v[136:139], v[8:15], v[192:199], v[136:139], v202, v202 op_sel_hi:[0,0,0]
	v_mfma_scale_f32_16x16x128_f8f6f4 v[124:127], v[0:7], v[210:217], v[124:127], v202, v202 op_sel_hi:[0,0,0]
	v_mfma_scale_f32_16x16x128_f8f6f4 v[120:123], v[8:15], v[210:217], v[120:123], v202, v202 op_sel_hi:[0,0,0]
	v_mfma_scale_f32_16x16x128_f8f6f4 v[108:111], v[0:7], v[218:225], v[108:111], v202, v202 op_sel_hi:[0,0,0]
	v_mfma_scale_f32_16x16x128_f8f6f4 v[104:107], v[8:15], v[218:225], v[104:107], v202, v202 op_sel_hi:[0,0,0]
	s_setprio 0
	s_setprio 1
	v_mfma_scale_f32_16x16x128_f8f6f4 v[148:151], v[16:23], v[184:191], v[148:151], v202, v202 op_sel_hi:[0,0,0]
	v_mfma_scale_f32_16x16x128_f8f6f4 v[144:147], v[24:31], v[184:191], v[144:147], v202, v202 op_sel_hi:[0,0,0]
	v_mfma_scale_f32_16x16x128_f8f6f4 v[132:135], v[16:23], v[192:199], v[132:135], v202, v202 op_sel_hi:[0,0,0]
	v_mfma_scale_f32_16x16x128_f8f6f4 v[128:131], v[24:31], v[192:199], v[128:131], v202, v202 op_sel_hi:[0,0,0]
	v_mfma_scale_f32_16x16x128_f8f6f4 v[116:119], v[16:23], v[210:217], v[116:119], v202, v202 op_sel_hi:[0,0,0]
	v_mfma_scale_f32_16x16x128_f8f6f4 v[112:115], v[24:31], v[210:217], v[112:115], v202, v202 op_sel_hi:[0,0,0]
	v_mfma_scale_f32_16x16x128_f8f6f4 v[100:103], v[16:23], v[218:225], v[100:103], v202, v202 op_sel_hi:[0,0,0]
	v_mfma_scale_f32_16x16x128_f8f6f4 v[96:99], v[24:31], v[218:225], v[96:99], v202, v202 op_sel_hi:[0,0,0]
	s_setprio 0
	s_barrier
	s_add_i32 s20, s58, s24
	v_lshl_add_u64 v[160:161], v[160:161], 0, s[8:9]
	s_mov_b32 m0, s20
	ds_read_b128 v[184:187], v208 offset:49152
	ds_read_b128 v[188:191], v208 offset:50176
	ds_read_b128 v[192:195], v208 offset:51200
	ds_read_b128 v[196:199], v208 offset:52224
	ds_read_b128 v[210:213], v208 offset:53248
	ds_read_b128 v[214:217], v208 offset:54272
	ds_read_b128 v[218:221], v208 offset:55296
	ds_read_b128 v[222:225], v208 offset:56320
	global_load_lds_dwordx4 v[160:161], off
	s_add_i32 m0, s20, 0x2000
	s_add_u32 s18, s18, 0xb0080
	v_lshl_add_u64 v[160:161], v[162:163], 0, s[8:9]
	s_addc_u32 s19, s19, 0
	s_add_i32 s20, s59, s24
	global_load_lds_dwordx4 v[160:161], off
	v_lshl_add_u64 v[160:161], s[18:19], 0, v[170:171]
	s_mov_b32 m0, s20
	s_nop 0
	global_load_lds_dwordx4 v[160:161], off
	v_lshl_add_u64 v[160:161], s[18:19], 0, v[174:175]
	s_add_i32 m0, s20, 0x2000
	s_nop 0
	global_load_lds_dwordx4 v[160:161], off
	v_lshl_add_u64 v[160:161], v[164:165], 0, s[8:9]
	s_mov_b32 m0, s35
	s_nop 0
	global_load_lds_dwordx4 v[160:161], off
	v_lshl_add_u64 v[160:161], v[166:167], 0, s[8:9]
	s_mov_b32 m0, s36
	s_nop 0
	global_load_lds_dwordx4 v[160:161], off
	s_waitcnt vmcnt(8)
	s_waitcnt lgkmcnt(0)
	s_setprio 1
	s_barrier
	v_mfma_scale_f32_16x16x128_f8f6f4 v[92:95], v[0:7], v[184:191], v[92:95], v202, v202 op_sel_hi:[0,0,0]
	v_mfma_scale_f32_16x16x128_f8f6f4 v[88:91], v[8:15], v[184:191], v[88:91], v202, v202 op_sel_hi:[0,0,0]
	v_mfma_scale_f32_16x16x128_f8f6f4 v[76:79], v[0:7], v[192:199], v[76:79], v202, v202 op_sel_hi:[0,0,0]
	v_mfma_scale_f32_16x16x128_f8f6f4 v[72:75], v[8:15], v[192:199], v[72:75], v202, v202 op_sel_hi:[0,0,0]
	v_mfma_scale_f32_16x16x128_f8f6f4 v[60:63], v[0:7], v[210:217], v[60:63], v202, v202 op_sel_hi:[0,0,0]
	v_mfma_scale_f32_16x16x128_f8f6f4 v[56:59], v[8:15], v[210:217], v[56:59], v202, v202 op_sel_hi:[0,0,0]
	v_mfma_scale_f32_16x16x128_f8f6f4 v[44:47], v[0:7], v[218:225], v[44:47], v202, v202 op_sel_hi:[0,0,0]
	v_mfma_scale_f32_16x16x128_f8f6f4 v[40:43], v[8:15], v[218:225], v[40:43], v202, v202 op_sel_hi:[0,0,0]
	s_setprio 0
	s_setprio 1
	v_mfma_scale_f32_16x16x128_f8f6f4 v[84:87], v[16:23], v[184:191], v[84:87], v202, v202 op_sel_hi:[0,0,0]
	v_mfma_scale_f32_16x16x128_f8f6f4 v[80:83], v[24:31], v[184:191], v[80:83], v202, v202 op_sel_hi:[0,0,0]
	v_mfma_scale_f32_16x16x128_f8f6f4 v[68:71], v[16:23], v[192:199], v[68:71], v202, v202 op_sel_hi:[0,0,0]
	v_mfma_scale_f32_16x16x128_f8f6f4 v[64:67], v[24:31], v[192:199], v[64:67], v202, v202 op_sel_hi:[0,0,0]
	v_mfma_scale_f32_16x16x128_f8f6f4 v[52:55], v[16:23], v[210:217], v[52:55], v202, v202 op_sel_hi:[0,0,0]
	v_mfma_scale_f32_16x16x128_f8f6f4 v[48:51], v[24:31], v[210:217], v[48:51], v202, v202 op_sel_hi:[0,0,0]
	v_mfma_scale_f32_16x16x128_f8f6f4 v[36:39], v[16:23], v[218:225], v[36:39], v202, v202 op_sel_hi:[0,0,0]
	v_mfma_scale_f32_16x16x128_f8f6f4 v[32:35], v[24:31], v[218:225], v[32:35], v202, v202 op_sel_hi:[0,0,0]
	s_setprio 0
	s_barrier
	s_add_i32 s57, s57, 2
	s_add_u32 s16, s16, 0x100
	s_addc_u32 s17, s17, 0
	s_add_u32 s55, s55, 0x100
	s_addc_u32 s56, s56, 0
	s_cmp_gt_u32 s57, 41
	s_cbranch_scc0 .LBB0_2516
	s_nop 15
	s_nop 15
	s_nop 15
	s_nop 15
	s_nop 15
	s_and_b64 vcc, exec, s[10:11]
	s_cbranch_vccz .LBB0_2519
	s_barrier
